# speedup vs baseline: 1.0426x; 1.0073x over previous
; DI unsigned xb_ld(unsigned* p) { return __hip_atomic_load(p, __ATOMIC_RELAXED, __HIP_MEMORY_SCOPE_AGENT); }
; DI unsigned xb_add(unsigned* p, unsigned v) { return __hip_atomic_fetch_add(p, v, __ATOMIC_RELAXED, __HIP_MEMORY_SCOPE_AGENT); }
; #define XB_SPIN(cond, bar) do { unsigned _sp = 0; while (cond) { __builtin_amdgcn_s_sleep(1); \
;     if ((++_sp & 255u) == 0u) { if (xb_ld(&(bar)[XB_TMO])) break; if (_sp > XB_SPIN_CAP) { atomicAdd(&(bar)[XB_TMO], 1u); break; } } } } while (0)
; DI void xcd_barrier(const XcdBarrier& b) {
;     ...
;       __builtin_amdgcn_fence(__ATOMIC_RELEASE, "agent");
;       asm volatile("s_waitcnt vmcnt(0)" ::: "memory");
;       const unsigned og = xb_add(&bar[XB_TOP], 1u);
;       const unsigned tg = og / nx;
;       if (og + 1u == (tg + 1u) * nx) xb_add(&bar[XB_TOPGEN], 1u);
;       else XB_SPIN(xb_ld(&bar[XB_TOPGEN]) == tg, bar);
;       __builtin_amdgcn_fence(__ATOMIC_ACQUIRE, "agent");
;       xb_add(&bar[XB_XGEN(b.x)], 1u);
;       asm volatile("s_waitcnt vmcnt(0)" ::: "memory");
.LBB0_68:
	s_or_b64 exec, exec, s[0:1]
	s_mov_b64 s[0:1], exec
	v_mbcnt_lo_u32_b32 v0, s0, 0
	v_mbcnt_hi_u32_b32 v0, s1, v0
	v_cmp_eq_u32_e32 vcc, 0, v0
	s_and_saveexec_b64 s[8:9], vcc
	s_cbranch_execz .LBB0_70
	s_bcnt1_i32_b64 s0, s[0:1]
	v_mov_b32_e32 v0, 0x2000
	v_mov_b32_e32 v1, s0
	global_atomic_add v0, v1, s[6:7] offset:1024
.LBB0_70:
	s_or_b64 exec, exec, s[8:9]
	buffer_inv sc1
	s_waitcnt vmcnt(0)

; DI unsigned xb_ld(unsigned* p) { return __hip_atomic_load(p, __ATOMIC_RELAXED, __HIP_MEMORY_SCOPE_AGENT); }
; DI unsigned xb_add(unsigned* p, unsigned v) { return __hip_atomic_fetch_add(p, v, __ATOMIC_RELAXED, __HIP_MEMORY_SCOPE_AGENT); }
; #define XB_SPIN(cond, bar) do { unsigned _sp = 0; while (cond) { __builtin_amdgcn_s_sleep(1); \
;     if ((++_sp & 255u) == 0u) { if (xb_ld(&(bar)[XB_TMO])) break; if (_sp > XB_SPIN_CAP) { atomicAdd(&(bar)[XB_TMO], 1u); break; } } } } while (0)
; DI void xcd_barrier(const XcdBarrier& b) {
;     ...
;       __builtin_amdgcn_fence(__ATOMIC_RELEASE, "agent");
;       asm volatile("s_waitcnt vmcnt(0)" ::: "memory");
;       const unsigned og = xb_add(&bar[XB_TOP], 1u);
;       const unsigned tg = og / nx;
;       if (og + 1u == (tg + 1u) * nx) xb_add(&bar[XB_TOPGEN], 1u);
;       else XB_SPIN(xb_ld(&bar[XB_TOPGEN]) == tg, bar);
;       __builtin_amdgcn_fence(__ATOMIC_ACQUIRE, "agent");
;       xb_add(&bar[XB_XGEN(b.x)], 1u);
;       asm volatile("s_waitcnt vmcnt(0)" ::: "memory");
.LBB0_207:
	s_or_b64 exec, exec, s[0:1]
	s_mov_b64 s[0:1], exec
	v_mbcnt_lo_u32_b32 v0, s0, 0
	v_mbcnt_hi_u32_b32 v0, s1, v0
	v_cmp_eq_u32_e32 vcc, 0, v0
	s_and_saveexec_b64 s[6:7], vcc
	s_cbranch_execz .LBB0_209
	s_bcnt1_i32_b64 s0, s[0:1]
	v_mov_b32_e32 v0, 0x2000
	v_mov_b32_e32 v1, s0
	global_atomic_add v0, v1, s[4:5] offset:1024
.LBB0_209:
	s_or_b64 exec, exec, s[6:7]
	buffer_inv sc1
	s_waitcnt vmcnt(0)

; DI int lbid() { int x = blockIdx.x; asm volatile("" : "+s"(x)); return x; }
; template <class Epi>
; DI void gemm_phase_plain(const u16* A, long lda, const u16* Bt, long ldb, int M, int N, int K, const Epi& epi, char* smem) {
;     ...
;   for (int t = lbid(); t < nwg; t += gridDim.x) {
;     const int xcd = t & 7, off = t >> 3;
;     const int wg = (xcd < rr ? xcd * (q + 1) : rr * (q + 1) + (xcd - rr) * q) + off;
;     const int nig = 8 * MT, gid = wg / nig, fm = gid * 8, gsz = (NT - fm) < 8 ? (NT - fm) : 8;
;     const int nt = fm + (wg % nig) % gsz, mt = (wg % nig) / gsz;
;     gemm_tile(ar, 64, Bt, ldb, K, mt * 128, nt * 128, epi, smem);
.Lfe_join_A:
	s_load_dword s0, s[24:25], 0x0
	s_waitcnt lgkmcnt(0)
	s_add_i32 s31, s0, s31
	s_cmpk_lt_i32 s31, 0xe80
	s_cbranch_scc0 .LBB0_460

; template <class ARow, class Epi>
; DI void gemm_tile(const ARow& arow, long a_kstride, const u16* __restrict__ Bt, long ldb, int K, int m0, int n0,
;                   const Epi& epi, char* smem) {
;     ...
;   for (int kt = 0; kt < KT; ++kt) {
;     const int cur = kt & 1;
;     if (kt + 1 < KT) GEMM_STAGE(cur ^ 1, kt + 1);
;     const char* sa = smem + cur * 32768 + wm * 64 * 128;
;     const char* sb = smem + cur * 32768 + 16384 + wn * 64 * 128;
; #pragma unroll
;     for (int ks = 0; ks < 2; ++ks) {
;       bf16x8 wf[4], af[4];
; #pragma unroll
;       for (int j = 0; j < 4; ++j) {
;         wf[j] = *(const bf16x8*)(sb + j * 2048 + foff[ks]);
;         af[j] = *(const bf16x8*)(sa + j * 2048 + foff[ks]);
;       }
; #pragma unroll
;       for (int ni = 0; ni < 4; ++ni)
; #pragma unroll
;         for (int mi = 0; mi < 4; ++mi) acc[ni][mi] = __builtin_amdgcn_mfma_f32_16x16x32_bf16(wf[ni], af[mi], acc[ni][mi], 0, 0, 0);
;     }
;     asm volatile("s_waitcnt vmcnt(0)" ::: "memory");
;     __syncthreads();
;   }
.LBB0_217:
	s_and_b32 s6, s1, 0x8000
	s_xor_b32 s7, s6, 0x8000
	v_add_u32_e32 v108, s7, v91
	v_add_u32_e32 v116, s6, v89
	v_or_b32_e32 v117, s6, v90
	v_readfirstlane_b32 s6, v108
	v_add_u32_e32 v109, 0x4000, v108
	v_lshl_add_u64 v[92:93], v[66:67], 0, s[4:5]
	v_add_u32_e32 v110, 0x400, v108
	v_readfirstlane_b32 s7, v109
	s_mov_b32 m0, s6
	v_lshl_add_u64 v[94:95], v[68:69], 0, s[4:5]
	v_add_u32_e32 v111, 0x4400, v108
	v_readfirstlane_b32 s8, v110
	global_load_lds_dwordx4 v[92:93], off
	s_mov_b32 m0, s7
	v_lshl_add_u64 v[96:97], v[70:71], 0, s[4:5]
	v_add_u32_e32 v113, 0x800, v108
	v_readfirstlane_b32 s9, v111
	global_load_lds_dwordx4 v[94:95], off
	s_mov_b32 m0, s8
	v_lshl_add_u64 v[98:99], v[72:73], 0, s[4:5]
	v_add_u32_e32 v114, 0x4800, v108
	v_readfirstlane_b32 s10, v113
	global_load_lds_dwordx4 v[96:97], off
	s_mov_b32 m0, s9
	v_lshl_add_u64 v[100:101], v[74:75], 0, s[4:5]
	v_add_u32_e32 v115, 0xc00, v108
	v_readfirstlane_b32 s11, v114
	global_load_lds_dwordx4 v[98:99], off
	s_mov_b32 m0, s10
	v_lshl_add_u64 v[102:103], v[76:77], 0, s[4:5]
	v_add_u32_e32 v108, 0x4c00, v108
	v_readfirstlane_b32 s12, v115
	global_load_lds_dwordx4 v[100:101], off
	s_mov_b32 m0, s11
	v_lshl_add_u64 v[104:105], v[78:79], 0, s[4:5]
	v_readfirstlane_b32 s13, v108
	global_load_lds_dwordx4 v[102:103], off
	s_mov_b32 m0, s12
	v_lshl_add_u64 v[106:107], v[80:81], 0, s[4:5]
	global_load_lds_dwordx4 v[104:105], off
	s_mov_b32 m0, s13
	v_add_u32_e32 v118, v117, v88
	global_load_lds_dwordx4 v[106:107], off
	v_add_u32_e32 v112, v116, v88
	ds_read_b128 v[92:95], v118 offset:16384
	ds_read_b128 v[96:99], v112
	ds_read_b128 v[100:103], v118 offset:18432
	ds_read_b128 v[104:107], v112 offset:2048
	ds_read_b128 v[108:111], v112 offset:4096
	ds_read_b128 v[112:115], v112 offset:6144
	s_waitcnt lgkmcnt(0)
	v_mfma_f32_16x16x32_bf16 v[60:63], v[92:95], v[96:99], v[60:63]
	v_add_u32_e32 v117, v117, v87
	v_add_u32_e32 v116, v116, v87
	s_add_i32 s1, s1, 0x8000
	v_mfma_f32_16x16x32_bf16 v[56:59], v[92:95], v[104:107], v[56:59]
	s_add_u32 s4, s4, 0x80
	s_addc_u32 s5, s5, 0
	s_cmpk_eq_i32 s4, 0x780
	v_mfma_f32_16x16x32_bf16 v[48:51], v[92:95], v[108:111], v[48:51]
	v_mfma_f32_16x16x32_bf16 v[40:43], v[92:95], v[112:115], v[40:43]
	v_mfma_f32_16x16x32_bf16 v[36:39], v[100:103], v[96:99], v[36:39]
	v_mfma_f32_16x16x32_bf16 v[32:35], v[100:103], v[104:107], v[32:35]
	v_mfma_f32_16x16x32_bf16 v[28:31], v[100:103], v[108:111], v[28:31]
	v_mfma_f32_16x16x32_bf16 v[24:27], v[100:103], v[112:115], v[24:27]
	ds_read_b128 v[92:95], v118 offset:20480
	ds_read_b128 v[100:103], v118 offset:22528
	s_waitcnt lgkmcnt(0)
	v_mfma_f32_16x16x32_bf16 v[20:23], v[92:95], v[96:99], v[20:23]
	v_mfma_f32_16x16x32_bf16 v[16:19], v[92:95], v[104:107], v[16:19]
	v_mfma_f32_16x16x32_bf16 v[12:15], v[92:95], v[108:111], v[12:15]
	v_mfma_f32_16x16x32_bf16 v[8:11], v[92:95], v[112:115], v[8:11]
	ds_read_b128 v[92:95], v117 offset:16384
	v_mfma_f32_16x16x32_bf16 v[4:7], v[100:103], v[96:99], v[4:7]
	v_mfma_f32_16x16x32_bf16 v[0:3], v[100:103], v[104:107], v[0:3]
	v_mfma_f32_16x16x32_bf16 v[52:55], v[100:103], v[108:111], v[52:55]
	v_mfma_f32_16x16x32_bf16 v[44:47], v[100:103], v[112:115], v[44:47]
	ds_read_b128 v[96:99], v116
	ds_read_b128 v[100:103], v117 offset:18432
	ds_read_b128 v[104:107], v116 offset:2048
	ds_read_b128 v[108:111], v116 offset:4096
	ds_read_b128 v[112:115], v116 offset:6144
	s_waitcnt lgkmcnt(0)
	v_mfma_f32_16x16x32_bf16 v[60:63], v[92:95], v[96:99], v[60:63]
	v_mfma_f32_16x16x32_bf16 v[56:59], v[92:95], v[104:107], v[56:59]
	v_mfma_f32_16x16x32_bf16 v[48:51], v[92:95], v[108:111], v[48:51]
	v_mfma_f32_16x16x32_bf16 v[40:43], v[92:95], v[112:115], v[40:43]
	v_mfma_f32_16x16x32_bf16 v[36:39], v[100:103], v[96:99], v[36:39]
	v_mfma_f32_16x16x32_bf16 v[32:35], v[100:103], v[104:107], v[32:35]
	v_mfma_f32_16x16x32_bf16 v[28:31], v[100:103], v[108:111], v[28:31]
	v_mfma_f32_16x16x32_bf16 v[24:27], v[100:103], v[112:115], v[24:27]
	ds_read_b128 v[92:95], v117 offset:20480
	ds_read_b128 v[100:103], v117 offset:22528
	s_waitcnt vmcnt(0)
	s_waitcnt vmcnt(0) lgkmcnt(0)
	v_mfma_f32_16x16x32_bf16 v[20:23], v[92:95], v[96:99], v[20:23]
	s_barrier
	v_mfma_f32_16x16x32_bf16 v[16:19], v[92:95], v[104:107], v[16:19]
	v_mfma_f32_16x16x32_bf16 v[12:15], v[92:95], v[108:111], v[12:15]
	v_mfma_f32_16x16x32_bf16 v[8:11], v[92:95], v[112:115], v[8:11]
	v_mfma_f32_16x16x32_bf16 v[4:7], v[100:103], v[96:99], v[4:7]
	v_mfma_f32_16x16x32_bf16 v[0:3], v[100:103], v[104:107], v[0:3]
	v_mfma_f32_16x16x32_bf16 v[52:55], v[100:103], v[108:111], v[52:55]
	v_mfma_f32_16x16x32_bf16 v[44:47], v[100:103], v[112:115], v[44:47]
	s_cbranch_scc0 .LBB0_217
;   DI u32x2 pack(int, int, float a, float b, float c, float d, float&) const { u32x2 v; v.x = pack2(a, b); v.y = pack2(c, d); return v; }
; template <class ARow, class Epi>
; DI void gemm_tile(const ARow& arow, long a_kstride, const u16* __restrict__ Bt, long ldb, int K, int m0, int n0,
;                   const Epi& epi, char* smem) {
;     ...
; #pragma unroll
;     for (int ks = 0; ks < 2; ++ks) {
;       bf16x8 wf[4], af[4];
; #pragma unroll
;       for (int j = 0; j < 4; ++j) {
;         wf[j] = *(const bf16x8*)(sb + j * 2048 + foff[ks]);
;         af[j] = *(const bf16x8*)(sa + j * 2048 + foff[ks]);
;       }
; #pragma unroll
;       for (int ni = 0; ni < 4; ++ni)
; #pragma unroll
;         for (int mi = 0; mi < 4; ++mi) acc[ni][mi] = __builtin_amdgcn_mfma_f32_16x16x32_bf16(wf[ni], af[mi], acc[ni][mi], 0, 0, 0);
;     }
;     asm volatile("s_waitcnt vmcnt(0)" ::: "memory");
;     __syncthreads();
;     ...
;   const int nh = n0 + wn * 64;
;   if (epi.packed(nh)) {
; #pragma unroll
;     for (int mi = 0; mi < 4; ++mi) {
;       const int m = m0 + wm * 64 + mi * 16 + fr;
;       float ss = 0.f;
;       u32x2 pk[4];
; #pragma unroll
;       for (int ni = 0; ni < 4; ++ni) pk[ni] = epi.pack(m, nh + ni * 16 + fq * 4, acc[ni][mi][0], acc[ni][mi][1], acc[ni][mi][2], acc[ni][mi][3], ss);
;       epi.finish16(m, nh, ss);
;       u16* rp = epi.rowp(m) + nh;
; #pragma unroll
;       for (int pp = 0; pp < 2; ++pp) {
;         u32x2 a = pk[2 * pp], b = pk[2 * pp + 1];
;         const u32x2 rx = __builtin_amdgcn_permlane16_swap(a.x, b.x, false, false);
;         const u32x2 ry = __builtin_amdgcn_permlane16_swap(a.y, b.y, false, false);
;         const int nst = (fq & 1) ? ((2 * pp + 1) * 16 + (fq - 1) * 4) : ((2 * pp) * 16 + fq * 4);
;         *(u32x4*)(rp + nst) = (u32x4){rx[0], ry[0], rx[1], ry[1]};
;       }
	v_add_u32_e32 v91, v90, v88
	ds_read_b128 v[66:69], v91 offset:49152
	v_add_u32_e32 v88, v89, v88
	ds_read_b128 v[70:73], v88 offset:32768
	ds_read_b128 v[74:77], v88 offset:34816
	ds_read_b128 v[78:81], v88 offset:36864
	ds_read_b128 v[92:95], v88 offset:38912
	v_add_u32_e32 v116, v90, v87
	s_waitcnt lgkmcnt(3)
	v_mfma_f32_16x16x32_bf16 v[60:63], v[66:69], v[70:73], v[60:63]
	s_waitcnt lgkmcnt(2)
	v_mfma_f32_16x16x32_bf16 v[56:59], v[66:69], v[74:77], v[56:59]
	s_waitcnt lgkmcnt(1)
	v_mfma_f32_16x16x32_bf16 v[48:51], v[66:69], v[78:81], v[48:51]
	s_waitcnt lgkmcnt(0)
	v_mfma_f32_16x16x32_bf16 v[40:43], v[66:69], v[92:95], v[40:43]
	ds_read_b128 v[66:69], v91 offset:51200
	s_waitcnt lgkmcnt(0)
	v_mfma_f32_16x16x32_bf16 v[36:39], v[66:69], v[70:73], v[36:39]
	v_mfma_f32_16x16x32_bf16 v[32:35], v[66:69], v[74:77], v[32:35]
	v_mfma_f32_16x16x32_bf16 v[96:99], v[66:69], v[78:81], v[28:31]
	v_mfma_f32_16x16x32_bf16 v[66:69], v[66:69], v[92:95], v[24:27]
	s_nop 2
	ds_read_b128 v[24:27], v91 offset:53248
	s_waitcnt lgkmcnt(0)
	v_mfma_f32_16x16x32_bf16 v[104:107], v[24:27], v[92:95], v[8:11]
	s_nop 2
	ds_read_b128 v[8:11], v91 offset:55296
	v_mfma_f32_16x16x32_bf16 v[20:23], v[24:27], v[70:73], v[20:23]
	s_waitcnt lgkmcnt(0)
	v_mfma_f32_16x16x32_bf16 v[70:73], v[8:11], v[70:73], v[4:7]
	s_nop 2
	ds_read_b128 v[4:7], v116 offset:49152
	v_mfma_f32_16x16x32_bf16 v[100:103], v[24:27], v[78:81], v[12:15]
	s_nop 2
	v_add_u32_e32 v12, v89, v87
	v_mfma_f32_16x16x32_bf16 v[16:19], v[24:27], v[74:77], v[16:19]
	ds_read_b128 v[88:91], v12 offset:32768
	ds_read_b128 v[108:111], v12 offset:36864
	ds_read_b128 v[112:115], v12 offset:38912
	v_mfma_f32_16x16x32_bf16 v[0:3], v[8:11], v[74:77], v[0:3]
	v_mfma_f32_16x16x32_bf16 v[74:77], v[8:11], v[78:81], v[52:55]
	v_mfma_f32_16x16x32_bf16 v[78:81], v[8:11], v[92:95], v[44:47]
	ds_read_b128 v[92:95], v12 offset:34816
	s_waitcnt lgkmcnt(3)
	v_mfma_f32_16x16x32_bf16 v[60:63], v[4:7], v[88:91], v[60:63]
	s_waitcnt lgkmcnt(0)
	v_mfma_f32_16x16x32_bf16 v[44:47], v[4:7], v[92:95], v[56:59]
	v_mfma_f32_16x16x32_bf16 v[28:31], v[4:7], v[108:111], v[48:51]
	v_mfma_f32_16x16x32_bf16 v[12:15], v[4:7], v[112:115], v[40:43]
	ds_read_b128 v[4:7], v116 offset:51200
	s_waitcnt lgkmcnt(0)
	v_mfma_f32_16x16x32_bf16 v[56:59], v[4:7], v[88:91], v[36:39]
	v_mfma_f32_16x16x32_bf16 v[40:43], v[4:7], v[92:95], v[32:35]
	v_mfma_f32_16x16x32_bf16 v[24:27], v[4:7], v[108:111], v[96:99]
	v_mfma_f32_16x16x32_bf16 v[8:11], v[4:7], v[112:115], v[66:69]
	ds_read_b128 v[4:7], v116 offset:53248
	s_nop 0
	ds_read_b128 v[96:99], v116 offset:55296
	s_waitcnt vmcnt(0)
	s_waitcnt lgkmcnt(0)
	v_mfma_f32_16x16x32_bf16 v[32:35], v[96:99], v[92:95], v[0:3]
	s_nop 2
	v_or_b32_e32 v0, s0, v64
	v_lshl_or_b32 v66, v85, 6, s42
	v_cmp_lt_i32_e32 vcc, s33, v66
	v_mfma_f32_16x16x32_bf16 v[52:55], v[4:7], v[88:91], v[20:23]
	s_barrier
	v_mfma_f32_16x16x32_bf16 v[36:39], v[4:7], v[92:95], v[16:19]
	v_mfma_f32_16x16x32_bf16 v[20:23], v[4:7], v[108:111], v[100:103]
	v_mfma_f32_16x16x32_bf16 v[4:7], v[4:7], v[112:115], v[104:107]
	v_mfma_f32_16x16x32_bf16 v[48:51], v[96:99], v[88:91], v[70:73]
	v_mfma_f32_16x16x32_bf16 v[16:19], v[96:99], v[108:111], v[74:77]
	s_nop 1
	v_lshlrev_b32_e32 v70, 2, v84
	v_or_b32_e32 v64, v66, v70
	v_lshl_add_u32 v74, v86, 6, v0
	v_mfma_f32_16x16x32_bf16 v[0:3], v[96:99], v[112:115], v[78:81]
	s_nop 7
	v_readfirstlane_b32 s99, v66
	s_cmpk_lt_u32 s99, 0x400
	s_cbranch_scc0 .Lfe_A_not_q
	s_load_dwordx2 s[100:101], s[56:57], 0x130
	v_and_b32_e32 v152, 1, v84
	v_mul_u32_u24_e32 v152, 12, v152
	v_lshl_add_u32 v152, v84, 2, v152
	v_add_u32_e32 v152, v152, v66
	v_mul_u32_u24_e32 v153, 0xe00, v74
	v_add_u32_e32 v152, v152, v153
	v_lshlrev_b32_e32 v152, 1, v152
	v_add_u32_e32 v153, 0x1c000, v152
	v_add_u32_e32 v154, 0x38000, v152
	v_add_u32_e32 v155, 0x54000, v152
	s_mov_b32 s98, 0x3e38aa3b
	s_nop 3
	v_pk_mul_f32 v[60:61], v[60:61], s[98:99] op_sel_hi:[1,0]
	v_pk_mul_f32 v[62:63], v[62:63], s[98:99] op_sel_hi:[1,0]
	v_pk_mul_f32 v[56:57], v[56:57], s[98:99] op_sel_hi:[1,0]
	v_pk_mul_f32 v[58:59], v[58:59], s[98:99] op_sel_hi:[1,0]
	v_pk_mul_f32 v[52:53], v[52:53], s[98:99] op_sel_hi:[1,0]
	v_pk_mul_f32 v[54:55], v[54:55], s[98:99] op_sel_hi:[1,0]
	v_pk_mul_f32 v[48:49], v[48:49], s[98:99] op_sel_hi:[1,0]
	v_pk_mul_f32 v[50:51], v[50:51], s[98:99] op_sel_hi:[1,0]
	v_cvt_pk_bf16_f32 v120, v60, v61
	v_cvt_pk_bf16_f32 v121, v62, v63
	v_cvt_pk_bf16_f32 v122, v56, v57
	v_cvt_pk_bf16_f32 v123, v58, v59
	v_cvt_pk_bf16_f32 v124, v52, v53
	v_cvt_pk_bf16_f32 v125, v54, v55
	v_cvt_pk_bf16_f32 v126, v48, v49
	v_cvt_pk_bf16_f32 v127, v50, v51
	s_nop 1
	v_permlane16_swap_b32_e32 v120, v122
	v_permlane16_swap_b32_e32 v121, v123
	v_permlane16_swap_b32_e32 v124, v126
	v_permlane16_swap_b32_e32 v125, v127
	s_waitcnt lgkmcnt(0)
; DI unsigned pack2(float a, float b) { v2f f = {a, b}; return __builtin_bit_cast(unsigned, __builtin_convertvector(f, v2bf)); }
; DI float silu_f(float v) { return v / (1.f + fexp(-v)); }
;   DI u32x2 pack(int, int, float a, float b, float c, float d, float&) const { u32x2 v; v.x = pack2(a, b); v.y = pack2(c, d); return v; }
; template <class ARow, class Epi>
; DI void gemm_tile(const ARow& arow, long a_kstride, const u16* __restrict__ Bt, long ldb, int K, int m0, int n0,
;                   const Epi& epi, char* smem) {
;     ...
;   const int nh = n0 + wn * 64;
;   if (epi.packed(nh)) {
; #pragma unroll
;     for (int mi = 0; mi < 4; ++mi) {
;       const int m = m0 + wm * 64 + mi * 16 + fr;
;       float ss = 0.f;
;       u32x2 pk[4];
; #pragma unroll
;       for (int ni = 0; ni < 4; ++ni) pk[ni] = epi.pack(m, nh + ni * 16 + fq * 4, acc[ni][mi][0], acc[ni][mi][1], acc[ni][mi][2], acc[ni][mi][3], ss);
;       epi.finish16(m, nh, ss);
;       u16* rp = epi.rowp(m) + nh;
; #pragma unroll
;       for (int pp = 0; pp < 2; ++pp) {
;         u32x2 a = pk[2 * pp], b = pk[2 * pp + 1];
;         const u32x2 rx = __builtin_amdgcn_permlane16_swap(a.x, b.x, false, false);
;         const u32x2 ry = __builtin_amdgcn_permlane16_swap(a.y, b.y, false, false);
;         const int nst = (fq & 1) ? ((2 * pp + 1) * 16 + (fq - 1) * 4) : ((2 * pp) * 16 + fq * 4);
;         *(u32x4*)(rp + nst) = (u32x4){rx[0], ry[0], rx[1], ry[1]};
;       }
;   DI u32x2 pack(int m, int n, float a, float b, float c, float d, float& ss) const {
;     if (n < q_end) { a *= qscale; b *= qscale; c *= qscale; d *= qscale; }
;     else if (n >= z_start) { a = silu_f(a); b = silu_f(b); c = silu_f(c); d = silu_f(d); }
;     ss += a * a + b * b + c * c + d * d;
;     u32x2 v; v.x = pack2(a, b); v.y = pack2(c, d);
;     return v;
;   }
	global_store_dwordx4 v152, v[120:123], s[100:101]
	global_store_dwordx4 v152, v[124:127], s[100:101] offset:64
	v_pk_mul_f32 v[44:45], v[44:45], s[98:99] op_sel_hi:[1,0]
	v_pk_mul_f32 v[46:47], v[46:47], s[98:99] op_sel_hi:[1,0]
	v_pk_mul_f32 v[40:41], v[40:41], s[98:99] op_sel_hi:[1,0]
	v_pk_mul_f32 v[42:43], v[42:43], s[98:99] op_sel_hi:[1,0]
	v_pk_mul_f32 v[36:37], v[36:37], s[98:99] op_sel_hi:[1,0]
	v_pk_mul_f32 v[38:39], v[38:39], s[98:99] op_sel_hi:[1,0]
	v_pk_mul_f32 v[32:33], v[32:33], s[98:99] op_sel_hi:[1,0]
	v_pk_mul_f32 v[34:35], v[34:35], s[98:99] op_sel_hi:[1,0]
	v_cvt_pk_bf16_f32 v128, v44, v45
	v_cvt_pk_bf16_f32 v129, v46, v47
	v_cvt_pk_bf16_f32 v130, v40, v41
	v_cvt_pk_bf16_f32 v131, v42, v43
	v_cvt_pk_bf16_f32 v132, v36, v37
	v_cvt_pk_bf16_f32 v133, v38, v39
	v_cvt_pk_bf16_f32 v134, v32, v33
	v_cvt_pk_bf16_f32 v135, v34, v35
	s_nop 1
	v_permlane16_swap_b32_e32 v128, v130
	v_permlane16_swap_b32_e32 v129, v131
	v_permlane16_swap_b32_e32 v132, v134
	v_permlane16_swap_b32_e32 v133, v135
	global_store_dwordx4 v153, v[128:131], s[100:101]
	global_store_dwordx4 v153, v[132:135], s[100:101] offset:64
	v_pk_mul_f32 v[28:29], v[28:29], s[98:99] op_sel_hi:[1,0]
	v_pk_mul_f32 v[30:31], v[30:31], s[98:99] op_sel_hi:[1,0]
	v_pk_mul_f32 v[24:25], v[24:25], s[98:99] op_sel_hi:[1,0]
	v_pk_mul_f32 v[26:27], v[26:27], s[98:99] op_sel_hi:[1,0]
	v_pk_mul_f32 v[20:21], v[20:21], s[98:99] op_sel_hi:[1,0]
	v_pk_mul_f32 v[22:23], v[22:23], s[98:99] op_sel_hi:[1,0]
	v_pk_mul_f32 v[16:17], v[16:17], s[98:99] op_sel_hi:[1,0]
	v_pk_mul_f32 v[18:19], v[18:19], s[98:99] op_sel_hi:[1,0]
	v_cvt_pk_bf16_f32 v136, v28, v29
	v_cvt_pk_bf16_f32 v137, v30, v31
	v_cvt_pk_bf16_f32 v138, v24, v25
	v_cvt_pk_bf16_f32 v139, v26, v27
	v_cvt_pk_bf16_f32 v140, v20, v21
	v_cvt_pk_bf16_f32 v141, v22, v23
	v_cvt_pk_bf16_f32 v142, v16, v17
	v_cvt_pk_bf16_f32 v143, v18, v19
	s_nop 1
	v_permlane16_swap_b32_e32 v136, v138
	v_permlane16_swap_b32_e32 v137, v139
	v_permlane16_swap_b32_e32 v140, v142
	v_permlane16_swap_b32_e32 v141, v143
	global_store_dwordx4 v154, v[136:139], s[100:101]
	global_store_dwordx4 v154, v[140:143], s[100:101] offset:64
	v_pk_mul_f32 v[12:13], v[12:13], s[98:99] op_sel_hi:[1,0]
	v_pk_mul_f32 v[14:15], v[14:15], s[98:99] op_sel_hi:[1,0]
	v_pk_mul_f32 v[8:9], v[8:9], s[98:99] op_sel_hi:[1,0]
	v_pk_mul_f32 v[10:11], v[10:11], s[98:99] op_sel_hi:[1,0]
	v_pk_mul_f32 v[4:5], v[4:5], s[98:99] op_sel_hi:[1,0]
	v_pk_mul_f32 v[6:7], v[6:7], s[98:99] op_sel_hi:[1,0]
	v_pk_mul_f32 v[0:1], v[0:1], s[98:99] op_sel_hi:[1,0]
	v_pk_mul_f32 v[2:3], v[2:3], s[98:99] op_sel_hi:[1,0]
	v_cvt_pk_bf16_f32 v144, v12, v13
	v_cvt_pk_bf16_f32 v145, v14, v15
	v_cvt_pk_bf16_f32 v146, v8, v9
	v_cvt_pk_bf16_f32 v147, v10, v11
	v_cvt_pk_bf16_f32 v148, v4, v5
	v_cvt_pk_bf16_f32 v149, v6, v7
	v_cvt_pk_bf16_f32 v150, v0, v1
	v_cvt_pk_bf16_f32 v151, v2, v3
	s_nop 1
	v_permlane16_swap_b32_e32 v144, v146
	v_permlane16_swap_b32_e32 v145, v147
	v_permlane16_swap_b32_e32 v148, v150
	v_permlane16_swap_b32_e32 v149, v151
	global_store_dwordx4 v155, v[144:147], s[100:101]
	global_store_dwordx4 v155, v[148:151], s[100:101] offset:64
	s_branch .Lfe_join_A
.Lfe_A_not_q:
	s_cmpk_ge_u32 s99, 0xa00
	s_cbranch_scc0 .Lfe_A_not_z
	s_cmpk_lt_u32 s99, 0xe00
	s_cbranch_scc0 .Lfe_A_not_z
	s_load_dwordx2 s[100:101], s[56:57], 0x130
	v_and_b32_e32 v152, 1, v84
	v_mul_u32_u24_e32 v152, 12, v152
	v_lshl_add_u32 v152, v84, 2, v152
	v_add_u32_e32 v152, v152, v66
	v_mul_u32_u24_e32 v153, 0xe00, v74
	v_add_u32_e32 v152, v152, v153
	v_lshlrev_b32_e32 v152, 1, v152
	v_add_u32_e32 v153, 0x1c000, v152
	v_add_u32_e32 v154, 0x38000, v152
	v_add_u32_e32 v155, 0x54000, v152
	s_nop 3
	v_mul_f32_e32 v156, 0xbfb8aa3b, v60
	v_mul_f32_e32 v157, 0xbfb8aa3b, v61
	v_mul_f32_e32 v158, 0xbfb8aa3b, v62
	v_mul_f32_e32 v159, 0xbfb8aa3b, v63
	v_mul_f32_e32 v160, 0xbfb8aa3b, v56
	v_mul_f32_e32 v161, 0xbfb8aa3b, v57
	v_mul_f32_e32 v162, 0xbfb8aa3b, v58
	v_mul_f32_e32 v163, 0xbfb8aa3b, v59
	v_exp_f32_e32 v156, v156
	v_exp_f32_e32 v157, v157
	v_exp_f32_e32 v158, v158
	v_exp_f32_e32 v159, v159
	v_exp_f32_e32 v160, v160
	v_exp_f32_e32 v161, v161
	v_exp_f32_e32 v162, v162
	v_exp_f32_e32 v163, v163
	v_add_f32_e32 v156, 1.0, v156
	v_add_f32_e32 v157, 1.0, v157
	v_add_f32_e32 v158, 1.0, v158
	v_add_f32_e32 v159, 1.0, v159
	v_add_f32_e32 v160, 1.0, v160
	v_add_f32_e32 v161, 1.0, v161
	v_add_f32_e32 v162, 1.0, v162
	v_add_f32_e32 v163, 1.0, v163
	v_rcp_f32_e32 v156, v156
	v_rcp_f32_e32 v157, v157
	v_rcp_f32_e32 v158, v158
	v_rcp_f32_e32 v159, v159
	v_rcp_f32_e32 v160, v160
	v_rcp_f32_e32 v161, v161
	v_rcp_f32_e32 v162, v162
	v_rcp_f32_e32 v163, v163
	v_mul_f32_e32 v60, v60, v156
	v_mul_f32_e32 v61, v61, v157
	v_mul_f32_e32 v62, v62, v158
	v_mul_f32_e32 v63, v63, v159
	v_mul_f32_e32 v56, v56, v160
	v_mul_f32_e32 v57, v57, v161
	v_mul_f32_e32 v58, v58, v162
	v_mul_f32_e32 v59, v59, v163
	v_mul_f32_e32 v156, 0xbfb8aa3b, v52
	v_mul_f32_e32 v157, 0xbfb8aa3b, v53
	v_mul_f32_e32 v158, 0xbfb8aa3b, v54
	v_mul_f32_e32 v159, 0xbfb8aa3b, v55
	v_mul_f32_e32 v160, 0xbfb8aa3b, v48
	v_mul_f32_e32 v161, 0xbfb8aa3b, v49
	v_mul_f32_e32 v162, 0xbfb8aa3b, v50
	v_mul_f32_e32 v163, 0xbfb8aa3b, v51
	v_exp_f32_e32 v156, v156
	v_exp_f32_e32 v157, v157
	v_exp_f32_e32 v158, v158
	v_exp_f32_e32 v159, v159
	v_exp_f32_e32 v160, v160
	v_exp_f32_e32 v161, v161
	v_exp_f32_e32 v162, v162
	v_exp_f32_e32 v163, v163
	v_add_f32_e32 v156, 1.0, v156
	v_add_f32_e32 v157, 1.0, v157
	v_add_f32_e32 v158, 1.0, v158
	v_add_f32_e32 v159, 1.0, v159
	v_add_f32_e32 v160, 1.0, v160
	v_add_f32_e32 v161, 1.0, v161
	v_add_f32_e32 v162, 1.0, v162
	v_add_f32_e32 v163, 1.0, v163
	v_rcp_f32_e32 v156, v156
	v_rcp_f32_e32 v157, v157
	v_rcp_f32_e32 v158, v158
	v_rcp_f32_e32 v159, v159
	v_rcp_f32_e32 v160, v160
	v_rcp_f32_e32 v161, v161
	v_rcp_f32_e32 v162, v162
	v_rcp_f32_e32 v163, v163
	v_mul_f32_e32 v52, v52, v156
	v_mul_f32_e32 v53, v53, v157
	v_mul_f32_e32 v54, v54, v158
	v_mul_f32_e32 v55, v55, v159
	v_mul_f32_e32 v48, v48, v160
	v_mul_f32_e32 v49, v49, v161
	v_mul_f32_e32 v50, v50, v162
	v_mul_f32_e32 v51, v51, v163
	v_cvt_pk_bf16_f32 v120, v60, v61
	v_cvt_pk_bf16_f32 v121, v62, v63
	v_cvt_pk_bf16_f32 v122, v56, v57
	v_cvt_pk_bf16_f32 v123, v58, v59
	v_cvt_pk_bf16_f32 v124, v52, v53
	v_cvt_pk_bf16_f32 v125, v54, v55
	v_cvt_pk_bf16_f32 v126, v48, v49
	v_cvt_pk_bf16_f32 v127, v50, v51
	s_nop 1
	v_permlane16_swap_b32_e32 v120, v122
	v_permlane16_swap_b32_e32 v121, v123
	v_permlane16_swap_b32_e32 v124, v126
	v_permlane16_swap_b32_e32 v125, v127
	s_waitcnt lgkmcnt(0)
; DI unsigned pack2(float a, float b) { v2f f = {a, b}; return __builtin_bit_cast(unsigned, __builtin_convertvector(f, v2bf)); }
;   DI u32x2 pack(int, int, float a, float b, float c, float d, float&) const { u32x2 v; v.x = pack2(a, b); v.y = pack2(c, d); return v; }
; DI float fexp(float x) { return __builtin_amdgcn_exp2f(x * LOG2E); }
; DI float flog(float x) { return __builtin_amdgcn_logf(x) * 0.6931471805599453f; }
; DI float silu_f(float v) { return v / (1.f + fexp(-v)); }
; template <class ARow, class Epi>
; DI void gemm_tile(const ARow& arow, long a_kstride, const u16* __restrict__ Bt, long ldb, int K, int m0, int n0,
;                   const Epi& epi, char* smem) {
;     ...
;   const int nh = n0 + wn * 64;
;   if (epi.packed(nh)) {
; #pragma unroll
;     for (int mi = 0; mi < 4; ++mi) {
;       const int m = m0 + wm * 64 + mi * 16 + fr;
;       float ss = 0.f;
;       u32x2 pk[4];
; #pragma unroll
;       for (int ni = 0; ni < 4; ++ni) pk[ni] = epi.pack(m, nh + ni * 16 + fq * 4, acc[ni][mi][0], acc[ni][mi][1], acc[ni][mi][2], acc[ni][mi][3], ss);
;       epi.finish16(m, nh, ss);
;       u16* rp = epi.rowp(m) + nh;
; #pragma unroll
;       for (int pp = 0; pp < 2; ++pp) {
;         u32x2 a = pk[2 * pp], b = pk[2 * pp + 1];
;         const u32x2 rx = __builtin_amdgcn_permlane16_swap(a.x, b.x, false, false);
;         const u32x2 ry = __builtin_amdgcn_permlane16_swap(a.y, b.y, false, false);
;         const int nst = (fq & 1) ? ((2 * pp + 1) * 16 + (fq - 1) * 4) : ((2 * pp) * 16 + fq * 4);
;         *(u32x4*)(rp + nst) = (u32x4){rx[0], ry[0], rx[1], ry[1]};
;       }
;   DI u32x2 pack(int m, int n, float a, float b, float c, float d, float& ss) const {
;     if (n < q_end) { a *= qscale; b *= qscale; c *= qscale; d *= qscale; }
;     else if (n >= z_start) { a = silu_f(a); b = silu_f(b); c = silu_f(c); d = silu_f(d); }
;     ss += a * a + b * b + c * c + d * d;
;     u32x2 v; v.x = pack2(a, b); v.y = pack2(c, d);
;     return v;
;   }
	global_store_dwordx4 v152, v[120:123], s[100:101]
	global_store_dwordx4 v152, v[124:127], s[100:101] offset:64
	v_mul_f32_e32 v156, 0xbfb8aa3b, v44
	v_mul_f32_e32 v157, 0xbfb8aa3b, v45
	v_mul_f32_e32 v158, 0xbfb8aa3b, v46
	v_mul_f32_e32 v159, 0xbfb8aa3b, v47
	v_mul_f32_e32 v160, 0xbfb8aa3b, v40
	v_mul_f32_e32 v161, 0xbfb8aa3b, v41
	v_mul_f32_e32 v162, 0xbfb8aa3b, v42
	v_mul_f32_e32 v163, 0xbfb8aa3b, v43
	v_exp_f32_e32 v156, v156
	v_exp_f32_e32 v157, v157
	v_exp_f32_e32 v158, v158
	v_exp_f32_e32 v159, v159
	v_exp_f32_e32 v160, v160
	v_exp_f32_e32 v161, v161
	v_exp_f32_e32 v162, v162
	v_exp_f32_e32 v163, v163
	v_add_f32_e32 v156, 1.0, v156
	v_add_f32_e32 v157, 1.0, v157
	v_add_f32_e32 v158, 1.0, v158
	v_add_f32_e32 v159, 1.0, v159
	v_add_f32_e32 v160, 1.0, v160
	v_add_f32_e32 v161, 1.0, v161
	v_add_f32_e32 v162, 1.0, v162
	v_add_f32_e32 v163, 1.0, v163
	v_rcp_f32_e32 v156, v156
	v_rcp_f32_e32 v157, v157
	v_rcp_f32_e32 v158, v158
	v_rcp_f32_e32 v159, v159
	v_rcp_f32_e32 v160, v160
	v_rcp_f32_e32 v161, v161
	v_rcp_f32_e32 v162, v162
	v_rcp_f32_e32 v163, v163
	v_mul_f32_e32 v44, v44, v156
	v_mul_f32_e32 v45, v45, v157
	v_mul_f32_e32 v46, v46, v158
	v_mul_f32_e32 v47, v47, v159
	v_mul_f32_e32 v40, v40, v160
	v_mul_f32_e32 v41, v41, v161
	v_mul_f32_e32 v42, v42, v162
	v_mul_f32_e32 v43, v43, v163
	v_mul_f32_e32 v156, 0xbfb8aa3b, v36
	v_mul_f32_e32 v157, 0xbfb8aa3b, v37
	v_mul_f32_e32 v158, 0xbfb8aa3b, v38
	v_mul_f32_e32 v159, 0xbfb8aa3b, v39
	v_mul_f32_e32 v160, 0xbfb8aa3b, v32
	v_mul_f32_e32 v161, 0xbfb8aa3b, v33
	v_mul_f32_e32 v162, 0xbfb8aa3b, v34
	v_mul_f32_e32 v163, 0xbfb8aa3b, v35
	v_exp_f32_e32 v156, v156
	v_exp_f32_e32 v157, v157
	v_exp_f32_e32 v158, v158
	v_exp_f32_e32 v159, v159
	v_exp_f32_e32 v160, v160
	v_exp_f32_e32 v161, v161
	v_exp_f32_e32 v162, v162
	v_exp_f32_e32 v163, v163
	v_add_f32_e32 v156, 1.0, v156
	v_add_f32_e32 v157, 1.0, v157
	v_add_f32_e32 v158, 1.0, v158
	v_add_f32_e32 v159, 1.0, v159
	v_add_f32_e32 v160, 1.0, v160
	v_add_f32_e32 v161, 1.0, v161
	v_add_f32_e32 v162, 1.0, v162
	v_add_f32_e32 v163, 1.0, v163
	v_rcp_f32_e32 v156, v156
	v_rcp_f32_e32 v157, v157
	v_rcp_f32_e32 v158, v158
	v_rcp_f32_e32 v159, v159
	v_rcp_f32_e32 v160, v160
	v_rcp_f32_e32 v161, v161
	v_rcp_f32_e32 v162, v162
	v_rcp_f32_e32 v163, v163
	v_mul_f32_e32 v36, v36, v156
	v_mul_f32_e32 v37, v37, v157
	v_mul_f32_e32 v38, v38, v158
	v_mul_f32_e32 v39, v39, v159
	v_mul_f32_e32 v32, v32, v160
	v_mul_f32_e32 v33, v33, v161
	v_mul_f32_e32 v34, v34, v162
	v_mul_f32_e32 v35, v35, v163
	v_cvt_pk_bf16_f32 v128, v44, v45
	v_cvt_pk_bf16_f32 v129, v46, v47
	v_cvt_pk_bf16_f32 v130, v40, v41
	v_cvt_pk_bf16_f32 v131, v42, v43
	v_cvt_pk_bf16_f32 v132, v36, v37
	v_cvt_pk_bf16_f32 v133, v38, v39
	v_cvt_pk_bf16_f32 v134, v32, v33
	v_cvt_pk_bf16_f32 v135, v34, v35
	s_nop 1
	v_permlane16_swap_b32_e32 v128, v130
	v_permlane16_swap_b32_e32 v129, v131
	v_permlane16_swap_b32_e32 v132, v134
	v_permlane16_swap_b32_e32 v133, v135
	global_store_dwordx4 v153, v[128:131], s[100:101]
	global_store_dwordx4 v153, v[132:135], s[100:101] offset:64
	v_mul_f32_e32 v156, 0xbfb8aa3b, v28
	v_mul_f32_e32 v157, 0xbfb8aa3b, v29
	v_mul_f32_e32 v158, 0xbfb8aa3b, v30
	v_mul_f32_e32 v159, 0xbfb8aa3b, v31
	v_mul_f32_e32 v160, 0xbfb8aa3b, v24
	v_mul_f32_e32 v161, 0xbfb8aa3b, v25
	v_mul_f32_e32 v162, 0xbfb8aa3b, v26
	v_mul_f32_e32 v163, 0xbfb8aa3b, v27
	v_exp_f32_e32 v156, v156
	v_exp_f32_e32 v157, v157
	v_exp_f32_e32 v158, v158
	v_exp_f32_e32 v159, v159
	v_exp_f32_e32 v160, v160
	v_exp_f32_e32 v161, v161
	v_exp_f32_e32 v162, v162
	v_exp_f32_e32 v163, v163
	v_add_f32_e32 v156, 1.0, v156
	v_add_f32_e32 v157, 1.0, v157
	v_add_f32_e32 v158, 1.0, v158
	v_add_f32_e32 v159, 1.0, v159
	v_add_f32_e32 v160, 1.0, v160
	v_add_f32_e32 v161, 1.0, v161
	v_add_f32_e32 v162, 1.0, v162
	v_add_f32_e32 v163, 1.0, v163
	v_rcp_f32_e32 v156, v156
	v_rcp_f32_e32 v157, v157
	v_rcp_f32_e32 v158, v158
	v_rcp_f32_e32 v159, v159
	v_rcp_f32_e32 v160, v160
	v_rcp_f32_e32 v161, v161
	v_rcp_f32_e32 v162, v162
	v_rcp_f32_e32 v163, v163
	v_mul_f32_e32 v28, v28, v156
	v_mul_f32_e32 v29, v29, v157
	v_mul_f32_e32 v30, v30, v158
	v_mul_f32_e32 v31, v31, v159
	v_mul_f32_e32 v24, v24, v160
	v_mul_f32_e32 v25, v25, v161
	v_mul_f32_e32 v26, v26, v162
	v_mul_f32_e32 v27, v27, v163
	v_mul_f32_e32 v156, 0xbfb8aa3b, v20
	v_mul_f32_e32 v157, 0xbfb8aa3b, v21
	v_mul_f32_e32 v158, 0xbfb8aa3b, v22
	v_mul_f32_e32 v159, 0xbfb8aa3b, v23
	v_mul_f32_e32 v160, 0xbfb8aa3b, v16
	v_mul_f32_e32 v161, 0xbfb8aa3b, v17
	v_mul_f32_e32 v162, 0xbfb8aa3b, v18
	v_mul_f32_e32 v163, 0xbfb8aa3b, v19
	v_exp_f32_e32 v156, v156
	v_exp_f32_e32 v157, v157
	v_exp_f32_e32 v158, v158
	v_exp_f32_e32 v159, v159
	v_exp_f32_e32 v160, v160
	v_exp_f32_e32 v161, v161
	v_exp_f32_e32 v162, v162
	v_exp_f32_e32 v163, v163
	v_add_f32_e32 v156, 1.0, v156
	v_add_f32_e32 v157, 1.0, v157
	v_add_f32_e32 v158, 1.0, v158
	v_add_f32_e32 v159, 1.0, v159
	v_add_f32_e32 v160, 1.0, v160
	v_add_f32_e32 v161, 1.0, v161
	v_add_f32_e32 v162, 1.0, v162
	v_add_f32_e32 v163, 1.0, v163
	v_rcp_f32_e32 v156, v156
; DI unsigned pack2(float a, float b) { v2f f = {a, b}; return __builtin_bit_cast(unsigned, __builtin_convertvector(f, v2bf)); }
; DI float silu_f(float v) { return v / (1.f + fexp(-v)); }
; DI float sigmoid_f(float v) { return 1.f / (1.f + fexp(-v)); }
;   DI u32x2 pack(int, int, float a, float b, float c, float d, float&) const { u32x2 v; v.x = pack2(a, b); v.y = pack2(c, d); return v; }
;   DI void operator()(int m, int n, float a, float b, float c, float d, float& ss) const { u32x2 v; v.x = pack2(a, b); v.y = pack2(c, d); *(u32x2*)(y + (long)m * 1024 + n) = v; }
; template <class ARow, class Epi>
; DI void gemm_tile(const ARow& arow, long a_kstride, const u16* __restrict__ Bt, long ldb, int K, int m0, int n0,
;                   const Epi& epi, char* smem) {
;     ...
;   const int nh = n0 + wn * 64;
;   if (epi.packed(nh)) {
; #pragma unroll
;     for (int mi = 0; mi < 4; ++mi) {
;       const int m = m0 + wm * 64 + mi * 16 + fr;
;       float ss = 0.f;
;       u32x2 pk[4];
; #pragma unroll
;       for (int ni = 0; ni < 4; ++ni) pk[ni] = epi.pack(m, nh + ni * 16 + fq * 4, acc[ni][mi][0], acc[ni][mi][1], acc[ni][mi][2], acc[ni][mi][3], ss);
;       epi.finish16(m, nh, ss);
;       u16* rp = epi.rowp(m) + nh;
; #pragma unroll
;       for (int pp = 0; pp < 2; ++pp) {
;         u32x2 a = pk[2 * pp], b = pk[2 * pp + 1];
;         const u32x2 rx = __builtin_amdgcn_permlane16_swap(a.x, b.x, false, false);
;         const u32x2 ry = __builtin_amdgcn_permlane16_swap(a.y, b.y, false, false);
;         const int nst = (fq & 1) ? ((2 * pp + 1) * 16 + (fq - 1) * 4) : ((2 * pp) * 16 + fq * 4);
;         *(u32x4*)(rp + nst) = (u32x4){rx[0], ry[0], rx[1], ry[1]};
;       }
;   DI void operator()(int m, int n, float a, float b, float c, float d, float& ss) const {
;     if (n >= gl_start) {
;       const int j = n - gl_start;
;       if (j < 48) { float* g = gates + (long)m * 48 + j; g[0] = sigmoid_f(a); g[1] = sigmoid_f(b); g[2] = sigmoid_f(c); g[3] = sigmoid_f(d); }
;       return;
;   DI u32x2 pack(int m, int n, float a, float b, float c, float d, float& ss) const {
;     if (n < q_end) { a *= qscale; b *= qscale; c *= qscale; d *= qscale; }
;     else if (n >= z_start) { a = silu_f(a); b = silu_f(b); c = silu_f(c); d = silu_f(d); }
;     ss += a * a + b * b + c * c + d * d;
;     u32x2 v; v.x = pack2(a, b); v.y = pack2(c, d);
;     return v;
;   }
	v_rcp_f32_e32 v157, v157
	v_rcp_f32_e32 v158, v158
	v_rcp_f32_e32 v159, v159
	v_rcp_f32_e32 v160, v160
	v_rcp_f32_e32 v161, v161
	v_rcp_f32_e32 v162, v162
	v_rcp_f32_e32 v163, v163
	v_mul_f32_e32 v20, v20, v156
	v_mul_f32_e32 v21, v21, v157
	v_mul_f32_e32 v22, v22, v158
	v_mul_f32_e32 v23, v23, v159
	v_mul_f32_e32 v16, v16, v160
	v_mul_f32_e32 v17, v17, v161
	v_mul_f32_e32 v18, v18, v162
	v_mul_f32_e32 v19, v19, v163
	v_cvt_pk_bf16_f32 v136, v28, v29
	v_cvt_pk_bf16_f32 v137, v30, v31
	v_cvt_pk_bf16_f32 v138, v24, v25
	v_cvt_pk_bf16_f32 v139, v26, v27
	v_cvt_pk_bf16_f32 v140, v20, v21
	v_cvt_pk_bf16_f32 v141, v22, v23
	v_cvt_pk_bf16_f32 v142, v16, v17
	v_cvt_pk_bf16_f32 v143, v18, v19
	s_nop 1
	v_permlane16_swap_b32_e32 v136, v138
	v_permlane16_swap_b32_e32 v137, v139
	v_permlane16_swap_b32_e32 v140, v142
	v_permlane16_swap_b32_e32 v141, v143
	global_store_dwordx4 v154, v[136:139], s[100:101]
	global_store_dwordx4 v154, v[140:143], s[100:101] offset:64
	v_mul_f32_e32 v156, 0xbfb8aa3b, v12
	v_mul_f32_e32 v157, 0xbfb8aa3b, v13
	v_mul_f32_e32 v158, 0xbfb8aa3b, v14
	v_mul_f32_e32 v159, 0xbfb8aa3b, v15
	v_mul_f32_e32 v160, 0xbfb8aa3b, v8
	v_mul_f32_e32 v161, 0xbfb8aa3b, v9
	v_mul_f32_e32 v162, 0xbfb8aa3b, v10
	v_mul_f32_e32 v163, 0xbfb8aa3b, v11
	v_exp_f32_e32 v156, v156
	v_exp_f32_e32 v157, v157
	v_exp_f32_e32 v158, v158
	v_exp_f32_e32 v159, v159
	v_exp_f32_e32 v160, v160
	v_exp_f32_e32 v161, v161
	v_exp_f32_e32 v162, v162
	v_exp_f32_e32 v163, v163
	v_add_f32_e32 v156, 1.0, v156
	v_add_f32_e32 v157, 1.0, v157
	v_add_f32_e32 v158, 1.0, v158
	v_add_f32_e32 v159, 1.0, v159
	v_add_f32_e32 v160, 1.0, v160
	v_add_f32_e32 v161, 1.0, v161
	v_add_f32_e32 v162, 1.0, v162
	v_add_f32_e32 v163, 1.0, v163
	v_rcp_f32_e32 v156, v156
	v_rcp_f32_e32 v157, v157
	v_rcp_f32_e32 v158, v158
	v_rcp_f32_e32 v159, v159
	v_rcp_f32_e32 v160, v160
	v_rcp_f32_e32 v161, v161
	v_rcp_f32_e32 v162, v162
	v_rcp_f32_e32 v163, v163
	v_mul_f32_e32 v12, v12, v156
	v_mul_f32_e32 v13, v13, v157
	v_mul_f32_e32 v14, v14, v158
	v_mul_f32_e32 v15, v15, v159
	v_mul_f32_e32 v8, v8, v160
	v_mul_f32_e32 v9, v9, v161
	v_mul_f32_e32 v10, v10, v162
	v_mul_f32_e32 v11, v11, v163
	v_mul_f32_e32 v156, 0xbfb8aa3b, v4
	v_mul_f32_e32 v157, 0xbfb8aa3b, v5
	v_mul_f32_e32 v158, 0xbfb8aa3b, v6
	v_mul_f32_e32 v159, 0xbfb8aa3b, v7
	v_mul_f32_e32 v160, 0xbfb8aa3b, v0
	v_mul_f32_e32 v161, 0xbfb8aa3b, v1
	v_mul_f32_e32 v162, 0xbfb8aa3b, v2
	v_mul_f32_e32 v163, 0xbfb8aa3b, v3
	v_exp_f32_e32 v156, v156
	v_exp_f32_e32 v157, v157
	v_exp_f32_e32 v158, v158
	v_exp_f32_e32 v159, v159
	v_exp_f32_e32 v160, v160
	v_exp_f32_e32 v161, v161
	v_exp_f32_e32 v162, v162
	v_exp_f32_e32 v163, v163
	v_add_f32_e32 v156, 1.0, v156
	v_add_f32_e32 v157, 1.0, v157
	v_add_f32_e32 v158, 1.0, v158
	v_add_f32_e32 v159, 1.0, v159
	v_add_f32_e32 v160, 1.0, v160
	v_add_f32_e32 v161, 1.0, v161
	v_add_f32_e32 v162, 1.0, v162
	v_add_f32_e32 v163, 1.0, v163
	v_rcp_f32_e32 v156, v156
	v_rcp_f32_e32 v157, v157
	v_rcp_f32_e32 v158, v158
	v_rcp_f32_e32 v159, v159
	v_rcp_f32_e32 v160, v160
	v_rcp_f32_e32 v161, v161
	v_rcp_f32_e32 v162, v162
	v_rcp_f32_e32 v163, v163
	v_mul_f32_e32 v4, v4, v156
	v_mul_f32_e32 v5, v5, v157
	v_mul_f32_e32 v6, v6, v158
	v_mul_f32_e32 v7, v7, v159
	v_mul_f32_e32 v0, v0, v160
	v_mul_f32_e32 v1, v1, v161
	v_mul_f32_e32 v2, v2, v162
	v_mul_f32_e32 v3, v3, v163
	v_cvt_pk_bf16_f32 v144, v12, v13
	v_cvt_pk_bf16_f32 v145, v14, v15
	v_cvt_pk_bf16_f32 v146, v8, v9
	v_cvt_pk_bf16_f32 v147, v10, v11
	v_cvt_pk_bf16_f32 v148, v4, v5
	v_cvt_pk_bf16_f32 v149, v6, v7
	v_cvt_pk_bf16_f32 v150, v0, v1
	v_cvt_pk_bf16_f32 v151, v2, v3
	s_nop 1
	v_permlane16_swap_b32_e32 v144, v146
	v_permlane16_swap_b32_e32 v145, v147
	v_permlane16_swap_b32_e32 v148, v150
	v_permlane16_swap_b32_e32 v149, v151
	global_store_dwordx4 v155, v[144:147], s[100:101]
	global_store_dwordx4 v155, v[148:151], s[100:101] offset:64
	s_branch .Lfe_join_A
.Lfe_A_not_z:
	s_and_saveexec_b64 s[0:1], vcc
	s_xor_b64 s[12:13], exec, s[0:1]
	s_cbranch_execz .LBB0_364
	v_mad_i64_i32 v[68:69], s[0:1], v74, s38, 0
	v_cmp_lt_i32_e64 s[4:5], s33, v64
	v_add_u32_e32 v66, 0xfffff200, v64
	s_and_saveexec_b64 s[0:1], s[4:5]
	s_xor_b64 s[0:1], exec, s[0:1]
	s_cbranch_execz .LBB0_223
	v_cmp_gt_u32_e32 vcc, 48, v66
	s_and_saveexec_b64 s[6:7], vcc
	s_cbranch_execz .LBB0_222
	v_mul_f32_e32 v60, 0xbfb8aa3b, v60
	v_mul_f32_e32 v61, 0xbfb8aa3b, v61
	v_exp_f32_e32 v60, v60
	v_exp_f32_e32 v61, v61
	v_lshl_add_u64 v[70:71], s[2:3], 0, v[68:69]
	v_mov_b32_e32 v67, v65
	v_lshl_add_u64 v[70:71], v[66:67], 2, v[70:71]
	v_pk_add_f32 v[60:61], v[60:61], 1.0 op_sel_hi:[1,0]
	v_mul_f32_e32 v62, 0xbfb8aa3b, v62
	v_mul_f32_e32 v63, 0xbfb8aa3b, v63
	v_exp_f32_e32 v62, v62
	v_exp_f32_e32 v63, v63
	v_rcp_f32_e32 v67, v61
	s_nop 0
	v_mul_f32_e32 v61, 1.0, v67
	v_pk_add_f32 v[62:63], v[62:63], 1.0 op_sel_hi:[1,0]
	v_rcp_f32_e32 v67, v60
	s_nop 0
	v_mul_f32_e32 v60, 1.0, v67
	v_rcp_f32_e32 v67, v63
	s_nop 0
	v_mul_f32_e32 v63, 1.0, v67
	v_rcp_f32_e32 v67, v62
	s_nop 0
	v_mul_f32_e32 v62, 1.0, v67
	global_store_dwordx4 v[70:71], v[60:63], off

; DI int lbid() { int x = blockIdx.x; asm volatile("" : "+s"(x)); return x; }
; template <class Epi>
; DI void gemm_phase_plain(const u16* A, long lda, const u16* Bt, long ldb, int M, int N, int K, const Epi& epi, char* smem) {
;     ...
;   for (int t = lbid(); t < nwg; t += gridDim.x) {
;     const int xcd = t & 7, off = t >> 3;
;     const int wg = (xcd < rr ? xcd * (q + 1) : rr * (q + 1) + (xcd - rr) * q) + off;
;     const int nig = 8 * MT, gid = wg / nig, fm = gid * 8, gsz = (NT - fm) < 8 ? (NT - fm) : 8;
;     const int nt = fm + (wg % nig) % gsz, mt = (wg % nig) / gsz;
;     gemm_tile(ar, 64, Bt, ldb, K, mt * 128, nt * 128, epi, smem);
.Lfe_join_B:
	s_load_dword s0, s[22:23], 0x0
	s_waitcnt lgkmcnt(0)
	s_add_i32 s29, s0, s29
	s_cmpk_lt_i32 s29, 0x1000
	s_cbranch_scc0 .LBB0_1416

; template <class ARow, class Epi>
; DI void gemm_tile(const ARow& arow, long a_kstride, const u16* __restrict__ Bt, long ldb, int K, int m0, int n0,
;                   const Epi& epi, char* smem) {
;     ...
;   for (int kt = 0; kt < KT; ++kt) {
;     const int cur = kt & 1;
;     if (kt + 1 < KT) GEMM_STAGE(cur ^ 1, kt + 1);
;     const char* sa = smem + cur * 32768 + wm * 64 * 128;
;     const char* sb = smem + cur * 32768 + 16384 + wn * 64 * 128;
; #pragma unroll
;     for (int ks = 0; ks < 2; ++ks) {
;       bf16x8 wf[4], af[4];
; #pragma unroll
;       for (int j = 0; j < 4; ++j) {
;         wf[j] = *(const bf16x8*)(sb + j * 2048 + foff[ks]);
;         af[j] = *(const bf16x8*)(sa + j * 2048 + foff[ks]);
;       }
; #pragma unroll
;       for (int ni = 0; ni < 4; ++ni)
; #pragma unroll
;         for (int mi = 0; mi < 4; ++mi) acc[ni][mi] = __builtin_amdgcn_mfma_f32_16x16x32_bf16(wf[ni], af[mi], acc[ni][mi], 0, 0, 0);
;     }
;     asm volatile("s_waitcnt vmcnt(0)" ::: "memory");
;     __syncthreads();
;   }
.LBB0_1173:
	s_and_b32 s6, s1, 0x8000
	s_xor_b32 s7, s6, 0x8000
	v_add_u32_e32 v108, s7, v91
	v_add_u32_e32 v116, s6, v89
	v_or_b32_e32 v117, s6, v90
	v_readfirstlane_b32 s6, v108
	v_add_u32_e32 v109, 0x4000, v108
	v_lshl_add_u64 v[92:93], v[66:67], 0, s[4:5]
	v_add_u32_e32 v110, 0x400, v108
	v_readfirstlane_b32 s7, v109
	s_mov_b32 m0, s6
	v_lshl_add_u64 v[94:95], v[68:69], 0, s[4:5]
	v_add_u32_e32 v111, 0x4400, v108
	v_readfirstlane_b32 s8, v110
	global_load_lds_dwordx4 v[92:93], off
	s_mov_b32 m0, s7
	v_lshl_add_u64 v[96:97], v[70:71], 0, s[4:5]
	v_add_u32_e32 v113, 0x800, v108
	v_readfirstlane_b32 s9, v111
	global_load_lds_dwordx4 v[94:95], off
	s_mov_b32 m0, s8
	v_lshl_add_u64 v[98:99], v[72:73], 0, s[4:5]
	v_add_u32_e32 v114, 0x4800, v108
	v_readfirstlane_b32 s10, v113
	global_load_lds_dwordx4 v[96:97], off
	s_mov_b32 m0, s9
	v_lshl_add_u64 v[100:101], v[74:75], 0, s[4:5]
	v_add_u32_e32 v115, 0xc00, v108
	v_readfirstlane_b32 s11, v114
	global_load_lds_dwordx4 v[98:99], off
	s_mov_b32 m0, s10
	v_lshl_add_u64 v[102:103], v[76:77], 0, s[4:5]
	v_add_u32_e32 v108, 0x4c00, v108
	v_readfirstlane_b32 s12, v115
	global_load_lds_dwordx4 v[100:101], off
	s_mov_b32 m0, s11
	v_lshl_add_u64 v[104:105], v[78:79], 0, s[4:5]
	v_readfirstlane_b32 s13, v108
	global_load_lds_dwordx4 v[102:103], off
	s_mov_b32 m0, s12
	v_lshl_add_u64 v[106:107], v[80:81], 0, s[4:5]
	global_load_lds_dwordx4 v[104:105], off
	s_mov_b32 m0, s13
	v_add_u32_e32 v118, v117, v88
	global_load_lds_dwordx4 v[106:107], off
	v_add_u32_e32 v112, v116, v88
	ds_read_b128 v[92:95], v118 offset:16384
	ds_read_b128 v[96:99], v112
	ds_read_b128 v[100:103], v118 offset:18432
	ds_read_b128 v[104:107], v112 offset:2048
	ds_read_b128 v[108:111], v112 offset:4096
	ds_read_b128 v[112:115], v112 offset:6144
	s_waitcnt lgkmcnt(0)
	v_mfma_f32_16x16x32_bf16 v[60:63], v[92:95], v[96:99], v[60:63]
	v_add_u32_e32 v117, v117, v87
	v_add_u32_e32 v116, v116, v87
	s_add_i32 s1, s1, 0x8000
	v_mfma_f32_16x16x32_bf16 v[56:59], v[92:95], v[104:107], v[56:59]
	s_add_u32 s4, s4, 0x80
	s_addc_u32 s5, s5, 0
	s_cmpk_eq_i32 s4, 0x780
	v_mfma_f32_16x16x32_bf16 v[48:51], v[92:95], v[108:111], v[48:51]
	v_mfma_f32_16x16x32_bf16 v[40:43], v[92:95], v[112:115], v[40:43]
	v_mfma_f32_16x16x32_bf16 v[36:39], v[100:103], v[96:99], v[36:39]
	v_mfma_f32_16x16x32_bf16 v[32:35], v[100:103], v[104:107], v[32:35]
	v_mfma_f32_16x16x32_bf16 v[28:31], v[100:103], v[108:111], v[28:31]
	v_mfma_f32_16x16x32_bf16 v[24:27], v[100:103], v[112:115], v[24:27]
	ds_read_b128 v[92:95], v118 offset:20480
	ds_read_b128 v[100:103], v118 offset:22528
	s_waitcnt lgkmcnt(0)
	v_mfma_f32_16x16x32_bf16 v[20:23], v[92:95], v[96:99], v[20:23]
	v_mfma_f32_16x16x32_bf16 v[16:19], v[92:95], v[104:107], v[16:19]
	v_mfma_f32_16x16x32_bf16 v[12:15], v[92:95], v[108:111], v[12:15]
	v_mfma_f32_16x16x32_bf16 v[8:11], v[92:95], v[112:115], v[8:11]
	ds_read_b128 v[92:95], v117 offset:16384
	v_mfma_f32_16x16x32_bf16 v[4:7], v[100:103], v[96:99], v[4:7]
	v_mfma_f32_16x16x32_bf16 v[0:3], v[100:103], v[104:107], v[0:3]
	v_mfma_f32_16x16x32_bf16 v[52:55], v[100:103], v[108:111], v[52:55]
	v_mfma_f32_16x16x32_bf16 v[44:47], v[100:103], v[112:115], v[44:47]
	ds_read_b128 v[96:99], v116
	ds_read_b128 v[100:103], v117 offset:18432
	ds_read_b128 v[104:107], v116 offset:2048
	ds_read_b128 v[108:111], v116 offset:4096
	ds_read_b128 v[112:115], v116 offset:6144
	s_waitcnt lgkmcnt(0)
	v_mfma_f32_16x16x32_bf16 v[60:63], v[92:95], v[96:99], v[60:63]
	v_mfma_f32_16x16x32_bf16 v[56:59], v[92:95], v[104:107], v[56:59]
	v_mfma_f32_16x16x32_bf16 v[48:51], v[92:95], v[108:111], v[48:51]
	v_mfma_f32_16x16x32_bf16 v[40:43], v[92:95], v[112:115], v[40:43]
	v_mfma_f32_16x16x32_bf16 v[36:39], v[100:103], v[96:99], v[36:39]
	v_mfma_f32_16x16x32_bf16 v[32:35], v[100:103], v[104:107], v[32:35]
	v_mfma_f32_16x16x32_bf16 v[28:31], v[100:103], v[108:111], v[28:31]
	v_mfma_f32_16x16x32_bf16 v[24:27], v[100:103], v[112:115], v[24:27]
	ds_read_b128 v[92:95], v117 offset:20480
	ds_read_b128 v[100:103], v117 offset:22528
	s_waitcnt vmcnt(0)
	s_waitcnt vmcnt(0) lgkmcnt(0)
	v_mfma_f32_16x16x32_bf16 v[20:23], v[92:95], v[96:99], v[20:23]
	s_barrier
	v_mfma_f32_16x16x32_bf16 v[16:19], v[92:95], v[104:107], v[16:19]
	v_mfma_f32_16x16x32_bf16 v[12:15], v[92:95], v[108:111], v[12:15]
	v_mfma_f32_16x16x32_bf16 v[8:11], v[92:95], v[112:115], v[8:11]
	v_mfma_f32_16x16x32_bf16 v[4:7], v[100:103], v[96:99], v[4:7]
	v_mfma_f32_16x16x32_bf16 v[0:3], v[100:103], v[104:107], v[0:3]
	v_mfma_f32_16x16x32_bf16 v[52:55], v[100:103], v[108:111], v[52:55]
	v_mfma_f32_16x16x32_bf16 v[44:47], v[100:103], v[112:115], v[44:47]
	s_cbranch_scc0 .LBB0_1173
;   DI u32x2 pack(int, int, float a, float b, float c, float d, float&) const { u32x2 v; v.x = pack2(a, b); v.y = pack2(c, d); return v; }
; template <class ARow, class Epi>
; DI void gemm_tile(const ARow& arow, long a_kstride, const u16* __restrict__ Bt, long ldb, int K, int m0, int n0,
;                   const Epi& epi, char* smem) {
;     ...
; #pragma unroll
;     for (int ks = 0; ks < 2; ++ks) {
;       bf16x8 wf[4], af[4];
; #pragma unroll
;       for (int j = 0; j < 4; ++j) {
;         wf[j] = *(const bf16x8*)(sb + j * 2048 + foff[ks]);
;         af[j] = *(const bf16x8*)(sa + j * 2048 + foff[ks]);
;       }
; #pragma unroll
;       for (int ni = 0; ni < 4; ++ni)
; #pragma unroll
;         for (int mi = 0; mi < 4; ++mi) acc[ni][mi] = __builtin_amdgcn_mfma_f32_16x16x32_bf16(wf[ni], af[mi], acc[ni][mi], 0, 0, 0);
;     }
;     asm volatile("s_waitcnt vmcnt(0)" ::: "memory");
;     __syncthreads();
;     ...
;   const int nh = n0 + wn * 64;
;   if (epi.packed(nh)) {
; #pragma unroll
;     for (int mi = 0; mi < 4; ++mi) {
;       const int m = m0 + wm * 64 + mi * 16 + fr;
;       float ss = 0.f;
;       u32x2 pk[4];
; #pragma unroll
;       for (int ni = 0; ni < 4; ++ni) pk[ni] = epi.pack(m, nh + ni * 16 + fq * 4, acc[ni][mi][0], acc[ni][mi][1], acc[ni][mi][2], acc[ni][mi][3], ss);
;       epi.finish16(m, nh, ss);
;       u16* rp = epi.rowp(m) + nh;
; #pragma unroll
;       for (int pp = 0; pp < 2; ++pp) {
;         u32x2 a = pk[2 * pp], b = pk[2 * pp + 1];
;         const u32x2 rx = __builtin_amdgcn_permlane16_swap(a.x, b.x, false, false);
;         const u32x2 ry = __builtin_amdgcn_permlane16_swap(a.y, b.y, false, false);
;         const int nst = (fq & 1) ? ((2 * pp + 1) * 16 + (fq - 1) * 4) : ((2 * pp) * 16 + fq * 4);
;         *(u32x4*)(rp + nst) = (u32x4){rx[0], ry[0], rx[1], ry[1]};
;       }
	v_add_u32_e32 v91, v90, v88
	ds_read_b128 v[66:69], v91 offset:49152
	v_add_u32_e32 v88, v89, v88
	ds_read_b128 v[70:73], v88 offset:32768
	ds_read_b128 v[74:77], v88 offset:34816
	ds_read_b128 v[78:81], v88 offset:36864
	ds_read_b128 v[92:95], v88 offset:38912
	v_add_u32_e32 v116, v90, v87
	s_waitcnt lgkmcnt(3)
	v_mfma_f32_16x16x32_bf16 v[60:63], v[66:69], v[70:73], v[60:63]
	s_waitcnt lgkmcnt(2)
	v_mfma_f32_16x16x32_bf16 v[56:59], v[66:69], v[74:77], v[56:59]
	s_waitcnt lgkmcnt(1)
	v_mfma_f32_16x16x32_bf16 v[48:51], v[66:69], v[78:81], v[48:51]
	s_waitcnt lgkmcnt(0)
	v_mfma_f32_16x16x32_bf16 v[40:43], v[66:69], v[92:95], v[40:43]
	ds_read_b128 v[66:69], v91 offset:51200
	s_waitcnt lgkmcnt(0)
	v_mfma_f32_16x16x32_bf16 v[36:39], v[66:69], v[70:73], v[36:39]
	v_mfma_f32_16x16x32_bf16 v[32:35], v[66:69], v[74:77], v[32:35]
	v_mfma_f32_16x16x32_bf16 v[96:99], v[66:69], v[78:81], v[28:31]
	v_mfma_f32_16x16x32_bf16 v[66:69], v[66:69], v[92:95], v[24:27]
	s_nop 2
	ds_read_b128 v[24:27], v91 offset:53248
	s_waitcnt lgkmcnt(0)
	v_mfma_f32_16x16x32_bf16 v[104:107], v[24:27], v[92:95], v[8:11]
	s_nop 2
	ds_read_b128 v[8:11], v91 offset:55296
	v_mfma_f32_16x16x32_bf16 v[20:23], v[24:27], v[70:73], v[20:23]
	s_waitcnt lgkmcnt(0)
	v_mfma_f32_16x16x32_bf16 v[70:73], v[8:11], v[70:73], v[4:7]
	s_nop 2
	ds_read_b128 v[4:7], v116 offset:49152
	v_mfma_f32_16x16x32_bf16 v[100:103], v[24:27], v[78:81], v[12:15]
	s_nop 2
	v_add_u32_e32 v12, v89, v87
	v_mfma_f32_16x16x32_bf16 v[16:19], v[24:27], v[74:77], v[16:19]
	ds_read_b128 v[88:91], v12 offset:32768
	ds_read_b128 v[108:111], v12 offset:36864
	ds_read_b128 v[112:115], v12 offset:38912
	v_mfma_f32_16x16x32_bf16 v[0:3], v[8:11], v[74:77], v[0:3]
	v_mfma_f32_16x16x32_bf16 v[74:77], v[8:11], v[78:81], v[52:55]
	v_mfma_f32_16x16x32_bf16 v[78:81], v[8:11], v[92:95], v[44:47]
	ds_read_b128 v[92:95], v12 offset:34816
	s_waitcnt lgkmcnt(3)
	v_mfma_f32_16x16x32_bf16 v[60:63], v[4:7], v[88:91], v[60:63]
	s_waitcnt lgkmcnt(0)
	v_mfma_f32_16x16x32_bf16 v[44:47], v[4:7], v[92:95], v[56:59]
	v_mfma_f32_16x16x32_bf16 v[28:31], v[4:7], v[108:111], v[48:51]
	v_mfma_f32_16x16x32_bf16 v[12:15], v[4:7], v[112:115], v[40:43]
	ds_read_b128 v[4:7], v116 offset:51200
	s_waitcnt lgkmcnt(0)
	v_mfma_f32_16x16x32_bf16 v[56:59], v[4:7], v[88:91], v[36:39]
	v_mfma_f32_16x16x32_bf16 v[40:43], v[4:7], v[92:95], v[32:35]
	v_mfma_f32_16x16x32_bf16 v[24:27], v[4:7], v[108:111], v[96:99]
	v_mfma_f32_16x16x32_bf16 v[8:11], v[4:7], v[112:115], v[66:69]
	ds_read_b128 v[4:7], v116 offset:53248
	s_nop 0
	ds_read_b128 v[96:99], v116 offset:55296
	s_waitcnt vmcnt(0)
	s_waitcnt lgkmcnt(0)
	v_mfma_f32_16x16x32_bf16 v[32:35], v[96:99], v[92:95], v[0:3]
	s_nop 2
	v_or_b32_e32 v0, s0, v64
	v_lshl_add_u32 v66, v86, 6, v0
	v_lshl_or_b32 v68, v85, 6, s38
	v_mfma_f32_16x16x32_bf16 v[52:55], v[4:7], v[88:91], v[20:23]
	v_cmp_lt_i32_e32 vcc, s33, v68
	s_barrier
	v_mfma_f32_16x16x32_bf16 v[36:39], v[4:7], v[92:95], v[16:19]
	v_mfma_f32_16x16x32_bf16 v[20:23], v[4:7], v[108:111], v[100:103]
	v_mfma_f32_16x16x32_bf16 v[4:7], v[4:7], v[112:115], v[104:107]
	v_mfma_f32_16x16x32_bf16 v[48:51], v[96:99], v[88:91], v[70:73]
	v_mfma_f32_16x16x32_bf16 v[16:19], v[96:99], v[108:111], v[74:77]
	s_nop 1
	v_lshlrev_b32_e32 v72, 2, v84
	v_or_b32_e32 v64, v68, v72
	v_mfma_f32_16x16x32_bf16 v[0:3], v[96:99], v[112:115], v[78:81]
	s_nop 7
	v_readfirstlane_b32 s99, v68
	s_cmpk_ge_u32 s99, 0x800
	s_cbranch_scc0 .Lfe_B_not_plain
	s_cmpk_lt_u32 s99, 0xc00
	s_cbranch_scc0 .Lfe_B_not_plain
	s_load_dwordx2 s[100:101], s[56:57], 0x130
	v_and_b32_e32 v152, 1, v84
	v_mul_u32_u24_e32 v152, 12, v152
	v_lshl_add_u32 v152, v84, 2, v152
	v_add_u32_e32 v152, v152, v68
	v_lshl_add_u32 v152, v66, 12, v152
	v_lshlrev_b32_e32 v152, 1, v152
	v_add_u32_e32 v153, 0x20000, v152
	v_add_u32_e32 v154, 0x40000, v152
	v_add_u32_e32 v155, 0x60000, v152
	s_nop 3
	v_cvt_pk_bf16_f32 v120, v60, v61
	v_cvt_pk_bf16_f32 v121, v62, v63
	v_cvt_pk_bf16_f32 v122, v56, v57
	v_cvt_pk_bf16_f32 v123, v58, v59
	v_cvt_pk_bf16_f32 v124, v52, v53
	v_cvt_pk_bf16_f32 v125, v54, v55
	v_cvt_pk_bf16_f32 v126, v48, v49
	v_cvt_pk_bf16_f32 v127, v50, v51
	s_nop 1
	v_permlane16_swap_b32_e32 v120, v122
	v_permlane16_swap_b32_e32 v121, v123
	v_permlane16_swap_b32_e32 v124, v126
	v_permlane16_swap_b32_e32 v125, v127
	s_waitcnt lgkmcnt(0)
	global_store_dwordx4 v152, v[120:123], s[100:101]
	global_store_dwordx4 v152, v[124:127], s[100:101] offset:64
	v_cvt_pk_bf16_f32 v128, v44, v45
	v_cvt_pk_bf16_f32 v129, v46, v47
	v_cvt_pk_bf16_f32 v130, v40, v41
	v_cvt_pk_bf16_f32 v131, v42, v43
	v_cvt_pk_bf16_f32 v132, v36, v37
	v_cvt_pk_bf16_f32 v133, v38, v39
	v_cvt_pk_bf16_f32 v134, v32, v33
	v_cvt_pk_bf16_f32 v135, v34, v35
	s_nop 1
	v_permlane16_swap_b32_e32 v128, v130
	v_permlane16_swap_b32_e32 v129, v131
	v_permlane16_swap_b32_e32 v132, v134
	v_permlane16_swap_b32_e32 v133, v135
	global_store_dwordx4 v153, v[128:131], s[100:101]
	global_store_dwordx4 v153, v[132:135], s[100:101] offset:64
	v_cvt_pk_bf16_f32 v136, v28, v29
	v_cvt_pk_bf16_f32 v137, v30, v31
	v_cvt_pk_bf16_f32 v138, v24, v25
	v_cvt_pk_bf16_f32 v139, v26, v27
	v_cvt_pk_bf16_f32 v140, v20, v21
	v_cvt_pk_bf16_f32 v141, v22, v23
	v_cvt_pk_bf16_f32 v142, v16, v17
	v_cvt_pk_bf16_f32 v143, v18, v19
	s_nop 1
	v_permlane16_swap_b32_e32 v136, v138
	v_permlane16_swap_b32_e32 v137, v139
	v_permlane16_swap_b32_e32 v140, v142
	v_permlane16_swap_b32_e32 v141, v143
	global_store_dwordx4 v154, v[136:139], s[100:101]
	global_store_dwordx4 v154, v[140:143], s[100:101] offset:64
	v_cvt_pk_bf16_f32 v144, v12, v13
	v_cvt_pk_bf16_f32 v145, v14, v15
	v_cvt_pk_bf16_f32 v146, v8, v9
	v_cvt_pk_bf16_f32 v147, v10, v11
	v_cvt_pk_bf16_f32 v148, v4, v5
	v_cvt_pk_bf16_f32 v149, v6, v7
	v_cvt_pk_bf16_f32 v150, v0, v1
	v_cvt_pk_bf16_f32 v151, v2, v3
	s_nop 1
	v_permlane16_swap_b32_e32 v144, v146
	v_permlane16_swap_b32_e32 v145, v147
	v_permlane16_swap_b32_e32 v148, v150
	v_permlane16_swap_b32_e32 v149, v151
	global_store_dwordx4 v155, v[144:147], s[100:101]
	global_store_dwordx4 v155, v[148:151], s[100:101] offset:64
	s_branch .Lfe_join_B
; DI unsigned pack2(float a, float b) { v2f f = {a, b}; return __builtin_bit_cast(unsigned, __builtin_convertvector(f, v2bf)); }
; DI float silu_f(float v) { return v / (1.f + fexp(-v)); }
;   DI u32x2 pack(int, int, float a, float b, float c, float d, float&) const { u32x2 v; v.x = pack2(a, b); v.y = pack2(c, d); return v; }
; template <class ARow, class Epi>
; DI void gemm_tile(const ARow& arow, long a_kstride, const u16* __restrict__ Bt, long ldb, int K, int m0, int n0,
;                   const Epi& epi, char* smem) {
;     ...
;   const int nh = n0 + wn * 64;
;   if (epi.packed(nh)) {
; #pragma unroll
;     for (int mi = 0; mi < 4; ++mi) {
;       const int m = m0 + wm * 64 + mi * 16 + fr;
;       float ss = 0.f;
;       u32x2 pk[4];
; #pragma unroll
;       for (int ni = 0; ni < 4; ++ni) pk[ni] = epi.pack(m, nh + ni * 16 + fq * 4, acc[ni][mi][0], acc[ni][mi][1], acc[ni][mi][2], acc[ni][mi][3], ss);
;       epi.finish16(m, nh, ss);
;       u16* rp = epi.rowp(m) + nh;
; #pragma unroll
;       for (int pp = 0; pp < 2; ++pp) {
;         u32x2 a = pk[2 * pp], b = pk[2 * pp + 1];
;         const u32x2 rx = __builtin_amdgcn_permlane16_swap(a.x, b.x, false, false);
;         const u32x2 ry = __builtin_amdgcn_permlane16_swap(a.y, b.y, false, false);
;         const int nst = (fq & 1) ? ((2 * pp + 1) * 16 + (fq - 1) * 4) : ((2 * pp) * 16 + fq * 4);
;         *(u32x4*)(rp + nst) = (u32x4){rx[0], ry[0], rx[1], ry[1]};
;       }
;   DI u32x2 pack(int m, int n, float a, float b, float c, float d, float& ss) const {
;     if (n < q_end) { a *= qscale; b *= qscale; c *= qscale; d *= qscale; }
;     else if (n >= z_start) { a = silu_f(a); b = silu_f(b); c = silu_f(c); d = silu_f(d); }
;     ss += a * a + b * b + c * c + d * d;
;     u32x2 v; v.x = pack2(a, b); v.y = pack2(c, d);
;     return v;
;   }
.Lfe_B_not_plain:
	s_cmpk_lt_u32 s99, 0x400
	s_cbranch_scc0 .Lfe_B_not_q
	s_load_dwordx2 s[100:101], s[56:57], 0x130
	v_and_b32_e32 v152, 1, v84
	v_mul_u32_u24_e32 v152, 12, v152
	v_lshl_add_u32 v152, v84, 2, v152
	v_add_u32_e32 v152, v152, v68
	v_lshl_add_u32 v152, v66, 12, v152
	v_lshlrev_b32_e32 v152, 1, v152
	v_add_u32_e32 v153, 0x20000, v152
	v_add_u32_e32 v154, 0x40000, v152
	v_add_u32_e32 v155, 0x60000, v152
	s_mov_b32 s98, 0x3e38aa3b
	s_nop 3
	v_pk_mul_f32 v[60:61], v[60:61], s[98:99] op_sel_hi:[1,0]
	v_pk_mul_f32 v[62:63], v[62:63], s[98:99] op_sel_hi:[1,0]
	v_pk_mul_f32 v[56:57], v[56:57], s[98:99] op_sel_hi:[1,0]
	v_pk_mul_f32 v[58:59], v[58:59], s[98:99] op_sel_hi:[1,0]
	v_pk_mul_f32 v[52:53], v[52:53], s[98:99] op_sel_hi:[1,0]
	v_pk_mul_f32 v[54:55], v[54:55], s[98:99] op_sel_hi:[1,0]
	v_pk_mul_f32 v[48:49], v[48:49], s[98:99] op_sel_hi:[1,0]
	v_pk_mul_f32 v[50:51], v[50:51], s[98:99] op_sel_hi:[1,0]
	v_cvt_pk_bf16_f32 v120, v60, v61
	v_cvt_pk_bf16_f32 v121, v62, v63
	v_cvt_pk_bf16_f32 v122, v56, v57
	v_cvt_pk_bf16_f32 v123, v58, v59
	v_cvt_pk_bf16_f32 v124, v52, v53
	v_cvt_pk_bf16_f32 v125, v54, v55
	v_cvt_pk_bf16_f32 v126, v48, v49
	v_cvt_pk_bf16_f32 v127, v50, v51
	s_nop 1
	v_permlane16_swap_b32_e32 v120, v122
	v_permlane16_swap_b32_e32 v121, v123
	v_permlane16_swap_b32_e32 v124, v126
	v_permlane16_swap_b32_e32 v125, v127
	s_waitcnt lgkmcnt(0)
	global_store_dwordx4 v152, v[120:123], s[100:101]
	global_store_dwordx4 v152, v[124:127], s[100:101] offset:64
	v_pk_mul_f32 v[44:45], v[44:45], s[98:99] op_sel_hi:[1,0]
	v_pk_mul_f32 v[46:47], v[46:47], s[98:99] op_sel_hi:[1,0]
	v_pk_mul_f32 v[40:41], v[40:41], s[98:99] op_sel_hi:[1,0]
	v_pk_mul_f32 v[42:43], v[42:43], s[98:99] op_sel_hi:[1,0]
	v_pk_mul_f32 v[36:37], v[36:37], s[98:99] op_sel_hi:[1,0]
	v_pk_mul_f32 v[38:39], v[38:39], s[98:99] op_sel_hi:[1,0]
	v_pk_mul_f32 v[32:33], v[32:33], s[98:99] op_sel_hi:[1,0]
	v_pk_mul_f32 v[34:35], v[34:35], s[98:99] op_sel_hi:[1,0]
	v_cvt_pk_bf16_f32 v128, v44, v45
	v_cvt_pk_bf16_f32 v129, v46, v47
	v_cvt_pk_bf16_f32 v130, v40, v41
	v_cvt_pk_bf16_f32 v131, v42, v43
	v_cvt_pk_bf16_f32 v132, v36, v37
	v_cvt_pk_bf16_f32 v133, v38, v39
	v_cvt_pk_bf16_f32 v134, v32, v33
	v_cvt_pk_bf16_f32 v135, v34, v35
	s_nop 1
	v_permlane16_swap_b32_e32 v128, v130
	v_permlane16_swap_b32_e32 v129, v131
	v_permlane16_swap_b32_e32 v132, v134
	v_permlane16_swap_b32_e32 v133, v135
	global_store_dwordx4 v153, v[128:131], s[100:101]
	global_store_dwordx4 v153, v[132:135], s[100:101] offset:64
	v_pk_mul_f32 v[28:29], v[28:29], s[98:99] op_sel_hi:[1,0]
	v_pk_mul_f32 v[30:31], v[30:31], s[98:99] op_sel_hi:[1,0]
	v_pk_mul_f32 v[24:25], v[24:25], s[98:99] op_sel_hi:[1,0]
	v_pk_mul_f32 v[26:27], v[26:27], s[98:99] op_sel_hi:[1,0]
	v_pk_mul_f32 v[20:21], v[20:21], s[98:99] op_sel_hi:[1,0]
	v_pk_mul_f32 v[22:23], v[22:23], s[98:99] op_sel_hi:[1,0]
	v_pk_mul_f32 v[16:17], v[16:17], s[98:99] op_sel_hi:[1,0]
	v_pk_mul_f32 v[18:19], v[18:19], s[98:99] op_sel_hi:[1,0]
	v_cvt_pk_bf16_f32 v136, v28, v29
	v_cvt_pk_bf16_f32 v137, v30, v31
	v_cvt_pk_bf16_f32 v138, v24, v25
	v_cvt_pk_bf16_f32 v139, v26, v27
	v_cvt_pk_bf16_f32 v140, v20, v21
	v_cvt_pk_bf16_f32 v141, v22, v23
	v_cvt_pk_bf16_f32 v142, v16, v17
	v_cvt_pk_bf16_f32 v143, v18, v19
	s_nop 1
	v_permlane16_swap_b32_e32 v136, v138
	v_permlane16_swap_b32_e32 v137, v139
	v_permlane16_swap_b32_e32 v140, v142
	v_permlane16_swap_b32_e32 v141, v143
	global_store_dwordx4 v154, v[136:139], s[100:101]
	global_store_dwordx4 v154, v[140:143], s[100:101] offset:64
	v_pk_mul_f32 v[12:13], v[12:13], s[98:99] op_sel_hi:[1,0]
	v_pk_mul_f32 v[14:15], v[14:15], s[98:99] op_sel_hi:[1,0]
	v_pk_mul_f32 v[8:9], v[8:9], s[98:99] op_sel_hi:[1,0]
	v_pk_mul_f32 v[10:11], v[10:11], s[98:99] op_sel_hi:[1,0]
	v_pk_mul_f32 v[4:5], v[4:5], s[98:99] op_sel_hi:[1,0]
	v_pk_mul_f32 v[6:7], v[6:7], s[98:99] op_sel_hi:[1,0]
	v_pk_mul_f32 v[0:1], v[0:1], s[98:99] op_sel_hi:[1,0]
	v_pk_mul_f32 v[2:3], v[2:3], s[98:99] op_sel_hi:[1,0]
	v_cvt_pk_bf16_f32 v144, v12, v13
	v_cvt_pk_bf16_f32 v145, v14, v15
	v_cvt_pk_bf16_f32 v146, v8, v9
	v_cvt_pk_bf16_f32 v147, v10, v11
	v_cvt_pk_bf16_f32 v148, v4, v5
	v_cvt_pk_bf16_f32 v149, v6, v7
	v_cvt_pk_bf16_f32 v150, v0, v1
	v_cvt_pk_bf16_f32 v151, v2, v3
	s_nop 1
	v_permlane16_swap_b32_e32 v144, v146
	v_permlane16_swap_b32_e32 v145, v147
	v_permlane16_swap_b32_e32 v148, v150
	v_permlane16_swap_b32_e32 v149, v151
	global_store_dwordx4 v155, v[144:147], s[100:101]
	global_store_dwordx4 v155, v[148:151], s[100:101] offset:64
	s_branch .Lfe_join_B
; DI unsigned pack2(float a, float b) { v2f f = {a, b}; return __builtin_bit_cast(unsigned, __builtin_convertvector(f, v2bf)); }
;   DI u32x2 pack(int, int, float a, float b, float c, float d, float&) const { u32x2 v; v.x = pack2(a, b); v.y = pack2(c, d); return v; }
; DI float fexp(float x) { return __builtin_amdgcn_exp2f(x * LOG2E); }
; DI float flog(float x) { return __builtin_amdgcn_logf(x) * 0.6931471805599453f; }
; DI float silu_f(float v) { return v / (1.f + fexp(-v)); }
; template <class ARow, class Epi>
; DI void gemm_tile(const ARow& arow, long a_kstride, const u16* __restrict__ Bt, long ldb, int K, int m0, int n0,
;                   const Epi& epi, char* smem) {
;     ...
;   const int nh = n0 + wn * 64;
;   if (epi.packed(nh)) {
; #pragma unroll
;     for (int mi = 0; mi < 4; ++mi) {
;       const int m = m0 + wm * 64 + mi * 16 + fr;
;       float ss = 0.f;
;       u32x2 pk[4];
; #pragma unroll
;       for (int ni = 0; ni < 4; ++ni) pk[ni] = epi.pack(m, nh + ni * 16 + fq * 4, acc[ni][mi][0], acc[ni][mi][1], acc[ni][mi][2], acc[ni][mi][3], ss);
;       epi.finish16(m, nh, ss);
;       u16* rp = epi.rowp(m) + nh;
; #pragma unroll
;       for (int pp = 0; pp < 2; ++pp) {
;         u32x2 a = pk[2 * pp], b = pk[2 * pp + 1];
;         const u32x2 rx = __builtin_amdgcn_permlane16_swap(a.x, b.x, false, false);
;         const u32x2 ry = __builtin_amdgcn_permlane16_swap(a.y, b.y, false, false);
;         const int nst = (fq & 1) ? ((2 * pp + 1) * 16 + (fq - 1) * 4) : ((2 * pp) * 16 + fq * 4);
;         *(u32x4*)(rp + nst) = (u32x4){rx[0], ry[0], rx[1], ry[1]};
;       }
;   DI u32x2 pack(int m, int n, float a, float b, float c, float d, float& ss) const {
;     if (n < q_end) { a *= qscale; b *= qscale; c *= qscale; d *= qscale; }
;     else if (n >= z_start) { a = silu_f(a); b = silu_f(b); c = silu_f(c); d = silu_f(d); }
;     ss += a * a + b * b + c * c + d * d;
;     u32x2 v; v.x = pack2(a, b); v.y = pack2(c, d);
;     return v;
;   }
.Lfe_B_not_q:
	s_cmpk_ge_u32 s99, 0xc00
	s_cbranch_scc0 .Lfe_B_not_z
	s_cmpk_lt_u32 s99, 0x1000
	s_cbranch_scc0 .Lfe_B_not_z
	s_load_dwordx2 s[100:101], s[56:57], 0x130
	v_and_b32_e32 v152, 1, v84
	v_mul_u32_u24_e32 v152, 12, v152
	v_lshl_add_u32 v152, v84, 2, v152
	v_add_u32_e32 v152, v152, v68
	v_lshl_add_u32 v152, v66, 12, v152
	v_lshlrev_b32_e32 v152, 1, v152
	v_add_u32_e32 v153, 0x20000, v152
	v_add_u32_e32 v154, 0x40000, v152
	v_add_u32_e32 v155, 0x60000, v152
	s_nop 3
	v_mul_f32_e32 v156, 0xbfb8aa3b, v60
	v_mul_f32_e32 v157, 0xbfb8aa3b, v61
	v_mul_f32_e32 v158, 0xbfb8aa3b, v62
	v_mul_f32_e32 v159, 0xbfb8aa3b, v63
	v_mul_f32_e32 v160, 0xbfb8aa3b, v56
	v_mul_f32_e32 v161, 0xbfb8aa3b, v57
	v_mul_f32_e32 v162, 0xbfb8aa3b, v58
	v_mul_f32_e32 v163, 0xbfb8aa3b, v59
	v_exp_f32_e32 v156, v156
	v_exp_f32_e32 v157, v157
	v_exp_f32_e32 v158, v158
	v_exp_f32_e32 v159, v159
	v_exp_f32_e32 v160, v160
	v_exp_f32_e32 v161, v161
	v_exp_f32_e32 v162, v162
	v_exp_f32_e32 v163, v163
	v_add_f32_e32 v156, 1.0, v156
	v_add_f32_e32 v157, 1.0, v157
	v_add_f32_e32 v158, 1.0, v158
	v_add_f32_e32 v159, 1.0, v159
	v_add_f32_e32 v160, 1.0, v160
	v_add_f32_e32 v161, 1.0, v161
	v_add_f32_e32 v162, 1.0, v162
	v_add_f32_e32 v163, 1.0, v163
	v_rcp_f32_e32 v156, v156
	v_rcp_f32_e32 v157, v157
	v_rcp_f32_e32 v158, v158
	v_rcp_f32_e32 v159, v159
	v_rcp_f32_e32 v160, v160
	v_rcp_f32_e32 v161, v161
	v_rcp_f32_e32 v162, v162
	v_rcp_f32_e32 v163, v163
	v_mul_f32_e32 v60, v60, v156
	v_mul_f32_e32 v61, v61, v157
	v_mul_f32_e32 v62, v62, v158
	v_mul_f32_e32 v63, v63, v159
	v_mul_f32_e32 v56, v56, v160
	v_mul_f32_e32 v57, v57, v161
	v_mul_f32_e32 v58, v58, v162
	v_mul_f32_e32 v59, v59, v163
	v_mul_f32_e32 v156, 0xbfb8aa3b, v52
	v_mul_f32_e32 v157, 0xbfb8aa3b, v53
	v_mul_f32_e32 v158, 0xbfb8aa3b, v54
	v_mul_f32_e32 v159, 0xbfb8aa3b, v55
	v_mul_f32_e32 v160, 0xbfb8aa3b, v48
	v_mul_f32_e32 v161, 0xbfb8aa3b, v49
	v_mul_f32_e32 v162, 0xbfb8aa3b, v50
	v_mul_f32_e32 v163, 0xbfb8aa3b, v51
	v_exp_f32_e32 v156, v156
	v_exp_f32_e32 v157, v157
	v_exp_f32_e32 v158, v158
	v_exp_f32_e32 v159, v159
	v_exp_f32_e32 v160, v160
	v_exp_f32_e32 v161, v161
	v_exp_f32_e32 v162, v162
	v_exp_f32_e32 v163, v163
	v_add_f32_e32 v156, 1.0, v156
	v_add_f32_e32 v157, 1.0, v157
	v_add_f32_e32 v158, 1.0, v158
	v_add_f32_e32 v159, 1.0, v159
	v_add_f32_e32 v160, 1.0, v160
	v_add_f32_e32 v161, 1.0, v161
	v_add_f32_e32 v162, 1.0, v162
	v_add_f32_e32 v163, 1.0, v163
	v_rcp_f32_e32 v156, v156
	v_rcp_f32_e32 v157, v157
	v_rcp_f32_e32 v158, v158
	v_rcp_f32_e32 v159, v159
	v_rcp_f32_e32 v160, v160
	v_rcp_f32_e32 v161, v161
	v_rcp_f32_e32 v162, v162
	v_rcp_f32_e32 v163, v163
	v_mul_f32_e32 v52, v52, v156
	v_mul_f32_e32 v53, v53, v157
	v_mul_f32_e32 v54, v54, v158
	v_mul_f32_e32 v55, v55, v159
	v_mul_f32_e32 v48, v48, v160
	v_mul_f32_e32 v49, v49, v161
	v_mul_f32_e32 v50, v50, v162
	v_mul_f32_e32 v51, v51, v163
	v_cvt_pk_bf16_f32 v120, v60, v61
	v_cvt_pk_bf16_f32 v121, v62, v63
	v_cvt_pk_bf16_f32 v122, v56, v57
	v_cvt_pk_bf16_f32 v123, v58, v59
	v_cvt_pk_bf16_f32 v124, v52, v53
	v_cvt_pk_bf16_f32 v125, v54, v55
	v_cvt_pk_bf16_f32 v126, v48, v49
	v_cvt_pk_bf16_f32 v127, v50, v51
	s_nop 1
	v_permlane16_swap_b32_e32 v120, v122
	v_permlane16_swap_b32_e32 v121, v123
	v_permlane16_swap_b32_e32 v124, v126
	v_permlane16_swap_b32_e32 v125, v127
	s_waitcnt lgkmcnt(0)
	global_store_dwordx4 v152, v[120:123], s[100:101]
	global_store_dwordx4 v152, v[124:127], s[100:101] offset:64
	v_mul_f32_e32 v156, 0xbfb8aa3b, v44
	v_mul_f32_e32 v157, 0xbfb8aa3b, v45
	v_mul_f32_e32 v158, 0xbfb8aa3b, v46
	v_mul_f32_e32 v159, 0xbfb8aa3b, v47
	v_mul_f32_e32 v160, 0xbfb8aa3b, v40
	v_mul_f32_e32 v161, 0xbfb8aa3b, v41
	v_mul_f32_e32 v162, 0xbfb8aa3b, v42
	v_mul_f32_e32 v163, 0xbfb8aa3b, v43
	v_exp_f32_e32 v156, v156
	v_exp_f32_e32 v157, v157
	v_exp_f32_e32 v158, v158
	v_exp_f32_e32 v159, v159
	v_exp_f32_e32 v160, v160
	v_exp_f32_e32 v161, v161
	v_exp_f32_e32 v162, v162
	v_exp_f32_e32 v163, v163
	v_add_f32_e32 v156, 1.0, v156
	v_add_f32_e32 v157, 1.0, v157
	v_add_f32_e32 v158, 1.0, v158
	v_add_f32_e32 v159, 1.0, v159
	v_add_f32_e32 v160, 1.0, v160
	v_add_f32_e32 v161, 1.0, v161
	v_add_f32_e32 v162, 1.0, v162
	v_add_f32_e32 v163, 1.0, v163
	v_rcp_f32_e32 v156, v156
	v_rcp_f32_e32 v157, v157
	v_rcp_f32_e32 v158, v158
	v_rcp_f32_e32 v159, v159
	v_rcp_f32_e32 v160, v160
	v_rcp_f32_e32 v161, v161
	v_rcp_f32_e32 v162, v162
	v_rcp_f32_e32 v163, v163
	v_mul_f32_e32 v44, v44, v156
	v_mul_f32_e32 v45, v45, v157
	v_mul_f32_e32 v46, v46, v158
	v_mul_f32_e32 v47, v47, v159
	v_mul_f32_e32 v40, v40, v160
	v_mul_f32_e32 v41, v41, v161
	v_mul_f32_e32 v42, v42, v162
	v_mul_f32_e32 v43, v43, v163
	v_mul_f32_e32 v156, 0xbfb8aa3b, v36
	v_mul_f32_e32 v157, 0xbfb8aa3b, v37
	v_mul_f32_e32 v158, 0xbfb8aa3b, v38
	v_mul_f32_e32 v159, 0xbfb8aa3b, v39
	v_mul_f32_e32 v160, 0xbfb8aa3b, v32
	v_mul_f32_e32 v161, 0xbfb8aa3b, v33
	v_mul_f32_e32 v162, 0xbfb8aa3b, v34
	v_mul_f32_e32 v163, 0xbfb8aa3b, v35
	v_exp_f32_e32 v156, v156
	v_exp_f32_e32 v157, v157
	v_exp_f32_e32 v158, v158
	v_exp_f32_e32 v159, v159
	v_exp_f32_e32 v160, v160
	v_exp_f32_e32 v161, v161
	v_exp_f32_e32 v162, v162
	v_exp_f32_e32 v163, v163
	v_add_f32_e32 v156, 1.0, v156
	v_add_f32_e32 v157, 1.0, v157
	v_add_f32_e32 v158, 1.0, v158
	v_add_f32_e32 v159, 1.0, v159
	v_add_f32_e32 v160, 1.0, v160
	v_add_f32_e32 v161, 1.0, v161
	v_add_f32_e32 v162, 1.0, v162
	v_add_f32_e32 v163, 1.0, v163
	v_rcp_f32_e32 v156, v156
	v_rcp_f32_e32 v157, v157
	v_rcp_f32_e32 v158, v158
	v_rcp_f32_e32 v159, v159
	v_rcp_f32_e32 v160, v160
	v_rcp_f32_e32 v161, v161
	v_rcp_f32_e32 v162, v162
	v_rcp_f32_e32 v163, v163
	v_mul_f32_e32 v36, v36, v156
; DI unsigned pack2(float a, float b) { v2f f = {a, b}; return __builtin_bit_cast(unsigned, __builtin_convertvector(f, v2bf)); }
; DI float silu_f(float v) { return v / (1.f + fexp(-v)); }
;   DI u32x2 pack(int, int, float a, float b, float c, float d, float&) const { u32x2 v; v.x = pack2(a, b); v.y = pack2(c, d); return v; }
; template <class ARow, class Epi>
; DI void gemm_tile(const ARow& arow, long a_kstride, const u16* __restrict__ Bt, long ldb, int K, int m0, int n0,
;                   const Epi& epi, char* smem) {
;     ...
;       for (int ni = 0; ni < 4; ++ni) pk[ni] = epi.pack(m, nh + ni * 16 + fq * 4, acc[ni][mi][0], acc[ni][mi][1], acc[ni][mi][2], acc[ni][mi][3], ss);
;       epi.finish16(m, nh, ss);
;       u16* rp = epi.rowp(m) + nh;
; #pragma unroll
;       for (int pp = 0; pp < 2; ++pp) {
;         u32x2 a = pk[2 * pp], b = pk[2 * pp + 1];
;         const u32x2 rx = __builtin_amdgcn_permlane16_swap(a.x, b.x, false, false);
;         const u32x2 ry = __builtin_amdgcn_permlane16_swap(a.y, b.y, false, false);
;         const int nst = (fq & 1) ? ((2 * pp + 1) * 16 + (fq - 1) * 4) : ((2 * pp) * 16 + fq * 4);
;         *(u32x4*)(rp + nst) = (u32x4){rx[0], ry[0], rx[1], ry[1]};
;       }
;   DI u32x2 pack(int m, int n, float a, float b, float c, float d, float& ss) const {
;     if (n < q_end) { a *= qscale; b *= qscale; c *= qscale; d *= qscale; }
;     else if (n >= z_start) { a = silu_f(a); b = silu_f(b); c = silu_f(c); d = silu_f(d); }
;     ss += a * a + b * b + c * c + d * d;
;     u32x2 v; v.x = pack2(a, b); v.y = pack2(c, d);
;     return v;
	v_mul_f32_e32 v37, v37, v157
	v_mul_f32_e32 v38, v38, v158
	v_mul_f32_e32 v39, v39, v159
	v_mul_f32_e32 v32, v32, v160
	v_mul_f32_e32 v33, v33, v161
	v_mul_f32_e32 v34, v34, v162
	v_mul_f32_e32 v35, v35, v163
	v_cvt_pk_bf16_f32 v128, v44, v45
	v_cvt_pk_bf16_f32 v129, v46, v47
	v_cvt_pk_bf16_f32 v130, v40, v41
	v_cvt_pk_bf16_f32 v131, v42, v43
	v_cvt_pk_bf16_f32 v132, v36, v37
	v_cvt_pk_bf16_f32 v133, v38, v39
	v_cvt_pk_bf16_f32 v134, v32, v33
	v_cvt_pk_bf16_f32 v135, v34, v35
	s_nop 1
	v_permlane16_swap_b32_e32 v128, v130
	v_permlane16_swap_b32_e32 v129, v131
	v_permlane16_swap_b32_e32 v132, v134
	v_permlane16_swap_b32_e32 v133, v135
	global_store_dwordx4 v153, v[128:131], s[100:101]
	global_store_dwordx4 v153, v[132:135], s[100:101] offset:64
	v_mul_f32_e32 v156, 0xbfb8aa3b, v28
	v_mul_f32_e32 v157, 0xbfb8aa3b, v29
	v_mul_f32_e32 v158, 0xbfb8aa3b, v30
	v_mul_f32_e32 v159, 0xbfb8aa3b, v31
	v_mul_f32_e32 v160, 0xbfb8aa3b, v24
	v_mul_f32_e32 v161, 0xbfb8aa3b, v25
	v_mul_f32_e32 v162, 0xbfb8aa3b, v26
	v_mul_f32_e32 v163, 0xbfb8aa3b, v27
	v_exp_f32_e32 v156, v156
	v_exp_f32_e32 v157, v157
	v_exp_f32_e32 v158, v158
	v_exp_f32_e32 v159, v159
	v_exp_f32_e32 v160, v160
	v_exp_f32_e32 v161, v161
	v_exp_f32_e32 v162, v162
	v_exp_f32_e32 v163, v163
	v_add_f32_e32 v156, 1.0, v156
	v_add_f32_e32 v157, 1.0, v157
	v_add_f32_e32 v158, 1.0, v158
	v_add_f32_e32 v159, 1.0, v159
	v_add_f32_e32 v160, 1.0, v160
	v_add_f32_e32 v161, 1.0, v161
	v_add_f32_e32 v162, 1.0, v162
	v_add_f32_e32 v163, 1.0, v163
	v_rcp_f32_e32 v156, v156
	v_rcp_f32_e32 v157, v157
	v_rcp_f32_e32 v158, v158
	v_rcp_f32_e32 v159, v159
	v_rcp_f32_e32 v160, v160
	v_rcp_f32_e32 v161, v161
	v_rcp_f32_e32 v162, v162
	v_rcp_f32_e32 v163, v163
	v_mul_f32_e32 v28, v28, v156
	v_mul_f32_e32 v29, v29, v157
	v_mul_f32_e32 v30, v30, v158
	v_mul_f32_e32 v31, v31, v159
	v_mul_f32_e32 v24, v24, v160
	v_mul_f32_e32 v25, v25, v161
	v_mul_f32_e32 v26, v26, v162
	v_mul_f32_e32 v27, v27, v163
	v_mul_f32_e32 v156, 0xbfb8aa3b, v20
	v_mul_f32_e32 v157, 0xbfb8aa3b, v21
	v_mul_f32_e32 v158, 0xbfb8aa3b, v22
	v_mul_f32_e32 v159, 0xbfb8aa3b, v23
	v_mul_f32_e32 v160, 0xbfb8aa3b, v16
	v_mul_f32_e32 v161, 0xbfb8aa3b, v17
	v_mul_f32_e32 v162, 0xbfb8aa3b, v18
	v_mul_f32_e32 v163, 0xbfb8aa3b, v19
	v_exp_f32_e32 v156, v156
	v_exp_f32_e32 v157, v157
	v_exp_f32_e32 v158, v158
	v_exp_f32_e32 v159, v159
	v_exp_f32_e32 v160, v160
	v_exp_f32_e32 v161, v161
	v_exp_f32_e32 v162, v162
	v_exp_f32_e32 v163, v163
	v_add_f32_e32 v156, 1.0, v156
	v_add_f32_e32 v157, 1.0, v157
	v_add_f32_e32 v158, 1.0, v158
	v_add_f32_e32 v159, 1.0, v159
	v_add_f32_e32 v160, 1.0, v160
	v_add_f32_e32 v161, 1.0, v161
	v_add_f32_e32 v162, 1.0, v162
	v_add_f32_e32 v163, 1.0, v163
	v_rcp_f32_e32 v156, v156
	v_rcp_f32_e32 v157, v157
	v_rcp_f32_e32 v158, v158
	v_rcp_f32_e32 v159, v159
	v_rcp_f32_e32 v160, v160
	v_rcp_f32_e32 v161, v161
	v_rcp_f32_e32 v162, v162
	v_rcp_f32_e32 v163, v163
	v_mul_f32_e32 v20, v20, v156
	v_mul_f32_e32 v21, v21, v157
	v_mul_f32_e32 v22, v22, v158
	v_mul_f32_e32 v23, v23, v159
	v_mul_f32_e32 v16, v16, v160
	v_mul_f32_e32 v17, v17, v161
	v_mul_f32_e32 v18, v18, v162
	v_mul_f32_e32 v19, v19, v163
	v_cvt_pk_bf16_f32 v136, v28, v29
	v_cvt_pk_bf16_f32 v137, v30, v31
	v_cvt_pk_bf16_f32 v138, v24, v25
	v_cvt_pk_bf16_f32 v139, v26, v27
	v_cvt_pk_bf16_f32 v140, v20, v21
	v_cvt_pk_bf16_f32 v141, v22, v23
	v_cvt_pk_bf16_f32 v142, v16, v17
	v_cvt_pk_bf16_f32 v143, v18, v19
	s_nop 1
	v_permlane16_swap_b32_e32 v136, v138
	v_permlane16_swap_b32_e32 v137, v139
	v_permlane16_swap_b32_e32 v140, v142
	v_permlane16_swap_b32_e32 v141, v143
	global_store_dwordx4 v154, v[136:139], s[100:101]
	global_store_dwordx4 v154, v[140:143], s[100:101] offset:64
	v_mul_f32_e32 v156, 0xbfb8aa3b, v12
	v_mul_f32_e32 v157, 0xbfb8aa3b, v13
	v_mul_f32_e32 v158, 0xbfb8aa3b, v14
	v_mul_f32_e32 v159, 0xbfb8aa3b, v15
	v_mul_f32_e32 v160, 0xbfb8aa3b, v8
	v_mul_f32_e32 v161, 0xbfb8aa3b, v9
	v_mul_f32_e32 v162, 0xbfb8aa3b, v10
	v_mul_f32_e32 v163, 0xbfb8aa3b, v11
	v_exp_f32_e32 v156, v156
	v_exp_f32_e32 v157, v157
	v_exp_f32_e32 v158, v158
	v_exp_f32_e32 v159, v159
	v_exp_f32_e32 v160, v160
	v_exp_f32_e32 v161, v161
	v_exp_f32_e32 v162, v162
	v_exp_f32_e32 v163, v163
	v_add_f32_e32 v156, 1.0, v156
	v_add_f32_e32 v157, 1.0, v157
	v_add_f32_e32 v158, 1.0, v158
	v_add_f32_e32 v159, 1.0, v159
	v_add_f32_e32 v160, 1.0, v160
	v_add_f32_e32 v161, 1.0, v161
	v_add_f32_e32 v162, 1.0, v162
	v_add_f32_e32 v163, 1.0, v163
	v_rcp_f32_e32 v156, v156
	v_rcp_f32_e32 v157, v157
	v_rcp_f32_e32 v158, v158
	v_rcp_f32_e32 v159, v159
	v_rcp_f32_e32 v160, v160
	v_rcp_f32_e32 v161, v161
	v_rcp_f32_e32 v162, v162
	v_rcp_f32_e32 v163, v163
	v_mul_f32_e32 v12, v12, v156
	v_mul_f32_e32 v13, v13, v157
	v_mul_f32_e32 v14, v14, v158
	v_mul_f32_e32 v15, v15, v159
	v_mul_f32_e32 v8, v8, v160
	v_mul_f32_e32 v9, v9, v161
	v_mul_f32_e32 v10, v10, v162
	v_mul_f32_e32 v11, v11, v163
	v_mul_f32_e32 v156, 0xbfb8aa3b, v4
	v_mul_f32_e32 v157, 0xbfb8aa3b, v5
	v_mul_f32_e32 v158, 0xbfb8aa3b, v6
	v_mul_f32_e32 v159, 0xbfb8aa3b, v7
	v_mul_f32_e32 v160, 0xbfb8aa3b, v0
	v_mul_f32_e32 v161, 0xbfb8aa3b, v1
	v_mul_f32_e32 v162, 0xbfb8aa3b, v2
	v_mul_f32_e32 v163, 0xbfb8aa3b, v3
	v_exp_f32_e32 v156, v156
	v_exp_f32_e32 v157, v157
	v_exp_f32_e32 v158, v158
	v_exp_f32_e32 v159, v159
	v_exp_f32_e32 v160, v160
	v_exp_f32_e32 v161, v161
	v_exp_f32_e32 v162, v162
	v_exp_f32_e32 v163, v163
	v_add_f32_e32 v156, 1.0, v156
	v_add_f32_e32 v157, 1.0, v157
	v_add_f32_e32 v158, 1.0, v158
	v_add_f32_e32 v159, 1.0, v159
	v_add_f32_e32 v160, 1.0, v160
	v_add_f32_e32 v161, 1.0, v161
	v_add_f32_e32 v162, 1.0, v162
	v_add_f32_e32 v163, 1.0, v163
	v_rcp_f32_e32 v156, v156
	v_rcp_f32_e32 v157, v157
	v_rcp_f32_e32 v158, v158
	v_rcp_f32_e32 v159, v159
	v_rcp_f32_e32 v160, v160
	v_rcp_f32_e32 v161, v161
	v_rcp_f32_e32 v162, v162
	v_rcp_f32_e32 v163, v163
	v_mul_f32_e32 v4, v4, v156
	v_mul_f32_e32 v5, v5, v157
	v_mul_f32_e32 v6, v6, v158
	v_mul_f32_e32 v7, v7, v159
	v_mul_f32_e32 v0, v0, v160
	v_mul_f32_e32 v1, v1, v161
	v_mul_f32_e32 v2, v2, v162
	v_mul_f32_e32 v3, v3, v163
	v_cvt_pk_bf16_f32 v144, v12, v13
	v_cvt_pk_bf16_f32 v145, v14, v15
	v_cvt_pk_bf16_f32 v146, v8, v9
	v_cvt_pk_bf16_f32 v147, v10, v11
	v_cvt_pk_bf16_f32 v148, v4, v5
	v_cvt_pk_bf16_f32 v149, v6, v7
	v_cvt_pk_bf16_f32 v150, v0, v1
	v_cvt_pk_bf16_f32 v151, v2, v3
	s_nop 1
	v_permlane16_swap_b32_e32 v144, v146
	v_permlane16_swap_b32_e32 v145, v147
	v_permlane16_swap_b32_e32 v148, v150
	v_permlane16_swap_b32_e32 v149, v151
	global_store_dwordx4 v155, v[144:147], s[100:101]
	global_store_dwordx4 v155, v[148:151], s[100:101] offset:64
	s_branch .Lfe_join_B
; DI unsigned pack2(float a, float b) { v2f f = {a, b}; return __builtin_bit_cast(unsigned, __builtin_convertvector(f, v2bf)); }
; DI float silu_f(float v) { return v / (1.f + fexp(-v)); }
; DI float sigmoid_f(float v) { return 1.f / (1.f + fexp(-v)); }
;   DI void operator()(int m, int n, float a, float b, float c, float d, float& ss) const { u32x2 v; v.x = pack2(a, b); v.y = pack2(c, d); *(u32x2*)(y + (long)m * 1024 + n) = v; }
;   DI void operator()(int m, int n, float a, float b, float c, float d, float& ss) const {
;     if (n >= gl_start) {
;       const int j = n - gl_start;
;       if (j < 48) { float* g = gates + (long)m * 48 + j; g[0] = sigmoid_f(a); g[1] = sigmoid_f(b); g[2] = sigmoid_f(c); g[3] = sigmoid_f(d); }
;       return;
;     }
;     if (n < q_end) { a *= qscale; b *= qscale; c *= qscale; d *= qscale; }
;     else if (n >= z_start) { a = silu_f(a); b = silu_f(b); c = silu_f(c); d = silu_f(d); }
;     ss += a * a + b * b + c * c + d * d;
;     u32x2 v; v.x = pack2(a, b); v.y = pack2(c, d);
;     *(u32x2*)(dst + (long)m * ld + n) = v;
.Lfe_B_not_z:
	s_and_saveexec_b64 s[0:1], vcc
	s_xor_b64 s[12:13], exec, s[0:1]
	s_cbranch_execz .LBB0_1320
	v_mad_i64_i32 v[70:71], s[0:1], v66, s36, 0
	v_cmp_lt_i32_e64 s[4:5], s33, v64
	v_add_u32_e32 v68, -2.0, v64
	s_and_saveexec_b64 s[0:1], s[4:5]
	s_xor_b64 s[0:1], exec, s[0:1]
	s_cbranch_execz .LBB0_1179
	v_cmp_gt_u32_e32 vcc, 48, v68
	s_and_saveexec_b64 s[6:7], vcc
	s_cbranch_execz .LBB0_1178
	v_mul_f32_e32 v60, 0xbfb8aa3b, v60
	v_mul_f32_e32 v61, 0xbfb8aa3b, v61
	v_exp_f32_e32 v60, v60
	v_exp_f32_e32 v61, v61
	v_mov_b32_e32 v69, v65
	v_lshl_add_u64 v[72:73], v[68:69], 2, v[70:71]
	v_mul_f32_e32 v62, 0xbfb8aa3b, v62
	v_pk_add_f32 v[60:61], v[60:61], 1.0 op_sel_hi:[1,0]
	v_mul_f32_e32 v63, 0xbfb8aa3b, v63
	v_exp_f32_e32 v62, v62
	v_exp_f32_e32 v63, v63
	v_rcp_f32_e32 v67, v61
	s_nop 0
	v_mul_f32_e32 v61, 1.0, v67
	v_pk_add_f32 v[62:63], v[62:63], 1.0 op_sel_hi:[1,0]
	v_rcp_f32_e32 v67, v60
	s_nop 0
	v_mul_f32_e32 v60, 1.0, v67
	v_rcp_f32_e32 v67, v63
	s_nop 0
	v_mul_f32_e32 v63, 1.0, v67
	v_rcp_f32_e32 v67, v62
	s_nop 0
	v_mul_f32_e32 v62, 1.0, v67
	flat_store_dwordx4 v[72:73], v[60:63]

; DI float xsumh(float v) { const u32x2 r = __builtin_amdgcn_permlane32_swap(__float_as_uint(v), __float_as_uint(v), false, false); return __uint_as_float(r[0]) + __uint_as_float(r[1]); }
; DI int ltid() { int x = threadIdx.x; asm volatile("" : "+v"(x)); return x; }
; DI float q_bound(const bf16x8 (&qf)[4], unsigned kmax2bits) {
;   float ss = 0.f;
; #pragma unroll
;   for (int ks = 0; ks < 4; ++ks)
; #pragma unroll
;     for (int j = 0; j < 8; ++j) { const float v = __uint_as_float(((unsigned)(unsigned short)qf[ks][j]) << 16); ss += v * v; }
;   ss = xsumh(ss);
;   return sqrtf(ss * __uint_as_float(kmax2bits)) * 1.02f + 1.0f;
; DI void diff_attn_phase(const Params& p, char* smem) {
;     ...
;   for (;;) {
;     const int slot = fetch_task(p.ctr + 1, smem);
;     if (slot >= 2048) break;
;     const int tid = ltid(), lane = tid & 63, wid = tid >> 6, r = lane & 31, h = lane >> 5;
;     const int pair = slot >> 1, mm = (slot & 1) ? 0 : 1;
;     const int qt = 63 - (pair >> 4), bh = pair & 15;
;     const int b = bh >> 3, hd = bh & 7;
;     const int q0 = qt * 128 + wid * 32, tq = q0 + r;
;     const long tok = (long)b * SEQ + tq;
;     const float slope2 = exp2f(-(float)(hd + 1)) * LOG2E;
;     const int thi = ((qt * 128 + 127) >> 6) + 1;
;     const u16* vb_ = p.qkvz + (long)b * SEQ * LD + 2048 + hd * 128;
;     f32x16 ot[4];
;     float rl;
;     {
;       bf16x8 qf[4];
;       load_q(qf, p.qkvz + tok * LD + hd * 128 + mm * 64, h);
;       const u16* kb_ = p.qkvz + (long)b * SEQ * LD + 1024 + hd * 128 + mm * 64;
;       float m = 0.f, l = 0.f;
; #pragma unroll
;       for (int dc = 0; dc < 4; ++dc)
; #pragma unroll
;         for (int i = 0; i < 16; ++i) ot[dc][i] = 0.f;
;       const float qb = q_bound(qf, p.kmax2[128 + b * 64 + 16 + hd * 2 + mm]);
;       flash_pass<128, false, true>(smem, kb_, LD, vb_, LD, 0, thi, nullptr, qf, tq, 1, BIGW, slope2, q0, q0 + 31, nullptr, qb, ot, m, l);
.LBB0_1479:
	s_or_b64 exec, exec, s[0:1]
	s_waitcnt lgkmcnt(0)
	s_barrier
	ds_read_b32 v0, v148
	s_movk_i32 s0, 0x7ff
	s_waitcnt lgkmcnt(0)
	v_cmp_lt_i32_e32 vcc, s0, v0
	v_readfirstlane_b32 s2, v0
	s_mov_b64 s[0:1], -1
	s_cbranch_vccnz .LBB0_1474
	v_mov_b32_e32 v154, v222
	s_ashr_i32 s92, s2, 1
	s_lshl_b32 s0, s2, 2
	v_ashrrev_i32_e32 v0, 1, v154
	s_and_b32 s17, s92, 7
	s_and_b32 s4, s0, 0xffffff80
	v_and_b32_e32 v0, 0xffffffe0, v0
	v_subrev_u32_e32 v2, s4, v0
	s_add_i32 s0, s17, 1
	s_and_b32 s56, s2, 1
	s_bfe_u32 s16, s92, 0x10003
	v_add_u32_e32 v156, 0x1f80, v2
	v_cvt_f32_ubyte0_e32 v3, s0
	s_mov_b32 s0, 0x42fc0000
	s_xor_b32 s11, s56, 1
	v_and_or_b32 v134, v154, 31, v156
	s_lshl_b32 s2, s16, 13
	v_cmp_lt_f32_e32 vcc, s0, v3
	v_ashrrev_i32_e32 v135, 31, v134
	s_and_b64 s[0:1], vcc, exec
	v_lshl_add_u64 v[132:133], v[134:135], 0, s[2:3]
	s_cselect_b32 s1, 0xffffffc0, 0
	s_sub_i32 s0, 0x1fc0, s4
	s_lshl_b32 s2, s16, 26
	s_add_u32 s6, s62, s2
	v_lshlrev_b64 v[4:5], 13, v[132:133]
	s_addc_u32 s7, s63, 0
	v_lshl_add_u64 v[130:131], s[62:63], 0, v[4:5]
	s_lshl_b32 s2, s17, 8
	v_bfe_u32 v155, v154, 5, 1
	v_lshl_add_u64 v[4:5], v[130:131], 0, s[2:3]
	s_lshl_b32 s4, s11, 7
	s_mov_b32 s5, s3
	v_lshl_add_u64 v[4:5], v[4:5], 0, s[4:5]
	v_lshlrev_b32_e32 v0, 4, v155
	v_lshl_add_u64 v[4:5], v[4:5], 0, v[0:1]
	global_load_dwordx4 v[112:115], v[4:5], off
	global_load_dwordx4 v[116:119], v[4:5], off offset:32
	global_load_dwordx4 v[120:123], v[4:5], off offset:64
	global_load_dwordx4 v[124:127], v[4:5], off offset:96
	s_lshl_b32 s57, s17, 7
	s_add_u32 s8, s6, s2
	s_addc_u32 s9, s7, 0
	s_lshr_b32 s10, s0, 6
	s_add_u32 s6, s8, s4
	s_addc_u32 s7, s9, 0
	s_lshl_b32 s2, s16, 6
	s_lshl_b32 s4, s17, 1
	s_or_b32 s2, s2, s4
	s_or_b32 s2, s2, s11
	s_lshl_b32 s2, s2, 2
	v_readlane_b32 s16, v255, 14
	v_mov_b32_e32 v0, s2
	v_readlane_b32 s17, v255, 15
	v_cndmask_b32_e32 v6, 0, v152, vcc
	v_sub_f32_e32 v3, v6, v3
	s_mov_b32 s4, 0xf800000
	v_exp_f32_e32 v3, v3
	v_add_u32_e32 v157, 0x1f9f, v2
	global_load_dword v0, v0, s[16:17] offset:576
	s_add_i32 s24, s10, -1
	v_ldexp_f32 v3, v3, s1
	v_mul_f32_e32 v136, 0x3fb8aa3b, v3
	s_mov_b32 s1, 0x3f828f5c
	v_mov_b32_e32 v183, 0
	s_mov_b32 s2, 2
	s_mov_b32 s93, 0
	v_add_u32_e32 v171, 1, v134
	v_mov_b32_e32 v144, v136
	v_mov_b32_e32 v145, v136
	v_mov_b32_e32 v146, v136
	v_mov_b32_e32 v147, v136
	s_add_i32 s25, s10, 1
	s_mov_b32 s16, 0
	v_mov_b32_e32 v184, 0
	s_mov_b32 s17, 0
	v_mov_b32_e32 v80, 0
	v_mov_b32_e32 v81, v183
	v_mov_b32_e32 v82, v183
	v_mov_b32_e32 v83, v183
	v_mov_b32_e32 v84, v183
	v_mov_b32_e32 v85, v183
	v_mov_b32_e32 v86, v183
	v_mov_b32_e32 v87, v183
	v_mov_b32_e32 v88, v183
	v_mov_b32_e32 v89, v183
	v_mov_b32_e32 v90, v183
	v_mov_b32_e32 v91, v183
	v_mov_b32_e32 v92, v183
	v_mov_b32_e32 v93, v183
	v_mov_b32_e32 v94, v183
	v_mov_b32_e32 v95, v183
	v_mov_b32_e32 v96, v183
	v_mov_b32_e32 v97, v183
	v_mov_b32_e32 v98, v183
	v_mov_b32_e32 v99, v183
	v_mov_b32_e32 v100, v183
	v_mov_b32_e32 v101, v183
	v_mov_b32_e32 v102, v183
	v_mov_b32_e32 v103, v183
	v_mov_b32_e32 v104, v183
	v_mov_b32_e32 v105, v183
	v_mov_b32_e32 v106, v183
	v_mov_b32_e32 v107, v183
	v_mov_b32_e32 v108, v183
	v_mov_b32_e32 v109, v183
	v_mov_b32_e32 v110, v183
	v_mov_b32_e32 v111, v183
	v_readlane_b32 s18, v255, 16
	v_readlane_b32 s19, v255, 17
	s_waitcnt vmcnt(0)
	v_and_b32_e32 v5, 0xffff0000, v112
	v_lshlrev_b32_e32 v4, 16, v112
	v_mul_f32_e32 v5, v5, v5
	v_lshlrev_b32_e32 v6, 16, v113
	v_fmac_f32_e32 v5, v4, v4
	v_and_b32_e32 v7, 0xffff0000, v113
	v_fmac_f32_e32 v5, v6, v6
	v_lshlrev_b32_e32 v8, 16, v114
	v_fmac_f32_e32 v5, v7, v7
	v_and_b32_e32 v9, 0xffff0000, v114
	v_fmac_f32_e32 v5, v8, v8
	v_lshlrev_b32_e32 v10, 16, v115
	v_fmac_f32_e32 v5, v9, v9
	v_and_b32_e32 v11, 0xffff0000, v115
	v_fmac_f32_e32 v5, v10, v10
	s_waitcnt vmcnt(3)
	v_lshlrev_b32_e32 v12, 16, v116
	v_fmac_f32_e32 v5, v11, v11
	v_and_b32_e32 v13, 0xffff0000, v116
	v_fmac_f32_e32 v5, v12, v12
	v_lshlrev_b32_e32 v14, 16, v117
	v_fmac_f32_e32 v5, v13, v13
	v_and_b32_e32 v15, 0xffff0000, v117
	v_fmac_f32_e32 v5, v14, v14
	v_lshlrev_b32_e32 v16, 16, v118
	v_fmac_f32_e32 v5, v15, v15
	v_and_b32_e32 v17, 0xffff0000, v118
	v_fmac_f32_e32 v5, v16, v16
	v_lshlrev_b32_e32 v18, 16, v119
	v_fmac_f32_e32 v5, v17, v17
	v_and_b32_e32 v19, 0xffff0000, v119
	v_fmac_f32_e32 v5, v18, v18
	s_waitcnt vmcnt(2)
	v_lshlrev_b32_e32 v20, 16, v120
	v_fmac_f32_e32 v5, v19, v19
	v_and_b32_e32 v21, 0xffff0000, v120
	v_fmac_f32_e32 v5, v20, v20
	v_lshlrev_b32_e32 v22, 16, v121
	v_fmac_f32_e32 v5, v21, v21
	v_and_b32_e32 v23, 0xffff0000, v121
	v_fmac_f32_e32 v5, v22, v22
	v_lshlrev_b32_e32 v24, 16, v122
	v_fmac_f32_e32 v5, v23, v23
	v_and_b32_e32 v25, 0xffff0000, v122
	v_fmac_f32_e32 v5, v24, v24
	v_lshlrev_b32_e32 v26, 16, v123
	v_fmac_f32_e32 v5, v25, v25
	v_and_b32_e32 v27, 0xffff0000, v123
	v_fmac_f32_e32 v5, v26, v26
	s_waitcnt vmcnt(1)
	v_lshlrev_b32_e32 v28, 16, v124
	v_fmac_f32_e32 v5, v27, v27
	v_and_b32_e32 v29, 0xffff0000, v124
	v_fmac_f32_e32 v5, v28, v28
	v_lshlrev_b32_e32 v30, 16, v125
	v_fmac_f32_e32 v5, v29, v29
	v_and_b32_e32 v31, 0xffff0000, v125
	v_fmac_f32_e32 v5, v30, v30
	v_lshlrev_b32_e32 v32, 16, v126
	v_fmac_f32_e32 v5, v31, v31
	v_and_b32_e32 v33, 0xffff0000, v126
	v_fmac_f32_e32 v5, v32, v32
	v_lshlrev_b32_e32 v34, 16, v127
	v_fmac_f32_e32 v5, v33, v33
	v_and_b32_e32 v35, 0xffff0000, v127
	v_fmac_f32_e32 v5, v34, v34
	v_fmac_f32_e32 v5, v35, v35
	v_mov_b32_e32 v4, v5
	s_nop 1
	v_permlane32_swap_b32_e32 v5, v4
	v_add_f32_e32 v4, v5, v4
	s_waitcnt vmcnt(0)
	v_mul_f32_e32 v0, v0, v4
	v_mul_f32_e32 v4, 0x4f800000, v0
	v_cmp_gt_f32_e32 vcc, s4, v0
	s_nop 1
	v_cndmask_b32_e32 v0, v0, v4, vcc
	v_sqrt_f32_e32 v4, v0
	s_nop 0
	v_add_u32_e32 v3, -1, v4
	v_add_u32_e32 v5, 1, v4
	v_fma_f32 v6, -v3, v4, v0
	v_fma_f32 v7, -v5, v4, v0
	v_cmp_ge_f32_e64 s[4:5], 0, v6
	v_mov_b32_e32 v6, v222
	s_waitcnt lgkmcnt(0)
	s_barrier
; #define LAS __attribute__((address_space(3)))
; #define RAW_BARRIER() do { asm volatile("s_waitcnt lgkmcnt(0)" ::: "memory"); __builtin_amdgcn_s_barrier(); } while (0)
; template <int DV, bool WITH_V>
; DI void kv_issue(char* smem, int stage, const u16* kbase, long kpitch, const u16* vbase, long vpitch, int t, int lane, int wid) {
;   char* sb = smem + stage * Ring<DV>::STAGE;
;   {
;     const int lr = lane >> 3;
; #pragma unroll
;     for (int j = 0; j < 2; ++j) {
;       const int q = wid * 2 + j, row = q * 8 + lr;
;       const int cc = (lane & 7) ^ ((row >> 1) & 7);
;       __builtin_amdgcn_global_load_lds((const unsigned*)(kbase + (long)(t * 64 + row) * kpitch + cc * 8), (LAS unsigned*)(sb + q * 1024), 16, 0, 0);
;     }
;   }
;   if (WITH_V) {
;     if (DV == 128) {
;       const int lr = lane >> 4, cc = (lane & 15) ^ (lr << 2);
; #pragma unroll
;       for (int j = 0; j < 4; ++j) {
;         const int q = wid * 4 + j, row = q * 4 + lr;
;         __builtin_amdgcn_global_load_lds((const unsigned*)(vbase + (long)(t * 64 + row) * vpitch + cc * 8), (LAS unsigned*)(sb + 8192 + q * 1024), 16, 0, 0);
;       }
;     } else {
;       const int lr = lane >> 3, cc = (lane & 7) ^ (((lr >> 1) & 1) << 2);
; #pragma unroll
;       for (int j = 0; j < 2; ++j) {
;         const int q = wid * 2 + j, row = q * 8 + lr;
;         __builtin_amdgcn_global_load_lds((const unsigned*)(vbase + (long)(t * 64 + row) * vpitch + cc * 8), (LAS unsigned*)(sb + 8192 + q * 1024), 16, 0, 0);
;       }
;     }
;   }
; template <int DV, bool SEL, bool TERM> ...
;     ...
;   RAW_BARRIER();
;   int t = prev_active(thi - 1, tlo, um);
;   int t1 = (t >= tlo) ? prev_active(t - 1, tlo, um) : t;
;   if (t >= tlo) kv_issue<DV, true>(smem, 0, kbase, kpitch, vbase, vpitch, t, lane, wid);
;   if (t1 >= tlo) kv_issue<DV, true>(smem, 1, kbase, kpitch, vbase, vpitch, t1, lane, wid);
	v_cndmask_b32_e64 v3, v4, v3, s[4:5]
	v_cmp_lt_f32_e64 s[4:5], 0, v7
	v_ashrrev_i32_e32 v8, 6, v6
	v_bfe_u32 v9, v6, 5, 1
	v_cndmask_b32_e64 v3, v3, v5, s[4:5]
	v_mul_f32_e32 v4, 0x37800000, v3
	v_cndmask_b32_e32 v3, v3, v4, vcc
	v_cmp_class_f32_e32 vcc, v0, v149
	v_bfe_u32 v2, v6, 1, 3
	v_bfe_u32 v15, v6, 3, 3
	v_cndmask_b32_e32 v0, v3, v0, vcc
	v_fma_f32 v135, v0, s1, 1.0
	v_lshlrev_b32_e32 v0, 7, v6
	v_bitop3_b32 v12, v9, v2, 2 bitop3:0x36
	v_bitop3_b32 v13, v9, v2, 4 bitop3:0x36
	v_bitop3_b32 v14, v9, v2, 6 bitop3:0x36
	v_lshlrev_b32_e32 v158, 4, v8
	v_or_b32_e32 v2, s0, v15
	v_and_b32_e32 v10, 0xf80, v0
	v_lshrrev_b32_e32 v0, 1, v6
	v_bfe_u32 v159, v6, 4, 2
	v_add_u32_e32 v2, v2, v158
	v_bitop3_b32 v11, v9, v0, 7 bitop3:0x78
	v_xor_b32_e32 v0, v159, v6
	v_ashrrev_i32_e32 v3, 31, v2
	v_lshlrev_b64 v[2:3], 13, v[2:3]
	v_lshlrev_b32_e32 v0, 4, v0
	v_lshl_add_u64 v[2:3], s[6:7], 0, v[2:3]
	v_and_b32_e32 v0, 0x70, v0
	v_lshlrev_b32_e32 v16, 11, v8
	v_lshl_add_u64 v[2:3], v[2:3], 0, v[0:1]
	v_readfirstlane_b32 s1, v16
	v_lshl_or_b32 v17, v8, 1, 1
	v_lshl_add_u64 v[2:3], v[2:3], 0, s[12:13]
	s_mov_b32 m0, s1
	v_lshl_or_b32 v160, v17, 3, v15
	global_load_lds_dwordx4 v[2:3], off
	v_lshrrev_b32_e32 v2, 1, v160
	v_xor_b32_e32 v4, v2, v6
	v_add_u32_e32 v2, s0, v160
	v_ashrrev_i32_e32 v3, 31, v2
	v_lshlrev_b64 v[2:3], 13, v[2:3]
	v_lshlrev_b32_e32 v4, 4, v4
	v_lshl_add_u64 v[2:3], s[6:7], 0, v[2:3]
	v_and_b32_e32 v4, 0x70, v4
	v_mov_b32_e32 v5, v1
	v_lshlrev_b32_e32 v17, 10, v17
	v_lshl_add_u64 v[2:3], v[2:3], 0, v[4:5]
	v_readfirstlane_b32 s1, v17
	v_lshl_add_u64 v[2:3], v[2:3], 0, s[12:13]
	s_mov_b32 m0, s1
	v_or_b32_e32 v19, s0, v159
	global_load_lds_dwordx4 v[2:3], off
	v_lshlrev_b32_e32 v2, 4, v6
	v_lshlrev_b32_e32 v3, 6, v159
	s_movk_i32 s0, 0xf0
	v_bitop3_b32 v2, v3, v2, s0 bitop3:0x78
	v_mov_b32_e32 v3, v1
	v_lshl_add_u64 v[2:3], s[8:9], 0, v[2:3]
	s_mov_b64 s[0:1], 0x1000
	v_lshl_add_u64 v[138:139], v[2:3], 0, s[0:1]
	v_add_u32_e32 v2, v19, v158
	v_add_u32_e32 v21, v16, v16
	v_lshlrev_b32_e32 v18, 2, v8
	v_ashrrev_i32_e32 v3, 31, v2
	v_add_u32_e32 v22, 0x2000, v21
	v_lshlrev_b64 v[2:3], 13, v[2:3]
	v_readfirstlane_b32 s0, v22
	v_or_b32_e32 v22, 1, v18
	v_lshl_add_u64 v[2:3], v[138:139], 0, v[2:3]
	s_mov_b32 m0, s0
	v_lshlrev_b32_e32 v161, 2, v22
	global_load_lds_dwordx4 v[2:3], off
	v_add_u32_e32 v2, v161, v19
	v_lshlrev_b32_e32 v22, 10, v22
	v_ashrrev_i32_e32 v3, 31, v2
	v_add_u32_e32 v23, 0x2000, v22
	v_lshlrev_b64 v[2:3], 13, v[2:3]
	v_readfirstlane_b32 s0, v23
	v_or_b32_e32 v23, 2, v18
	v_lshl_add_u64 v[2:3], v[138:139], 0, v[2:3]
	s_mov_b32 m0, s0
	v_lshlrev_b32_e32 v162, 2, v23
	global_load_lds_dwordx4 v[2:3], off
	v_add_u32_e32 v2, v162, v19
	v_lshlrev_b32_e32 v23, 10, v23
	v_ashrrev_i32_e32 v3, 31, v2
	v_add_u32_e32 v24, 0x2000, v23
	v_lshlrev_b64 v[2:3], 13, v[2:3]
	v_readfirstlane_b32 s0, v24
	v_or_b32_e32 v24, 3, v18
	v_lshl_add_u64 v[2:3], v[138:139], 0, v[2:3]
	s_mov_b32 m0, s0
	v_lshlrev_b32_e32 v163, 2, v24
	global_load_lds_dwordx4 v[2:3], off
	v_add_u32_e32 v2, v163, v19
	v_lshlrev_b32_e32 v19, 10, v24
	v_ashrrev_i32_e32 v3, 31, v2
	v_add_u32_e32 v24, 0x2000, v19
	v_lshlrev_b64 v[2:3], 13, v[2:3]
	v_readfirstlane_b32 s0, v24
	v_lshl_add_u64 v[2:3], v[138:139], 0, v[2:3]
	s_mov_b32 m0, s0
	s_lshl_b32 s0, s24, 6
	global_load_lds_dwordx4 v[2:3], off
	v_or_b32_e32 v2, s0, v15
	v_add_u32_e32 v2, v2, v158
	v_ashrrev_i32_e32 v3, 31, v2
	v_lshlrev_b64 v[2:3], 13, v[2:3]
	v_lshl_add_u64 v[2:3], s[6:7], 0, v[2:3]
	v_add_u32_e32 v24, 0x6000, v16
	v_lshl_add_u64 v[2:3], v[2:3], 0, v[0:1]
	v_readfirstlane_b32 s1, v24
	v_lshl_add_u64 v[2:3], v[2:3], 0, s[12:13]
	s_mov_b32 m0, s1
	v_add_u32_e32 v17, 0x6000, v17
	global_load_lds_dwordx4 v[2:3], off
	v_add_u32_e32 v2, s0, v160
	v_ashrrev_i32_e32 v3, 31, v2
	v_lshlrev_b64 v[2:3], 13, v[2:3]
	v_lshl_add_u64 v[2:3], s[6:7], 0, v[2:3]
	v_lshl_add_u64 v[2:3], v[2:3], 0, v[4:5]
	v_readfirstlane_b32 s1, v17
	v_lshl_add_u64 v[2:3], v[2:3], 0, s[12:13]
	s_mov_b32 m0, s1
	v_or_b32_e32 v17, s0, v159
	global_load_lds_dwordx4 v[2:3], off
	v_add_u32_e32 v2, v17, v158
	v_ashrrev_i32_e32 v3, 31, v2
	v_add_u32_e32 v21, 0x8000, v21
	v_lshlrev_b64 v[2:3], 13, v[2:3]
	v_readfirstlane_b32 s0, v21
	v_lshl_add_u64 v[2:3], v[138:139], 0, v[2:3]
; #define LAS __attribute__((address_space(3)))
; template <int DV, bool WITH_V>
; DI void kv_issue(char* smem, int stage, const u16* kbase, long kpitch, const u16* vbase, long vpitch, int t, int lane, int wid) {
;   char* sb = smem + stage * Ring<DV>::STAGE;
;   {
;     const int lr = lane >> 3;
; #pragma unroll
;     for (int j = 0; j < 2; ++j) {
;       const int q = wid * 2 + j, row = q * 8 + lr;
;       const int cc = (lane & 7) ^ ((row >> 1) & 7);
;       __builtin_amdgcn_global_load_lds((const unsigned*)(kbase + (long)(t * 64 + row) * kpitch + cc * 8), (LAS unsigned*)(sb + q * 1024), 16, 0, 0);
;     }
;   }
;   if (WITH_V) {
;     if (DV == 128) {
;       const int lr = lane >> 4, cc = (lane & 15) ^ (lr << 2);
; #pragma unroll
;       for (int j = 0; j < 4; ++j) {
;         const int q = wid * 4 + j, row = q * 4 + lr;
;         __builtin_amdgcn_global_load_lds((const unsigned*)(vbase + (long)(t * 64 + row) * vpitch + cc * 8), (LAS unsigned*)(sb + 8192 + q * 1024), 16, 0, 0);
;       }
;     } else {
;       const int lr = lane >> 3, cc = (lane & 7) ^ (((lr >> 1) & 1) << 2);
; #pragma unroll
;       for (int j = 0; j < 2; ++j) {
;         const int q = wid * 2 + j, row = q * 8 + lr;
;         __builtin_amdgcn_global_load_lds((const unsigned*)(vbase + (long)(t * 64 + row) * vpitch + cc * 8), (LAS unsigned*)(sb + 8192 + q * 1024), 16, 0, 0);
;       }
;     }
;   }
; template <int DV>
; DI void pv_tile(f32x16 (&ot)[DV / 32], const bf16x8 (&pk)[2][2], char* sb, int lane) {
;     ...
;   const int h = lane >> 5, i16 = lane & 15, qq = i16 >> 2, pp = i16 & 3, blk = (lane >> 4) & 1;
;   const int qx = (DV == 128) ? qq : (qq >> 1);
;   const unsigned vb = (unsigned)(size_t)(sb + 8192) + (4 * h + qq) * VP + 32 * blk + 8 * pp;
;   unsigned a[NDC];
; #pragma unroll
;   for (int dc = 0; dc < NDC; ++dc) a[dc] = vb + ((dc ^ qx) << 6);
	s_mov_b32 m0, s0
	v_add_u32_e32 v21, 0x8000, v22
	global_load_lds_dwordx4 v[2:3], off
	v_add_u32_e32 v2, v161, v17
	v_ashrrev_i32_e32 v3, 31, v2
	v_lshlrev_b64 v[2:3], 13, v[2:3]
	v_readfirstlane_b32 s0, v21
	v_lshl_add_u64 v[2:3], v[138:139], 0, v[2:3]
	s_mov_b32 m0, s0
	v_add_u32_e32 v21, 0x8000, v23
	global_load_lds_dwordx4 v[2:3], off
	v_add_u32_e32 v2, v162, v17
	v_ashrrev_i32_e32 v3, 31, v2
	v_lshlrev_b64 v[2:3], 13, v[2:3]
	v_readfirstlane_b32 s0, v21
	v_lshl_add_u64 v[2:3], v[138:139], 0, v[2:3]
	s_mov_b32 m0, s0
	v_lshl_add_u64 v[140:141], s[6:7], 0, v[0:1]
	global_load_lds_dwordx4 v[2:3], off
	v_add_u32_e32 v2, v163, v17
	v_ashrrev_i32_e32 v3, 31, v2
	v_add_u32_e32 v17, 0x8000, v19
	v_lshlrev_b64 v[2:3], 13, v[2:3]
	v_readfirstlane_b32 s0, v17
	v_lshl_add_u64 v[2:3], v[138:139], 0, v[2:3]
	s_mov_b32 m0, s0
	v_bfe_u32 v0, v6, 2, 2
	global_load_lds_dwordx4 v[2:3], off
	v_lshrrev_b32_e32 v2, 3, v6
	v_lshlrev_b32_e32 v20, 3, v6
	v_and_or_b32 v2, v2, 4, v0
	v_lshlrev_b32_e32 v3, 1, v6
	v_and_b32_e32 v7, 63, v6
	v_lshlrev_b32_e32 v8, 12, v8
	v_or_b32_e32 v165, v158, v15
	v_lshl_add_u64 v[142:143], s[6:7], 0, v[4:5]
	v_lshlrev_b32_e32 v2, 8, v2
	v_and_b32_e32 v3, 32, v3
	v_and_b32_e32 v4, 24, v20
	v_lshl_or_b32 v179, v14, 4, v10
	v_mov_b32_e32 v14, v1
	v_mov_b32_e32 v15, v1
	v_add_u32_e32 v164, 0x12000, v18
	v_cmp_eq_u32_e64 s[4:5], 0, v7
	v_or3_b32 v166, v4, v3, v2
	v_lshlrev_b32_e32 v167, 6, v0
	v_lshlrev_b32_e32 v172, 2, v9
	v_add_u32_e32 v173, 0xec00, v8
	v_add_u32_e32 v174, 0xe800, v8
	v_add_u32_e32 v175, 0xe400, v8
	v_add_u32_e32 v176, 0xe000, v8
	v_add_u32_e32 v177, 0xc400, v16
	v_add_u32_e32 v178, 0xc000, v16
	v_lshl_or_b32 v180, v11, 4, v10
	v_lshl_or_b32 v181, v13, 4, v10
	v_lshl_or_b32 v182, v12, 4, v10
	v_mov_b32_e32 v0, v1
	v_mov_b32_e32 v2, v1
	v_mov_b32_e32 v3, v1
	v_mov_b32_e32 v4, v1
	v_mov_b32_e32 v6, v1
	v_mov_b32_e32 v7, v1
	v_mov_b32_e32 v8, v1
	v_mov_b32_e32 v9, v1
	v_mov_b32_e32 v10, v1
	v_mov_b32_e32 v11, v1
	v_mov_b32_e32 v12, v1
	v_mov_b32_e32 v13, v1
	v_mov_b64_e32 v[30:31], v[14:15]
	v_mov_b64_e32 v[46:47], v[14:15]
	v_mov_b64_e32 v[62:63], v[14:15]
	v_mov_b64_e32 v[78:79], v[14:15]
	v_xor_b32_e32 v168, 64, v167
	v_xor_b32_e32 v169, 0x80, v167
	v_xor_b32_e32 v170, 0xc0, v167
	v_mov_b64_e32 v[28:29], v[12:13]
	v_mov_b64_e32 v[26:27], v[10:11]
	v_mov_b64_e32 v[24:25], v[8:9]
	v_mov_b64_e32 v[22:23], v[6:7]
	v_mov_b64_e32 v[20:21], v[4:5]
	v_mov_b64_e32 v[18:19], v[2:3]
	v_mov_b64_e32 v[16:17], v[0:1]
	v_mov_b64_e32 v[44:45], v[12:13]
	v_mov_b64_e32 v[42:43], v[10:11]
	v_mov_b64_e32 v[40:41], v[8:9]
	v_mov_b64_e32 v[38:39], v[6:7]
	v_mov_b64_e32 v[36:37], v[4:5]
	v_mov_b64_e32 v[34:35], v[2:3]
	v_mov_b64_e32 v[32:33], v[0:1]
	v_mov_b64_e32 v[60:61], v[12:13]
	v_mov_b64_e32 v[58:59], v[10:11]
	v_mov_b64_e32 v[56:57], v[8:9]
	v_mov_b64_e32 v[54:55], v[6:7]
	v_mov_b64_e32 v[52:53], v[4:5]
	v_mov_b64_e32 v[50:51], v[2:3]
	v_mov_b64_e32 v[48:49], v[0:1]
	v_mov_b64_e32 v[76:77], v[12:13]
	v_mov_b64_e32 v[74:75], v[10:11]
	v_mov_b64_e32 v[72:73], v[8:9]
	v_mov_b64_e32 v[70:71], v[6:7]
	v_mov_b64_e32 v[68:69], v[4:5]
	v_mov_b64_e32 v[66:67], v[2:3]
	v_mov_b64_e32 v[64:65], v[0:1]
	v_mov_b32_e32 v6, 0
	v_mov_b32_e32 v224, v165
	v_ashrrev_i32_e32 v225, 31, v224
	v_lshlrev_b64 v[224:225], 13, v[224:225]
	v_lshl_add_u64 v[224:225], v[140:141], 0, v[224:225]
	v_lshl_add_u64 v[224:225], v[224:225], 0, s[12:13]
	v_mov_b32_e32 v226, v160
	v_ashrrev_i32_e32 v227, 31, v226
	v_lshlrev_b64 v[226:227], 13, v[226:227]
	v_lshl_add_u64 v[226:227], v[142:143], 0, v[226:227]
	v_lshl_add_u64 v[226:227], v[226:227], 0, s[12:13]
	v_add_u32_e32 v228, v159, v158
	v_ashrrev_i32_e32 v229, 31, v228
	v_lshlrev_b64 v[228:229], 13, v[228:229]
	v_lshl_add_u64 v[228:229], v[138:139], 0, v[228:229]
	v_add_u32_e32 v230, v159, v161
	v_ashrrev_i32_e32 v231, 31, v230
	v_lshlrev_b64 v[230:231], 13, v[230:231]
	v_lshl_add_u64 v[230:231], v[138:139], 0, v[230:231]
	v_add_u32_e32 v232, v159, v162
	v_ashrrev_i32_e32 v233, 31, v232
	v_lshlrev_b64 v[232:233], 13, v[232:233]
	v_lshl_add_u64 v[232:233], v[138:139], 0, v[232:233]
	v_add_u32_e32 v234, v159, v163
	v_ashrrev_i32_e32 v235, 31, v234
	v_lshlrev_b64 v[234:235], 13, v[234:235]
	v_lshl_add_u64 v[234:235], v[138:139], 0, v[234:235]

; #define LAS __attribute__((address_space(3)))
; template <int DV, bool WITH_V>
; DI void kv_issue(char* smem, int stage, const u16* kbase, long kpitch, const u16* vbase, long vpitch, int t, int lane, int wid) {
;   char* sb = smem + stage * Ring<DV>::STAGE;
;   {
;     const int lr = lane >> 3;
; #pragma unroll
;     for (int j = 0; j < 2; ++j) {
;       const int q = wid * 2 + j, row = q * 8 + lr;
;       const int cc = (lane & 7) ^ ((row >> 1) & 7);
;       __builtin_amdgcn_global_load_lds((const unsigned*)(kbase + (long)(t * 64 + row) * kpitch + cc * 8), (LAS unsigned*)(sb + q * 1024), 16, 0, 0);
;     }
;   }
;   if (WITH_V) {
;     if (DV == 128) {
;       const int lr = lane >> 4, cc = (lane & 15) ^ (lr << 2);
; #pragma unroll
;       for (int j = 0; j < 4; ++j) {
;         const int q = wid * 4 + j, row = q * 4 + lr;
;         __builtin_amdgcn_global_load_lds((const unsigned*)(vbase + (long)(t * 64 + row) * vpitch + cc * 8), (LAS unsigned*)(sb + 8192 + q * 1024), 16, 0, 0);
;       }
;     } else {
;       const int lr = lane >> 3, cc = (lane & 7) ^ (((lr >> 1) & 1) << 2);
; #pragma unroll
;       for (int j = 0; j < 2; ++j) {
;         const int q = wid * 2 + j, row = q * 8 + lr;
;         __builtin_amdgcn_global_load_lds((const unsigned*)(vbase + (long)(t * 64 + row) * vpitch + cc * 8), (LAS unsigned*)(sb + 8192 + q * 1024), 16, 0, 0);
;       }
;     }
;   }
.LBB0_1491:
	s_or_b64 exec, exec, s[10:11]
	v_cndmask_b32_e64 v5, 0, 1, s[8:9]
	s_nop 0
	v_readfirstlane_b32 s8, v5
	s_sub_i32 s18, s24, s8
	s_cmp_lt_i32 s18, 0
	s_cbranch_scc1 .LBB0_1493
	s_mul_hi_u32 s8, s2, 0xaaaaaaab
	s_lshr_b32 s8, s8, 1
	s_mul_i32 s8, s8, 0x12000
	s_lshl_b32 s100, s18, 19
	s_mov_b32 s101, 0
	s_sub_i32 s8, s93, s8
	v_add_u32_e32 v5, s8, v178
	v_lshl_add_u64 v[8:9], v[224:225], 0, s[100:101]
	v_readfirstlane_b32 s10, v5
	s_mov_b32 m0, s10
	v_add_u32_e32 v7, s8, v177
	global_load_lds_dwordx4 v[8:9], off
	v_lshl_add_u64 v[8:9], v[226:227], 0, s[100:101]
	v_readfirstlane_b32 s10, v7
	s_mov_b32 m0, s10
	v_add_u32_e32 v5, s8, v176
	global_load_lds_dwordx4 v[8:9], off
	v_lshl_add_u64 v[8:9], v[228:229], 0, s[100:101]
	v_readfirstlane_b32 s10, v5
	s_mov_b32 m0, s10
	v_add_u32_e32 v7, s8, v175
	global_load_lds_dwordx4 v[8:9], off
	v_lshl_add_u64 v[8:9], v[230:231], 0, s[100:101]
	v_readfirstlane_b32 s10, v7
	s_mov_b32 m0, s10
	v_add_u32_e32 v5, s8, v174
	global_load_lds_dwordx4 v[8:9], off
	v_lshl_add_u64 v[8:9], v[232:233], 0, s[100:101]
	v_readfirstlane_b32 s10, v5
	s_mov_b32 m0, s10
	v_add_u32_e32 v7, s8, v173
	global_load_lds_dwordx4 v[8:9], off
	v_lshl_add_u64 v[8:9], v[234:235], 0, s[100:101]
	v_readfirstlane_b32 s10, v7
	s_mov_b32 m0, s10
	s_nop 0
	global_load_lds_dwordx4 v[8:9], off

; DI int lbid() { int x = blockIdx.x; asm volatile("" : "+s"(x)); return x; }
; template <class Epi>
; DI void gemm_phase_plain(const u16* A, long lda, const u16* Bt, long ldb, int M, int N, int K, const Epi& epi, char* smem) {
;     ...
;   for (int t = lbid(); t < nwg; t += gridDim.x) {
;     const int xcd = t & 7, off = t >> 3;
;     const int wg = (xcd < rr ? xcd * (q + 1) : rr * (q + 1) + (xcd - rr) * q) + off;
;     const int nig = 8 * MT, gid = wg / nig, fm = gid * 8, gsz = (NT - fm) < 8 ? (NT - fm) : 8;
;     const int nt = fm + (wg % nig) % gsz, mt = (wg % nig) / gsz;
;     gemm_tile(ar, 64, Bt, ldb, K, mt * 128, nt * 128, epi, smem);
;   }
.Lfe_join_C:
	s_load_dword s0, s[18:19], 0x0
	s_waitcnt lgkmcnt(0)
	s_add_i32 s25, s0, s25
	s_cmpk_lt_i32 s25, 0xe00
	s_cbranch_scc0 .LBB0_1930

; template <class ARow, class Epi>
; DI void gemm_tile(const ARow& arow, long a_kstride, const u16* __restrict__ Bt, long ldb, int K, int m0, int n0,
;                   const Epi& epi, char* smem) {
;     ...
;   for (int kt = 0; kt < KT; ++kt) {
;     const int cur = kt & 1;
;     if (kt + 1 < KT) GEMM_STAGE(cur ^ 1, kt + 1);
;     const char* sa = smem + cur * 32768 + wm * 64 * 128;
;     const char* sb = smem + cur * 32768 + 16384 + wn * 64 * 128;
; #pragma unroll
;     for (int ks = 0; ks < 2; ++ks) {
;       bf16x8 wf[4], af[4];
; #pragma unroll
;       for (int j = 0; j < 4; ++j) {
;         wf[j] = *(const bf16x8*)(sb + j * 2048 + foff[ks]);
;         af[j] = *(const bf16x8*)(sa + j * 2048 + foff[ks]);
;       }
; #pragma unroll
;       for (int ni = 0; ni < 4; ++ni)
; #pragma unroll
;         for (int mi = 0; mi < 4; ++mi) acc[ni][mi] = __builtin_amdgcn_mfma_f32_16x16x32_bf16(wf[ni], af[mi], acc[ni][mi], 0, 0, 0);
;     }
;     asm volatile("s_waitcnt vmcnt(0)" ::: "memory");
;     __syncthreads();
;   }
.LBB0_1702:
	s_and_b32 s6, s1, 0x8000
	s_xor_b32 s7, s6, 0x8000
	v_add_u32_e32 v108, s7, v90
	v_add_u32_e32 v91, s6, v88
	v_or_b32_e32 v116, s6, v89
	v_readfirstlane_b32 s6, v108
	v_add_u32_e32 v109, 0x4000, v108
	v_lshl_add_u64 v[92:93], v[66:67], 0, s[4:5]
	v_add_u32_e32 v110, 0x400, v108
	v_readfirstlane_b32 s7, v109
	s_mov_b32 m0, s6
	v_lshl_add_u64 v[94:95], v[68:69], 0, s[4:5]
	v_add_u32_e32 v111, 0x4400, v108
	v_readfirstlane_b32 s8, v110
	global_load_lds_dwordx4 v[92:93], off
	s_mov_b32 m0, s7
	v_lshl_add_u64 v[96:97], v[70:71], 0, s[4:5]
	v_add_u32_e32 v113, 0x800, v108
	v_readfirstlane_b32 s9, v111
	global_load_lds_dwordx4 v[94:95], off
	s_mov_b32 m0, s8
	v_lshl_add_u64 v[98:99], v[72:73], 0, s[4:5]
	v_add_u32_e32 v114, 0x4800, v108
	v_readfirstlane_b32 s10, v113
	global_load_lds_dwordx4 v[96:97], off
	s_mov_b32 m0, s9
	v_lshl_add_u64 v[100:101], v[74:75], 0, s[4:5]
	v_add_u32_e32 v115, 0xc00, v108
	v_readfirstlane_b32 s11, v114
	global_load_lds_dwordx4 v[98:99], off
	s_mov_b32 m0, s10
	v_lshl_add_u64 v[102:103], v[76:77], 0, s[4:5]
	v_add_u32_e32 v108, 0x4c00, v108
	v_readfirstlane_b32 s26, v115
	global_load_lds_dwordx4 v[100:101], off
	s_mov_b32 m0, s11
	v_lshl_add_u64 v[104:105], v[78:79], 0, s[4:5]
	v_readfirstlane_b32 s27, v108
	global_load_lds_dwordx4 v[102:103], off
	s_mov_b32 m0, s26
	v_lshl_add_u64 v[106:107], v[80:81], 0, s[4:5]
	global_load_lds_dwordx4 v[104:105], off
	s_mov_b32 m0, s27
	v_add_u32_e32 v117, v116, v87
	global_load_lds_dwordx4 v[106:107], off
	v_add_u32_e32 v112, v91, v87
	ds_read_b128 v[92:95], v117 offset:16384
	ds_read_b128 v[96:99], v112
	ds_read_b128 v[100:103], v117 offset:18432
	ds_read_b128 v[104:107], v112 offset:2048
	ds_read_b128 v[108:111], v112 offset:4096
	ds_read_b128 v[112:115], v112 offset:6144
	s_waitcnt lgkmcnt(0)
	v_mfma_f32_16x16x32_bf16 v[60:63], v[92:95], v[96:99], v[60:63]
	v_add_u32_e32 v116, v116, v86
	v_add_u32_e32 v91, v91, v86
	s_add_i32 s1, s1, 0x8000
	v_mfma_f32_16x16x32_bf16 v[56:59], v[92:95], v[104:107], v[56:59]
	s_add_u32 s4, s4, 0x80
	s_addc_u32 s5, s5, 0
	s_cmpk_eq_i32 s4, 0x780
	v_mfma_f32_16x16x32_bf16 v[48:51], v[92:95], v[108:111], v[48:51]
	v_mfma_f32_16x16x32_bf16 v[40:43], v[92:95], v[112:115], v[40:43]
	v_mfma_f32_16x16x32_bf16 v[36:39], v[100:103], v[96:99], v[36:39]
	v_mfma_f32_16x16x32_bf16 v[32:35], v[100:103], v[104:107], v[32:35]
	v_mfma_f32_16x16x32_bf16 v[28:31], v[100:103], v[108:111], v[28:31]
	v_mfma_f32_16x16x32_bf16 v[24:27], v[100:103], v[112:115], v[24:27]
	ds_read_b128 v[92:95], v117 offset:20480
	ds_read_b128 v[100:103], v117 offset:22528
	s_waitcnt lgkmcnt(0)
	v_mfma_f32_16x16x32_bf16 v[20:23], v[92:95], v[96:99], v[20:23]
	v_mfma_f32_16x16x32_bf16 v[16:19], v[92:95], v[104:107], v[16:19]
	v_mfma_f32_16x16x32_bf16 v[12:15], v[92:95], v[108:111], v[12:15]
	v_mfma_f32_16x16x32_bf16 v[8:11], v[92:95], v[112:115], v[8:11]
	ds_read_b128 v[92:95], v116 offset:16384
	v_mfma_f32_16x16x32_bf16 v[4:7], v[100:103], v[96:99], v[4:7]
	v_mfma_f32_16x16x32_bf16 v[0:3], v[100:103], v[104:107], v[0:3]
	v_mfma_f32_16x16x32_bf16 v[52:55], v[100:103], v[108:111], v[52:55]
	v_mfma_f32_16x16x32_bf16 v[44:47], v[100:103], v[112:115], v[44:47]
	ds_read_b128 v[96:99], v91
	ds_read_b128 v[100:103], v116 offset:18432
	ds_read_b128 v[104:107], v91 offset:2048
	ds_read_b128 v[108:111], v91 offset:4096
	ds_read_b128 v[112:115], v91 offset:6144
	s_waitcnt lgkmcnt(0)
	v_mfma_f32_16x16x32_bf16 v[60:63], v[92:95], v[96:99], v[60:63]
	v_mfma_f32_16x16x32_bf16 v[56:59], v[92:95], v[104:107], v[56:59]
	v_mfma_f32_16x16x32_bf16 v[48:51], v[92:95], v[108:111], v[48:51]
	v_mfma_f32_16x16x32_bf16 v[40:43], v[92:95], v[112:115], v[40:43]
	v_mfma_f32_16x16x32_bf16 v[36:39], v[100:103], v[96:99], v[36:39]
	v_mfma_f32_16x16x32_bf16 v[32:35], v[100:103], v[104:107], v[32:35]
	v_mfma_f32_16x16x32_bf16 v[28:31], v[100:103], v[108:111], v[28:31]
	v_mfma_f32_16x16x32_bf16 v[24:27], v[100:103], v[112:115], v[24:27]
	ds_read_b128 v[92:95], v116 offset:20480
	ds_read_b128 v[100:103], v116 offset:22528
	s_waitcnt vmcnt(0)
	s_waitcnt vmcnt(0) lgkmcnt(0)
	v_mfma_f32_16x16x32_bf16 v[20:23], v[92:95], v[96:99], v[20:23]
	s_barrier
	v_mfma_f32_16x16x32_bf16 v[16:19], v[92:95], v[104:107], v[16:19]
	v_mfma_f32_16x16x32_bf16 v[12:15], v[92:95], v[108:111], v[12:15]
	v_mfma_f32_16x16x32_bf16 v[8:11], v[92:95], v[112:115], v[8:11]
	v_mfma_f32_16x16x32_bf16 v[4:7], v[100:103], v[96:99], v[4:7]
	v_mfma_f32_16x16x32_bf16 v[0:3], v[100:103], v[104:107], v[0:3]
	v_mfma_f32_16x16x32_bf16 v[52:55], v[100:103], v[108:111], v[52:55]
	v_mfma_f32_16x16x32_bf16 v[44:47], v[100:103], v[112:115], v[44:47]
	s_cbranch_scc0 .LBB0_1702
; DI unsigned pack2(float a, float b) { v2f f = {a, b}; return __builtin_bit_cast(unsigned, __builtin_convertvector(f, v2bf)); }
; DI float silu_f(float v) { return v / (1.f + fexp(-v)); }
;   DI u32x2 pack(int, int, float a, float b, float c, float d, float&) const { u32x2 v; v.x = pack2(a, b); v.y = pack2(c, d); return v; }
; template <class ARow, class Epi>
; DI void gemm_tile(const ARow& arow, long a_kstride, const u16* __restrict__ Bt, long ldb, int K, int m0, int n0,
;                   const Epi& epi, char* smem) {
;     ...
;   const int nh = n0 + wn * 64;
;   if (epi.packed(nh)) {
; #pragma unroll
;     for (int mi = 0; mi < 4; ++mi) {
;       const int m = m0 + wm * 64 + mi * 16 + fr;
;       float ss = 0.f;
;       u32x2 pk[4];
; #pragma unroll
;       for (int ni = 0; ni < 4; ++ni) pk[ni] = epi.pack(m, nh + ni * 16 + fq * 4, acc[ni][mi][0], acc[ni][mi][1], acc[ni][mi][2], acc[ni][mi][3], ss);
;       epi.finish16(m, nh, ss);
;       u16* rp = epi.rowp(m) + nh;
; #pragma unroll
;       for (int pp = 0; pp < 2; ++pp) {
;         u32x2 a = pk[2 * pp], b = pk[2 * pp + 1];
;         const u32x2 rx = __builtin_amdgcn_permlane16_swap(a.x, b.x, false, false);
;         const u32x2 ry = __builtin_amdgcn_permlane16_swap(a.y, b.y, false, false);
;         const int nst = (fq & 1) ? ((2 * pp + 1) * 16 + (fq - 1) * 4) : ((2 * pp) * 16 + fq * 4);
;         *(u32x4*)(rp + nst) = (u32x4){rx[0], ry[0], rx[1], ry[1]};
;       }
;     }
;   DI u32x2 pack(int m, int n, float a, float b, float c, float d, float& ss) const {
;     if (n < q_end) { a *= qscale; b *= qscale; c *= qscale; d *= qscale; }
;     else if (n >= z_start) { a = silu_f(a); b = silu_f(b); c = silu_f(c); d = silu_f(d); }
;     ss += a * a + b * b + c * c + d * d;
;     u32x2 v; v.x = pack2(a, b); v.y = pack2(c, d);
;     return v;
;   }
	v_add_u32_e32 v106, v89, v87
	ds_read_b128 v[66:69], v106 offset:49152
	v_add_u32_e32 v87, v88, v87
	ds_read_b128 v[70:73], v87 offset:32768
	ds_read_b128 v[74:77], v87 offset:34816
	ds_read_b128 v[78:81], v87 offset:36864
	ds_read_b128 v[90:93], v87 offset:38912
	v_add_u32_e32 v114, v89, v86
	s_waitcnt lgkmcnt(3)
	v_mfma_f32_16x16x32_bf16 v[60:63], v[66:69], v[70:73], v[60:63]
	s_waitcnt lgkmcnt(2)
	v_mfma_f32_16x16x32_bf16 v[56:59], v[66:69], v[74:77], v[56:59]
	s_waitcnt lgkmcnt(1)
	v_mfma_f32_16x16x32_bf16 v[48:51], v[66:69], v[78:81], v[48:51]
	s_waitcnt lgkmcnt(0)
	v_mfma_f32_16x16x32_bf16 v[40:43], v[66:69], v[90:93], v[40:43]
	ds_read_b128 v[66:69], v106 offset:51200
	s_waitcnt lgkmcnt(0)
	v_mfma_f32_16x16x32_bf16 v[36:39], v[66:69], v[70:73], v[36:39]
	v_mfma_f32_16x16x32_bf16 v[32:35], v[66:69], v[74:77], v[32:35]
	v_mfma_f32_16x16x32_bf16 v[94:97], v[66:69], v[78:81], v[28:31]
	v_mfma_f32_16x16x32_bf16 v[66:69], v[66:69], v[90:93], v[24:27]
	s_nop 2
	ds_read_b128 v[24:27], v106 offset:53248
	s_waitcnt lgkmcnt(0)
	v_mfma_f32_16x16x32_bf16 v[102:105], v[24:27], v[90:93], v[8:11]
	s_nop 2
	ds_read_b128 v[8:11], v106 offset:55296
	v_mfma_f32_16x16x32_bf16 v[20:23], v[24:27], v[70:73], v[20:23]
	s_waitcnt lgkmcnt(0)
	v_mfma_f32_16x16x32_bf16 v[70:73], v[8:11], v[70:73], v[4:7]
	s_nop 2
	ds_read_b128 v[4:7], v114 offset:49152
	v_mfma_f32_16x16x32_bf16 v[98:101], v[24:27], v[78:81], v[12:15]
	s_nop 2
	v_add_u32_e32 v12, v88, v86
	v_mfma_f32_16x16x32_bf16 v[16:19], v[24:27], v[74:77], v[16:19]
	ds_read_b128 v[86:89], v12 offset:32768
	ds_read_b128 v[106:109], v12 offset:36864
	ds_read_b128 v[110:113], v12 offset:38912
	v_mfma_f32_16x16x32_bf16 v[0:3], v[8:11], v[74:77], v[0:3]
	v_mfma_f32_16x16x32_bf16 v[74:77], v[8:11], v[78:81], v[52:55]
	v_mfma_f32_16x16x32_bf16 v[78:81], v[8:11], v[90:93], v[44:47]
	ds_read_b128 v[90:93], v12 offset:34816
	s_waitcnt lgkmcnt(3)
	v_mfma_f32_16x16x32_bf16 v[60:63], v[4:7], v[86:89], v[60:63]
	s_waitcnt lgkmcnt(0)
	v_mfma_f32_16x16x32_bf16 v[44:47], v[4:7], v[90:93], v[56:59]
	v_mfma_f32_16x16x32_bf16 v[28:31], v[4:7], v[106:109], v[48:51]
	v_mfma_f32_16x16x32_bf16 v[12:15], v[4:7], v[110:113], v[40:43]
	ds_read_b128 v[4:7], v114 offset:51200
	s_waitcnt lgkmcnt(0)
	v_mfma_f32_16x16x32_bf16 v[56:59], v[4:7], v[86:89], v[36:39]
	v_mfma_f32_16x16x32_bf16 v[40:43], v[4:7], v[90:93], v[32:35]
	v_mfma_f32_16x16x32_bf16 v[24:27], v[4:7], v[106:109], v[94:97]
	v_mfma_f32_16x16x32_bf16 v[8:11], v[4:7], v[110:113], v[66:69]
	ds_read_b128 v[4:7], v114 offset:53248
	s_nop 0
	ds_read_b128 v[94:97], v114 offset:55296
	s_waitcnt vmcnt(0)
	s_waitcnt lgkmcnt(0)
	v_mfma_f32_16x16x32_bf16 v[32:35], v[94:97], v[90:93], v[0:3]
	s_nop 2
	v_or_b32_e32 v0, s0, v64
	v_lshl_or_b32 v66, v84, 6, s35
	v_lshlrev_b32_e32 v68, 2, v83
	v_mfma_f32_16x16x32_bf16 v[52:55], v[4:7], v[86:89], v[20:23]
	v_cmp_lt_i32_e32 vcc, s30, v66
	v_or_b32_e32 v64, v66, v68
	v_mfma_f32_16x16x32_bf16 v[36:39], v[4:7], v[90:93], v[16:19]
	s_barrier
	v_mfma_f32_16x16x32_bf16 v[20:23], v[4:7], v[106:109], v[98:101]
	v_mfma_f32_16x16x32_bf16 v[4:7], v[4:7], v[110:113], v[102:105]
	v_mfma_f32_16x16x32_bf16 v[48:51], v[94:97], v[86:89], v[70:73]
	v_mfma_f32_16x16x32_bf16 v[16:19], v[94:97], v[106:109], v[74:77]
	s_nop 2
	v_lshl_add_u32 v74, v85, 6, v0
	v_mfma_f32_16x16x32_bf16 v[0:3], v[94:97], v[110:113], v[78:81]
	s_nop 7
	v_readfirstlane_b32 s99, v66
	s_cmpk_ge_u32 s99, 0x300
	s_cbranch_scc0 .Lfe_C_not_plain
	s_cmpk_lt_u32 s99, 0xa00
	s_cbranch_scc0 .Lfe_C_not_plain
	s_load_dwordx2 s[100:101], s[56:57], 0x130
	v_and_b32_e32 v152, 1, v83
	v_mul_u32_u24_e32 v152, 12, v152
	v_lshl_add_u32 v152, v83, 2, v152
	v_add_u32_e32 v152, v152, v66
	v_mul_u32_u24_e32 v153, 0xe00, v74
	v_add_u32_e32 v152, v152, v153
	v_lshlrev_b32_e32 v152, 1, v152
	v_add_u32_e32 v153, 0x1c000, v152
	v_add_u32_e32 v154, 0x38000, v152
	v_add_u32_e32 v155, 0x54000, v152
	s_nop 3
	v_cvt_pk_bf16_f32 v120, v60, v61
	v_cvt_pk_bf16_f32 v121, v62, v63
	v_cvt_pk_bf16_f32 v122, v56, v57
	v_cvt_pk_bf16_f32 v123, v58, v59
	v_cvt_pk_bf16_f32 v124, v52, v53
	v_cvt_pk_bf16_f32 v125, v54, v55
	v_cvt_pk_bf16_f32 v126, v48, v49
	v_cvt_pk_bf16_f32 v127, v50, v51
	s_nop 1
	v_permlane16_swap_b32_e32 v120, v122
	v_permlane16_swap_b32_e32 v121, v123
	v_permlane16_swap_b32_e32 v124, v126
	v_permlane16_swap_b32_e32 v125, v127
	s_waitcnt lgkmcnt(0)
	global_store_dwordx4 v152, v[120:123], s[100:101]
	global_store_dwordx4 v152, v[124:127], s[100:101] offset:64
	v_cvt_pk_bf16_f32 v128, v44, v45
	v_cvt_pk_bf16_f32 v129, v46, v47
	v_cvt_pk_bf16_f32 v130, v40, v41
	v_cvt_pk_bf16_f32 v131, v42, v43
	v_cvt_pk_bf16_f32 v132, v36, v37
	v_cvt_pk_bf16_f32 v133, v38, v39
	v_cvt_pk_bf16_f32 v134, v32, v33
	v_cvt_pk_bf16_f32 v135, v34, v35
	s_nop 1
	v_permlane16_swap_b32_e32 v128, v130
	v_permlane16_swap_b32_e32 v129, v131
	v_permlane16_swap_b32_e32 v132, v134
	v_permlane16_swap_b32_e32 v133, v135
	global_store_dwordx4 v153, v[128:131], s[100:101]
	global_store_dwordx4 v153, v[132:135], s[100:101] offset:64
	v_cvt_pk_bf16_f32 v136, v28, v29
	v_cvt_pk_bf16_f32 v137, v30, v31
	v_cvt_pk_bf16_f32 v138, v24, v25
	v_cvt_pk_bf16_f32 v139, v26, v27
	v_cvt_pk_bf16_f32 v140, v20, v21
	v_cvt_pk_bf16_f32 v141, v22, v23
	v_cvt_pk_bf16_f32 v142, v16, v17
	v_cvt_pk_bf16_f32 v143, v18, v19
	s_nop 1
	v_permlane16_swap_b32_e32 v136, v138
	v_permlane16_swap_b32_e32 v137, v139
	v_permlane16_swap_b32_e32 v140, v142
	v_permlane16_swap_b32_e32 v141, v143
	global_store_dwordx4 v154, v[136:139], s[100:101]
	global_store_dwordx4 v154, v[140:143], s[100:101] offset:64
	v_cvt_pk_bf16_f32 v144, v12, v13
	v_cvt_pk_bf16_f32 v145, v14, v15
	v_cvt_pk_bf16_f32 v146, v8, v9
	v_cvt_pk_bf16_f32 v147, v10, v11
	v_cvt_pk_bf16_f32 v148, v4, v5
	v_cvt_pk_bf16_f32 v149, v6, v7
	v_cvt_pk_bf16_f32 v150, v0, v1
	v_cvt_pk_bf16_f32 v151, v2, v3
	s_nop 1
	v_permlane16_swap_b32_e32 v144, v146
	v_permlane16_swap_b32_e32 v145, v147
	v_permlane16_swap_b32_e32 v148, v150
	v_permlane16_swap_b32_e32 v149, v151
	global_store_dwordx4 v155, v[144:147], s[100:101]
	global_store_dwordx4 v155, v[148:151], s[100:101] offset:64
	s_branch .Lfe_join_C
; DI unsigned pack2(float a, float b) { v2f f = {a, b}; return __builtin_bit_cast(unsigned, __builtin_convertvector(f, v2bf)); }
; DI float silu_f(float v) { return v / (1.f + fexp(-v)); }
;   DI u32x2 pack(int, int, float a, float b, float c, float d, float&) const { u32x2 v; v.x = pack2(a, b); v.y = pack2(c, d); return v; }
; template <class ARow, class Epi>
; DI void gemm_tile(const ARow& arow, long a_kstride, const u16* __restrict__ Bt, long ldb, int K, int m0, int n0,
;                   const Epi& epi, char* smem) {
;     ...
;   const int nh = n0 + wn * 64;
;   if (epi.packed(nh)) {
; #pragma unroll
;     for (int mi = 0; mi < 4; ++mi) {
;       const int m = m0 + wm * 64 + mi * 16 + fr;
;       float ss = 0.f;
;       u32x2 pk[4];
; #pragma unroll
;       for (int ni = 0; ni < 4; ++ni) pk[ni] = epi.pack(m, nh + ni * 16 + fq * 4, acc[ni][mi][0], acc[ni][mi][1], acc[ni][mi][2], acc[ni][mi][3], ss);
;       epi.finish16(m, nh, ss);
;       u16* rp = epi.rowp(m) + nh;
; #pragma unroll
;       for (int pp = 0; pp < 2; ++pp) {
;         u32x2 a = pk[2 * pp], b = pk[2 * pp + 1];
;         const u32x2 rx = __builtin_amdgcn_permlane16_swap(a.x, b.x, false, false);
;         const u32x2 ry = __builtin_amdgcn_permlane16_swap(a.y, b.y, false, false);
;         const int nst = (fq & 1) ? ((2 * pp + 1) * 16 + (fq - 1) * 4) : ((2 * pp) * 16 + fq * 4);
;         *(u32x4*)(rp + nst) = (u32x4){rx[0], ry[0], rx[1], ry[1]};
;       }
;     }
;   DI u32x2 pack(int m, int n, float a, float b, float c, float d, float& ss) const {
;     if (n < q_end) { a *= qscale; b *= qscale; c *= qscale; d *= qscale; }
;     else if (n >= z_start) { a = silu_f(a); b = silu_f(b); c = silu_f(c); d = silu_f(d); }
;     ss += a * a + b * b + c * c + d * d;
;     u32x2 v; v.x = pack2(a, b); v.y = pack2(c, d);
;     return v;
;   }
.Lfe_C_not_plain:
	s_cmpk_lt_u32 s99, 0x300
	s_cbranch_scc0 .Lfe_C_not_q
	s_load_dwordx2 s[100:101], s[56:57], 0x130
	v_and_b32_e32 v152, 1, v83
	v_mul_u32_u24_e32 v152, 12, v152
	v_lshl_add_u32 v152, v83, 2, v152
	v_add_u32_e32 v152, v152, v66
	v_mul_u32_u24_e32 v153, 0xe00, v74
	v_add_u32_e32 v152, v152, v153
	v_lshlrev_b32_e32 v152, 1, v152
	v_add_u32_e32 v153, 0x1c000, v152
	v_add_u32_e32 v154, 0x38000, v152
	v_add_u32_e32 v155, 0x54000, v152
	s_mov_b32 s98, 0x3e38aa3b
	s_nop 3
	v_pk_mul_f32 v[60:61], v[60:61], s[98:99] op_sel_hi:[1,0]
	v_pk_mul_f32 v[62:63], v[62:63], s[98:99] op_sel_hi:[1,0]
	v_pk_mul_f32 v[56:57], v[56:57], s[98:99] op_sel_hi:[1,0]
	v_pk_mul_f32 v[58:59], v[58:59], s[98:99] op_sel_hi:[1,0]
	v_pk_mul_f32 v[52:53], v[52:53], s[98:99] op_sel_hi:[1,0]
	v_pk_mul_f32 v[54:55], v[54:55], s[98:99] op_sel_hi:[1,0]
	v_pk_mul_f32 v[48:49], v[48:49], s[98:99] op_sel_hi:[1,0]
	v_pk_mul_f32 v[50:51], v[50:51], s[98:99] op_sel_hi:[1,0]
	v_cvt_pk_bf16_f32 v120, v60, v61
	v_cvt_pk_bf16_f32 v121, v62, v63
	v_cvt_pk_bf16_f32 v122, v56, v57
	v_cvt_pk_bf16_f32 v123, v58, v59
	v_cvt_pk_bf16_f32 v124, v52, v53
	v_cvt_pk_bf16_f32 v125, v54, v55
	v_cvt_pk_bf16_f32 v126, v48, v49
	v_cvt_pk_bf16_f32 v127, v50, v51
	s_nop 1
	v_permlane16_swap_b32_e32 v120, v122
	v_permlane16_swap_b32_e32 v121, v123
	v_permlane16_swap_b32_e32 v124, v126
	v_permlane16_swap_b32_e32 v125, v127
	s_waitcnt lgkmcnt(0)
	global_store_dwordx4 v152, v[120:123], s[100:101]
	global_store_dwordx4 v152, v[124:127], s[100:101] offset:64
	v_pk_mul_f32 v[44:45], v[44:45], s[98:99] op_sel_hi:[1,0]
	v_pk_mul_f32 v[46:47], v[46:47], s[98:99] op_sel_hi:[1,0]
	v_pk_mul_f32 v[40:41], v[40:41], s[98:99] op_sel_hi:[1,0]
	v_pk_mul_f32 v[42:43], v[42:43], s[98:99] op_sel_hi:[1,0]
	v_pk_mul_f32 v[36:37], v[36:37], s[98:99] op_sel_hi:[1,0]
	v_pk_mul_f32 v[38:39], v[38:39], s[98:99] op_sel_hi:[1,0]
	v_pk_mul_f32 v[32:33], v[32:33], s[98:99] op_sel_hi:[1,0]
	v_pk_mul_f32 v[34:35], v[34:35], s[98:99] op_sel_hi:[1,0]
	v_cvt_pk_bf16_f32 v128, v44, v45
	v_cvt_pk_bf16_f32 v129, v46, v47
	v_cvt_pk_bf16_f32 v130, v40, v41
	v_cvt_pk_bf16_f32 v131, v42, v43
	v_cvt_pk_bf16_f32 v132, v36, v37
	v_cvt_pk_bf16_f32 v133, v38, v39
	v_cvt_pk_bf16_f32 v134, v32, v33
	v_cvt_pk_bf16_f32 v135, v34, v35
	s_nop 1
	v_permlane16_swap_b32_e32 v128, v130
	v_permlane16_swap_b32_e32 v129, v131
	v_permlane16_swap_b32_e32 v132, v134
	v_permlane16_swap_b32_e32 v133, v135
	global_store_dwordx4 v153, v[128:131], s[100:101]
	global_store_dwordx4 v153, v[132:135], s[100:101] offset:64
	v_pk_mul_f32 v[28:29], v[28:29], s[98:99] op_sel_hi:[1,0]
	v_pk_mul_f32 v[30:31], v[30:31], s[98:99] op_sel_hi:[1,0]
	v_pk_mul_f32 v[24:25], v[24:25], s[98:99] op_sel_hi:[1,0]
	v_pk_mul_f32 v[26:27], v[26:27], s[98:99] op_sel_hi:[1,0]
	v_pk_mul_f32 v[20:21], v[20:21], s[98:99] op_sel_hi:[1,0]
	v_pk_mul_f32 v[22:23], v[22:23], s[98:99] op_sel_hi:[1,0]
	v_pk_mul_f32 v[16:17], v[16:17], s[98:99] op_sel_hi:[1,0]
	v_pk_mul_f32 v[18:19], v[18:19], s[98:99] op_sel_hi:[1,0]
	v_cvt_pk_bf16_f32 v136, v28, v29
	v_cvt_pk_bf16_f32 v137, v30, v31
	v_cvt_pk_bf16_f32 v138, v24, v25
	v_cvt_pk_bf16_f32 v139, v26, v27
	v_cvt_pk_bf16_f32 v140, v20, v21
	v_cvt_pk_bf16_f32 v141, v22, v23
	v_cvt_pk_bf16_f32 v142, v16, v17
	v_cvt_pk_bf16_f32 v143, v18, v19
	s_nop 1
	v_permlane16_swap_b32_e32 v136, v138
	v_permlane16_swap_b32_e32 v137, v139
	v_permlane16_swap_b32_e32 v140, v142
	v_permlane16_swap_b32_e32 v141, v143
	global_store_dwordx4 v154, v[136:139], s[100:101]
	global_store_dwordx4 v154, v[140:143], s[100:101] offset:64
	v_pk_mul_f32 v[12:13], v[12:13], s[98:99] op_sel_hi:[1,0]
	v_pk_mul_f32 v[14:15], v[14:15], s[98:99] op_sel_hi:[1,0]
	v_pk_mul_f32 v[8:9], v[8:9], s[98:99] op_sel_hi:[1,0]
	v_pk_mul_f32 v[10:11], v[10:11], s[98:99] op_sel_hi:[1,0]
	v_pk_mul_f32 v[4:5], v[4:5], s[98:99] op_sel_hi:[1,0]
	v_pk_mul_f32 v[6:7], v[6:7], s[98:99] op_sel_hi:[1,0]
	v_pk_mul_f32 v[0:1], v[0:1], s[98:99] op_sel_hi:[1,0]
	v_pk_mul_f32 v[2:3], v[2:3], s[98:99] op_sel_hi:[1,0]
	v_cvt_pk_bf16_f32 v144, v12, v13
	v_cvt_pk_bf16_f32 v145, v14, v15
	v_cvt_pk_bf16_f32 v146, v8, v9
	v_cvt_pk_bf16_f32 v147, v10, v11
	v_cvt_pk_bf16_f32 v148, v4, v5
	v_cvt_pk_bf16_f32 v149, v6, v7
	v_cvt_pk_bf16_f32 v150, v0, v1
	v_cvt_pk_bf16_f32 v151, v2, v3
	s_nop 1
	v_permlane16_swap_b32_e32 v144, v146
	v_permlane16_swap_b32_e32 v145, v147
	v_permlane16_swap_b32_e32 v148, v150
	v_permlane16_swap_b32_e32 v149, v151
	global_store_dwordx4 v155, v[144:147], s[100:101]
	global_store_dwordx4 v155, v[148:151], s[100:101] offset:64
	s_branch .Lfe_join_C
; DI unsigned pack2(float a, float b) { v2f f = {a, b}; return __builtin_bit_cast(unsigned, __builtin_convertvector(f, v2bf)); }
; DI float silu_f(float v) { return v / (1.f + fexp(-v)); }
;   DI u32x2 pack(int, int, float a, float b, float c, float d, float&) const { u32x2 v; v.x = pack2(a, b); v.y = pack2(c, d); return v; }
; template <class ARow, class Epi>
; DI void gemm_tile(const ARow& arow, long a_kstride, const u16* __restrict__ Bt, long ldb, int K, int m0, int n0,
;                   const Epi& epi, char* smem) {
;     ...
;   const int nh = n0 + wn * 64;
;   if (epi.packed(nh)) {
; #pragma unroll
;     for (int mi = 0; mi < 4; ++mi) {
;       const int m = m0 + wm * 64 + mi * 16 + fr;
;       float ss = 0.f;
;       u32x2 pk[4];
; #pragma unroll
;       for (int ni = 0; ni < 4; ++ni) pk[ni] = epi.pack(m, nh + ni * 16 + fq * 4, acc[ni][mi][0], acc[ni][mi][1], acc[ni][mi][2], acc[ni][mi][3], ss);
;       epi.finish16(m, nh, ss);
;       u16* rp = epi.rowp(m) + nh;
; #pragma unroll
;       for (int pp = 0; pp < 2; ++pp) {
;         u32x2 a = pk[2 * pp], b = pk[2 * pp + 1];
;         const u32x2 rx = __builtin_amdgcn_permlane16_swap(a.x, b.x, false, false);
;         const u32x2 ry = __builtin_amdgcn_permlane16_swap(a.y, b.y, false, false);
;         const int nst = (fq & 1) ? ((2 * pp + 1) * 16 + (fq - 1) * 4) : ((2 * pp) * 16 + fq * 4);
;         *(u32x4*)(rp + nst) = (u32x4){rx[0], ry[0], rx[1], ry[1]};
;       }
;     }
;   DI u32x2 pack(int m, int n, float a, float b, float c, float d, float& ss) const {
;     if (n < q_end) { a *= qscale; b *= qscale; c *= qscale; d *= qscale; }
;     else if (n >= z_start) { a = silu_f(a); b = silu_f(b); c = silu_f(c); d = silu_f(d); }
;     ss += a * a + b * b + c * c + d * d;
;     u32x2 v; v.x = pack2(a, b); v.y = pack2(c, d);
;     return v;
;   }
.Lfe_C_not_q:
	s_cmpk_ge_u32 s99, 0xa00
	s_cbranch_scc0 .Lfe_C_not_z
	s_cmpk_lt_u32 s99, 0xe00
	s_cbranch_scc0 .Lfe_C_not_z
	s_load_dwordx2 s[100:101], s[56:57], 0x130
	v_and_b32_e32 v152, 1, v83
	v_mul_u32_u24_e32 v152, 12, v152
	v_lshl_add_u32 v152, v83, 2, v152
	v_add_u32_e32 v152, v152, v66
	v_mul_u32_u24_e32 v153, 0xe00, v74
	v_add_u32_e32 v152, v152, v153
	v_lshlrev_b32_e32 v152, 1, v152
	v_add_u32_e32 v153, 0x1c000, v152
	v_add_u32_e32 v154, 0x38000, v152
	v_add_u32_e32 v155, 0x54000, v152
	s_nop 3
	v_mul_f32_e32 v156, 0xbfb8aa3b, v60
	v_mul_f32_e32 v157, 0xbfb8aa3b, v61
	v_mul_f32_e32 v158, 0xbfb8aa3b, v62
	v_mul_f32_e32 v159, 0xbfb8aa3b, v63
	v_mul_f32_e32 v160, 0xbfb8aa3b, v56
	v_mul_f32_e32 v161, 0xbfb8aa3b, v57
	v_mul_f32_e32 v162, 0xbfb8aa3b, v58
	v_mul_f32_e32 v163, 0xbfb8aa3b, v59
	v_exp_f32_e32 v156, v156
	v_exp_f32_e32 v157, v157
	v_exp_f32_e32 v158, v158
	v_exp_f32_e32 v159, v159
	v_exp_f32_e32 v160, v160
	v_exp_f32_e32 v161, v161
	v_exp_f32_e32 v162, v162
	v_exp_f32_e32 v163, v163
	v_add_f32_e32 v156, 1.0, v156
	v_add_f32_e32 v157, 1.0, v157
	v_add_f32_e32 v158, 1.0, v158
	v_add_f32_e32 v159, 1.0, v159
	v_add_f32_e32 v160, 1.0, v160
	v_add_f32_e32 v161, 1.0, v161
	v_add_f32_e32 v162, 1.0, v162
	v_add_f32_e32 v163, 1.0, v163
	v_rcp_f32_e32 v156, v156
	v_rcp_f32_e32 v157, v157
	v_rcp_f32_e32 v158, v158
	v_rcp_f32_e32 v159, v159
	v_rcp_f32_e32 v160, v160
	v_rcp_f32_e32 v161, v161
	v_rcp_f32_e32 v162, v162
	v_rcp_f32_e32 v163, v163
	v_mul_f32_e32 v60, v60, v156
	v_mul_f32_e32 v61, v61, v157
	v_mul_f32_e32 v62, v62, v158
	v_mul_f32_e32 v63, v63, v159
	v_mul_f32_e32 v56, v56, v160
	v_mul_f32_e32 v57, v57, v161
	v_mul_f32_e32 v58, v58, v162
	v_mul_f32_e32 v59, v59, v163
	v_mul_f32_e32 v156, 0xbfb8aa3b, v52
	v_mul_f32_e32 v157, 0xbfb8aa3b, v53
	v_mul_f32_e32 v158, 0xbfb8aa3b, v54
	v_mul_f32_e32 v159, 0xbfb8aa3b, v55
	v_mul_f32_e32 v160, 0xbfb8aa3b, v48
	v_mul_f32_e32 v161, 0xbfb8aa3b, v49
	v_mul_f32_e32 v162, 0xbfb8aa3b, v50
	v_mul_f32_e32 v163, 0xbfb8aa3b, v51
	v_exp_f32_e32 v156, v156
	v_exp_f32_e32 v157, v157
	v_exp_f32_e32 v158, v158
	v_exp_f32_e32 v159, v159
	v_exp_f32_e32 v160, v160
	v_exp_f32_e32 v161, v161
	v_exp_f32_e32 v162, v162
	v_exp_f32_e32 v163, v163
	v_add_f32_e32 v156, 1.0, v156
	v_add_f32_e32 v157, 1.0, v157
	v_add_f32_e32 v158, 1.0, v158
	v_add_f32_e32 v159, 1.0, v159
	v_add_f32_e32 v160, 1.0, v160
	v_add_f32_e32 v161, 1.0, v161
	v_add_f32_e32 v162, 1.0, v162
	v_add_f32_e32 v163, 1.0, v163
	v_rcp_f32_e32 v156, v156
	v_rcp_f32_e32 v157, v157
	v_rcp_f32_e32 v158, v158
	v_rcp_f32_e32 v159, v159
	v_rcp_f32_e32 v160, v160
	v_rcp_f32_e32 v161, v161
	v_rcp_f32_e32 v162, v162
	v_rcp_f32_e32 v163, v163
	v_mul_f32_e32 v52, v52, v156
	v_mul_f32_e32 v53, v53, v157
	v_mul_f32_e32 v54, v54, v158
	v_mul_f32_e32 v55, v55, v159
	v_mul_f32_e32 v48, v48, v160
	v_mul_f32_e32 v49, v49, v161
	v_mul_f32_e32 v50, v50, v162
	v_mul_f32_e32 v51, v51, v163
	v_cvt_pk_bf16_f32 v120, v60, v61
	v_cvt_pk_bf16_f32 v121, v62, v63
	v_cvt_pk_bf16_f32 v122, v56, v57
	v_cvt_pk_bf16_f32 v123, v58, v59
	v_cvt_pk_bf16_f32 v124, v52, v53
	v_cvt_pk_bf16_f32 v125, v54, v55
	v_cvt_pk_bf16_f32 v126, v48, v49
	v_cvt_pk_bf16_f32 v127, v50, v51
	s_nop 1
	v_permlane16_swap_b32_e32 v120, v122
	v_permlane16_swap_b32_e32 v121, v123
	v_permlane16_swap_b32_e32 v124, v126
	v_permlane16_swap_b32_e32 v125, v127
	s_waitcnt lgkmcnt(0)
	global_store_dwordx4 v152, v[120:123], s[100:101]
	global_store_dwordx4 v152, v[124:127], s[100:101] offset:64
	v_mul_f32_e32 v156, 0xbfb8aa3b, v44
	v_mul_f32_e32 v157, 0xbfb8aa3b, v45
	v_mul_f32_e32 v158, 0xbfb8aa3b, v46
	v_mul_f32_e32 v159, 0xbfb8aa3b, v47
	v_mul_f32_e32 v160, 0xbfb8aa3b, v40
	v_mul_f32_e32 v161, 0xbfb8aa3b, v41
	v_mul_f32_e32 v162, 0xbfb8aa3b, v42
	v_mul_f32_e32 v163, 0xbfb8aa3b, v43
	v_exp_f32_e32 v156, v156
	v_exp_f32_e32 v157, v157
	v_exp_f32_e32 v158, v158
	v_exp_f32_e32 v159, v159
	v_exp_f32_e32 v160, v160
	v_exp_f32_e32 v161, v161
	v_exp_f32_e32 v162, v162
	v_exp_f32_e32 v163, v163
	v_add_f32_e32 v156, 1.0, v156
	v_add_f32_e32 v157, 1.0, v157
	v_add_f32_e32 v158, 1.0, v158
	v_add_f32_e32 v159, 1.0, v159
	v_add_f32_e32 v160, 1.0, v160
	v_add_f32_e32 v161, 1.0, v161
	v_add_f32_e32 v162, 1.0, v162
	v_add_f32_e32 v163, 1.0, v163
	v_rcp_f32_e32 v156, v156
	v_rcp_f32_e32 v157, v157
	v_rcp_f32_e32 v158, v158
	v_rcp_f32_e32 v159, v159
	v_rcp_f32_e32 v160, v160
	v_rcp_f32_e32 v161, v161
	v_rcp_f32_e32 v162, v162
	v_rcp_f32_e32 v163, v163
	v_mul_f32_e32 v44, v44, v156
	v_mul_f32_e32 v45, v45, v157
	v_mul_f32_e32 v46, v46, v158
	v_mul_f32_e32 v47, v47, v159
	v_mul_f32_e32 v40, v40, v160
	v_mul_f32_e32 v41, v41, v161
	v_mul_f32_e32 v42, v42, v162
	v_mul_f32_e32 v43, v43, v163
	v_mul_f32_e32 v156, 0xbfb8aa3b, v36
	v_mul_f32_e32 v157, 0xbfb8aa3b, v37
	v_mul_f32_e32 v158, 0xbfb8aa3b, v38
	v_mul_f32_e32 v159, 0xbfb8aa3b, v39
	v_mul_f32_e32 v160, 0xbfb8aa3b, v32
	v_mul_f32_e32 v161, 0xbfb8aa3b, v33
	v_mul_f32_e32 v162, 0xbfb8aa3b, v34
	v_mul_f32_e32 v163, 0xbfb8aa3b, v35
	v_exp_f32_e32 v156, v156
	v_exp_f32_e32 v157, v157
	v_exp_f32_e32 v158, v158
	v_exp_f32_e32 v159, v159
	v_exp_f32_e32 v160, v160
	v_exp_f32_e32 v161, v161
	v_exp_f32_e32 v162, v162
	v_exp_f32_e32 v163, v163
	v_add_f32_e32 v156, 1.0, v156
	v_add_f32_e32 v157, 1.0, v157
	v_add_f32_e32 v158, 1.0, v158
	v_add_f32_e32 v159, 1.0, v159
	v_add_f32_e32 v160, 1.0, v160
	v_add_f32_e32 v161, 1.0, v161
	v_add_f32_e32 v162, 1.0, v162
	v_add_f32_e32 v163, 1.0, v163
	v_rcp_f32_e32 v156, v156
	v_rcp_f32_e32 v157, v157
	v_rcp_f32_e32 v158, v158
	v_rcp_f32_e32 v159, v159
	v_rcp_f32_e32 v160, v160
	v_rcp_f32_e32 v161, v161
	v_rcp_f32_e32 v162, v162
	v_rcp_f32_e32 v163, v163
; DI unsigned pack2(float a, float b) { v2f f = {a, b}; return __builtin_bit_cast(unsigned, __builtin_convertvector(f, v2bf)); }
; DI float silu_f(float v) { return v / (1.f + fexp(-v)); }
;   DI u32x2 pack(int, int, float a, float b, float c, float d, float&) const { u32x2 v; v.x = pack2(a, b); v.y = pack2(c, d); return v; }
; template <class ARow, class Epi>
; DI void gemm_tile(const ARow& arow, long a_kstride, const u16* __restrict__ Bt, long ldb, int K, int m0, int n0,
;                   const Epi& epi, char* smem) {
;     ...
;   const int nh = n0 + wn * 64;
;   if (epi.packed(nh)) {
; #pragma unroll
;     for (int mi = 0; mi < 4; ++mi) {
;       const int m = m0 + wm * 64 + mi * 16 + fr;
;       float ss = 0.f;
;       u32x2 pk[4];
; #pragma unroll
;       for (int ni = 0; ni < 4; ++ni) pk[ni] = epi.pack(m, nh + ni * 16 + fq * 4, acc[ni][mi][0], acc[ni][mi][1], acc[ni][mi][2], acc[ni][mi][3], ss);
;       epi.finish16(m, nh, ss);
;       u16* rp = epi.rowp(m) + nh;
; #pragma unroll
;       for (int pp = 0; pp < 2; ++pp) {
;         u32x2 a = pk[2 * pp], b = pk[2 * pp + 1];
;         const u32x2 rx = __builtin_amdgcn_permlane16_swap(a.x, b.x, false, false);
;         const u32x2 ry = __builtin_amdgcn_permlane16_swap(a.y, b.y, false, false);
;         const int nst = (fq & 1) ? ((2 * pp + 1) * 16 + (fq - 1) * 4) : ((2 * pp) * 16 + fq * 4);
;         *(u32x4*)(rp + nst) = (u32x4){rx[0], ry[0], rx[1], ry[1]};
;       }
;     }
;   DI u32x2 pack(int m, int n, float a, float b, float c, float d, float& ss) const {
;     if (n < q_end) { a *= qscale; b *= qscale; c *= qscale; d *= qscale; }
;     else if (n >= z_start) { a = silu_f(a); b = silu_f(b); c = silu_f(c); d = silu_f(d); }
;     ss += a * a + b * b + c * c + d * d;
;     u32x2 v; v.x = pack2(a, b); v.y = pack2(c, d);
;     return v;
;   }
	v_mul_f32_e32 v36, v36, v156
	v_mul_f32_e32 v37, v37, v157
	v_mul_f32_e32 v38, v38, v158
	v_mul_f32_e32 v39, v39, v159
	v_mul_f32_e32 v32, v32, v160
	v_mul_f32_e32 v33, v33, v161
	v_mul_f32_e32 v34, v34, v162
	v_mul_f32_e32 v35, v35, v163
	v_cvt_pk_bf16_f32 v128, v44, v45
	v_cvt_pk_bf16_f32 v129, v46, v47
	v_cvt_pk_bf16_f32 v130, v40, v41
	v_cvt_pk_bf16_f32 v131, v42, v43
	v_cvt_pk_bf16_f32 v132, v36, v37
	v_cvt_pk_bf16_f32 v133, v38, v39
	v_cvt_pk_bf16_f32 v134, v32, v33
	v_cvt_pk_bf16_f32 v135, v34, v35
	s_nop 1
	v_permlane16_swap_b32_e32 v128, v130
	v_permlane16_swap_b32_e32 v129, v131
	v_permlane16_swap_b32_e32 v132, v134
	v_permlane16_swap_b32_e32 v133, v135
	global_store_dwordx4 v153, v[128:131], s[100:101]
	global_store_dwordx4 v153, v[132:135], s[100:101] offset:64
	v_mul_f32_e32 v156, 0xbfb8aa3b, v28
	v_mul_f32_e32 v157, 0xbfb8aa3b, v29
	v_mul_f32_e32 v158, 0xbfb8aa3b, v30
	v_mul_f32_e32 v159, 0xbfb8aa3b, v31
	v_mul_f32_e32 v160, 0xbfb8aa3b, v24
	v_mul_f32_e32 v161, 0xbfb8aa3b, v25
	v_mul_f32_e32 v162, 0xbfb8aa3b, v26
	v_mul_f32_e32 v163, 0xbfb8aa3b, v27
	v_exp_f32_e32 v156, v156
	v_exp_f32_e32 v157, v157
	v_exp_f32_e32 v158, v158
	v_exp_f32_e32 v159, v159
	v_exp_f32_e32 v160, v160
	v_exp_f32_e32 v161, v161
	v_exp_f32_e32 v162, v162
	v_exp_f32_e32 v163, v163
	v_add_f32_e32 v156, 1.0, v156
	v_add_f32_e32 v157, 1.0, v157
	v_add_f32_e32 v158, 1.0, v158
	v_add_f32_e32 v159, 1.0, v159
	v_add_f32_e32 v160, 1.0, v160
	v_add_f32_e32 v161, 1.0, v161
	v_add_f32_e32 v162, 1.0, v162
	v_add_f32_e32 v163, 1.0, v163
	v_rcp_f32_e32 v156, v156
	v_rcp_f32_e32 v157, v157
	v_rcp_f32_e32 v158, v158
	v_rcp_f32_e32 v159, v159
	v_rcp_f32_e32 v160, v160
	v_rcp_f32_e32 v161, v161
	v_rcp_f32_e32 v162, v162
	v_rcp_f32_e32 v163, v163
	v_mul_f32_e32 v28, v28, v156
	v_mul_f32_e32 v29, v29, v157
	v_mul_f32_e32 v30, v30, v158
	v_mul_f32_e32 v31, v31, v159
	v_mul_f32_e32 v24, v24, v160
	v_mul_f32_e32 v25, v25, v161
	v_mul_f32_e32 v26, v26, v162
	v_mul_f32_e32 v27, v27, v163
	v_mul_f32_e32 v156, 0xbfb8aa3b, v20
	v_mul_f32_e32 v157, 0xbfb8aa3b, v21
	v_mul_f32_e32 v158, 0xbfb8aa3b, v22
	v_mul_f32_e32 v159, 0xbfb8aa3b, v23
	v_mul_f32_e32 v160, 0xbfb8aa3b, v16
	v_mul_f32_e32 v161, 0xbfb8aa3b, v17
	v_mul_f32_e32 v162, 0xbfb8aa3b, v18
	v_mul_f32_e32 v163, 0xbfb8aa3b, v19
	v_exp_f32_e32 v156, v156
	v_exp_f32_e32 v157, v157
	v_exp_f32_e32 v158, v158
	v_exp_f32_e32 v159, v159
	v_exp_f32_e32 v160, v160
	v_exp_f32_e32 v161, v161
	v_exp_f32_e32 v162, v162
	v_exp_f32_e32 v163, v163
	v_add_f32_e32 v156, 1.0, v156
	v_add_f32_e32 v157, 1.0, v157
	v_add_f32_e32 v158, 1.0, v158
	v_add_f32_e32 v159, 1.0, v159
	v_add_f32_e32 v160, 1.0, v160
	v_add_f32_e32 v161, 1.0, v161
	v_add_f32_e32 v162, 1.0, v162
	v_add_f32_e32 v163, 1.0, v163
	v_rcp_f32_e32 v156, v156
	v_rcp_f32_e32 v157, v157
	v_rcp_f32_e32 v158, v158
	v_rcp_f32_e32 v159, v159
	v_rcp_f32_e32 v160, v160
	v_rcp_f32_e32 v161, v161
	v_rcp_f32_e32 v162, v162
	v_rcp_f32_e32 v163, v163
	v_mul_f32_e32 v20, v20, v156
	v_mul_f32_e32 v21, v21, v157
	v_mul_f32_e32 v22, v22, v158
	v_mul_f32_e32 v23, v23, v159
	v_mul_f32_e32 v16, v16, v160
	v_mul_f32_e32 v17, v17, v161
	v_mul_f32_e32 v18, v18, v162
	v_mul_f32_e32 v19, v19, v163
	v_cvt_pk_bf16_f32 v136, v28, v29
	v_cvt_pk_bf16_f32 v137, v30, v31
	v_cvt_pk_bf16_f32 v138, v24, v25
	v_cvt_pk_bf16_f32 v139, v26, v27
	v_cvt_pk_bf16_f32 v140, v20, v21
	v_cvt_pk_bf16_f32 v141, v22, v23
	v_cvt_pk_bf16_f32 v142, v16, v17
	v_cvt_pk_bf16_f32 v143, v18, v19
	s_nop 1
	v_permlane16_swap_b32_e32 v136, v138
	v_permlane16_swap_b32_e32 v137, v139
	v_permlane16_swap_b32_e32 v140, v142
	v_permlane16_swap_b32_e32 v141, v143
	global_store_dwordx4 v154, v[136:139], s[100:101]
	global_store_dwordx4 v154, v[140:143], s[100:101] offset:64
	v_mul_f32_e32 v156, 0xbfb8aa3b, v12
	v_mul_f32_e32 v157, 0xbfb8aa3b, v13
	v_mul_f32_e32 v158, 0xbfb8aa3b, v14
	v_mul_f32_e32 v159, 0xbfb8aa3b, v15
	v_mul_f32_e32 v160, 0xbfb8aa3b, v8
	v_mul_f32_e32 v161, 0xbfb8aa3b, v9
	v_mul_f32_e32 v162, 0xbfb8aa3b, v10
	v_mul_f32_e32 v163, 0xbfb8aa3b, v11
	v_exp_f32_e32 v156, v156
	v_exp_f32_e32 v157, v157
	v_exp_f32_e32 v158, v158
	v_exp_f32_e32 v159, v159
	v_exp_f32_e32 v160, v160
	v_exp_f32_e32 v161, v161
	v_exp_f32_e32 v162, v162
	v_exp_f32_e32 v163, v163
	v_add_f32_e32 v156, 1.0, v156
	v_add_f32_e32 v157, 1.0, v157
	v_add_f32_e32 v158, 1.0, v158
	v_add_f32_e32 v159, 1.0, v159
	v_add_f32_e32 v160, 1.0, v160
	v_add_f32_e32 v161, 1.0, v161
	v_add_f32_e32 v162, 1.0, v162
	v_add_f32_e32 v163, 1.0, v163
	v_rcp_f32_e32 v156, v156
	v_rcp_f32_e32 v157, v157
	v_rcp_f32_e32 v158, v158
	v_rcp_f32_e32 v159, v159
	v_rcp_f32_e32 v160, v160
	v_rcp_f32_e32 v161, v161
	v_rcp_f32_e32 v162, v162
	v_rcp_f32_e32 v163, v163
	v_mul_f32_e32 v12, v12, v156
	v_mul_f32_e32 v13, v13, v157
	v_mul_f32_e32 v14, v14, v158
	v_mul_f32_e32 v15, v15, v159
	v_mul_f32_e32 v8, v8, v160
	v_mul_f32_e32 v9, v9, v161
	v_mul_f32_e32 v10, v10, v162
	v_mul_f32_e32 v11, v11, v163
	v_mul_f32_e32 v156, 0xbfb8aa3b, v4
	v_mul_f32_e32 v157, 0xbfb8aa3b, v5
	v_mul_f32_e32 v158, 0xbfb8aa3b, v6
	v_mul_f32_e32 v159, 0xbfb8aa3b, v7
	v_mul_f32_e32 v160, 0xbfb8aa3b, v0
	v_mul_f32_e32 v161, 0xbfb8aa3b, v1
	v_mul_f32_e32 v162, 0xbfb8aa3b, v2
	v_mul_f32_e32 v163, 0xbfb8aa3b, v3
	v_exp_f32_e32 v156, v156
	v_exp_f32_e32 v157, v157
	v_exp_f32_e32 v158, v158
	v_exp_f32_e32 v159, v159
	v_exp_f32_e32 v160, v160
	v_exp_f32_e32 v161, v161
	v_exp_f32_e32 v162, v162
	v_exp_f32_e32 v163, v163
	v_add_f32_e32 v156, 1.0, v156
	v_add_f32_e32 v157, 1.0, v157
	v_add_f32_e32 v158, 1.0, v158
	v_add_f32_e32 v159, 1.0, v159
	v_add_f32_e32 v160, 1.0, v160
	v_add_f32_e32 v161, 1.0, v161
	v_add_f32_e32 v162, 1.0, v162
	v_add_f32_e32 v163, 1.0, v163
	v_rcp_f32_e32 v156, v156
	v_rcp_f32_e32 v157, v157
	v_rcp_f32_e32 v158, v158
	v_rcp_f32_e32 v159, v159
	v_rcp_f32_e32 v160, v160
	v_rcp_f32_e32 v161, v161
	v_rcp_f32_e32 v162, v162
	v_rcp_f32_e32 v163, v163
	v_mul_f32_e32 v4, v4, v156
	v_mul_f32_e32 v5, v5, v157
	v_mul_f32_e32 v6, v6, v158
	v_mul_f32_e32 v7, v7, v159
	v_mul_f32_e32 v0, v0, v160
	v_mul_f32_e32 v1, v1, v161
	v_mul_f32_e32 v2, v2, v162
	v_mul_f32_e32 v3, v3, v163
	v_cvt_pk_bf16_f32 v144, v12, v13
	v_cvt_pk_bf16_f32 v145, v14, v15
	v_cvt_pk_bf16_f32 v146, v8, v9
	v_cvt_pk_bf16_f32 v147, v10, v11
	v_cvt_pk_bf16_f32 v148, v4, v5
	v_cvt_pk_bf16_f32 v149, v6, v7
	v_cvt_pk_bf16_f32 v150, v0, v1
	v_cvt_pk_bf16_f32 v151, v2, v3
	s_nop 1
	v_permlane16_swap_b32_e32 v144, v146
	v_permlane16_swap_b32_e32 v145, v147
	v_permlane16_swap_b32_e32 v148, v150
	v_permlane16_swap_b32_e32 v149, v151
	global_store_dwordx4 v155, v[144:147], s[100:101]
	global_store_dwordx4 v155, v[148:151], s[100:101] offset:64
	s_branch .Lfe_join_C
; DI unsigned pack2(float a, float b) { v2f f = {a, b}; return __builtin_bit_cast(unsigned, __builtin_convertvector(f, v2bf)); }
; DI float silu_f(float v) { return v / (1.f + fexp(-v)); }
; DI float sigmoid_f(float v) { return 1.f / (1.f + fexp(-v)); }
;   DI void operator()(int m, int n, float a, float b, float c, float d, float& ss) const { u32x2 v; v.x = pack2(a, b); v.y = pack2(c, d); *(u32x2*)(y + (long)m * 1024 + n) = v; }
; template <class ARow, class Epi>
; DI void gemm_tile(const ARow& arow, long a_kstride, const u16* __restrict__ Bt, long ldb, int K, int m0, int n0,
;                   const Epi& epi, char* smem) {
;     ...
;   } else {
; #pragma unroll
;     for (int mi = 0; mi < 4; ++mi) {
;       const int m = m0 + wm * 64 + mi * 16 + fr;
;       float ss = 0.f;
; #pragma unroll
;       for (int ni = 0; ni < 4; ++ni) {
;         const int n = nh + ni * 16 + fq * 4;
;         epi(m, n, acc[ni][mi][0], acc[ni][mi][1], acc[ni][mi][2], acc[ni][mi][3], ss);
;       }
;       epi.finish16(m, nh, ss);
;     }
;   }
;   DI void operator()(int m, int n, float a, float b, float c, float d, float& ss) const {
;     if (n >= gl_start) {
;       const int j = n - gl_start;
;       if (j < 48) { float* g = gates + (long)m * 48 + j; g[0] = sigmoid_f(a); g[1] = sigmoid_f(b); g[2] = sigmoid_f(c); g[3] = sigmoid_f(d); }
;       return;
;     }
;     if (n < q_end) { a *= qscale; b *= qscale; c *= qscale; d *= qscale; }
;     else if (n >= z_start) { a = silu_f(a); b = silu_f(b); c = silu_f(c); d = silu_f(d); }
;     ss += a * a + b * b + c * c + d * d;
;     u32x2 v; v.x = pack2(a, b); v.y = pack2(c, d);
;     *(u32x2*)(dst + (long)m * ld + n) = v;
.Lfe_C_not_z:
	s_and_saveexec_b64 s[0:1], vcc
	s_xor_b64 s[26:27], exec, s[0:1]
	s_cbranch_execz .LBB0_1849
	v_mad_i64_i32 v[68:69], s[0:1], v74, s31, 0
	v_cmp_lt_i32_e64 s[4:5], s30, v64
	v_add_u32_e32 v66, -2.0, v64
	s_and_saveexec_b64 s[0:1], s[4:5]
	s_xor_b64 s[0:1], exec, s[0:1]
	s_cbranch_execz .LBB0_1708
	v_cmp_gt_u32_e32 vcc, 48, v66
	s_and_saveexec_b64 s[6:7], vcc
	s_cbranch_execz .LBB0_1707
	v_mul_f32_e32 v60, 0xbfb8aa3b, v60
	v_mul_f32_e32 v61, 0xbfb8aa3b, v61
	v_exp_f32_e32 v60, v60
	v_exp_f32_e32 v61, v61
	v_mov_b32_e32 v67, v65
	v_lshl_add_u64 v[70:71], v[66:67], 2, v[68:69]
	v_mul_f32_e32 v62, 0xbfb8aa3b, v62
	v_pk_add_f32 v[60:61], v[60:61], 1.0 op_sel_hi:[1,0]
	v_mul_f32_e32 v63, 0xbfb8aa3b, v63
	v_exp_f32_e32 v62, v62
	v_exp_f32_e32 v63, v63
	v_rcp_f32_e32 v67, v61
	s_nop 0
	v_mul_f32_e32 v61, 1.0, v67
	v_pk_add_f32 v[62:63], v[62:63], 1.0 op_sel_hi:[1,0]
	v_rcp_f32_e32 v67, v60
	s_nop 0
	v_mul_f32_e32 v60, 1.0, v67
	v_rcp_f32_e32 v67, v63
	s_nop 0
	v_mul_f32_e32 v63, 1.0, v67
	v_rcp_f32_e32 v67, v62
	s_nop 0
	v_mul_f32_e32 v62, 1.0, v67
	flat_store_dwordx4 v[70:71], v[60:63]

; DI int lbid() { int x = blockIdx.x; asm volatile("" : "+s"(x)); return x; }
; template <class Epi>
; DI void gemm_phase_plain(const u16* A, long lda, const u16* Bt, long ldb, int M, int N, int K, const Epi& epi, char* smem) {
;     ...
;   for (int t = lbid(); t < nwg; t += gridDim.x) {
;     const int xcd = t & 7, off = t >> 3;
;     const int wg = (xcd < rr ? xcd * (q + 1) : rr * (q + 1) + (xcd - rr) * q) + off;
;     const int nig = 8 * MT, gid = wg / nig, fm = gid * 8, gsz = (NT - fm) < 8 ? (NT - fm) : 8;
;     const int nt = fm + (wg % nig) % gsz, mt = (wg % nig) / gsz;
;     gemm_tile(ar, 64, Bt, ldb, K, mt * 128, nt * 128, epi, smem);
;   }
.Lfe_join_D:
	s_load_dword s0, s[18:19], 0x0
	s_waitcnt lgkmcnt(0)
	s_add_i32 s25, s0, s25
	s_cmpk_lt_i32 s25, 0x1000
	s_cbranch_scc0 .LBB0_2542

; template <class ARow, class Epi>
; DI void gemm_tile(const ARow& arow, long a_kstride, const u16* __restrict__ Bt, long ldb, int K, int m0, int n0,
;                   const Epi& epi, char* smem) {
;     ...
;   for (int kt = 0; kt < KT; ++kt) {
;     const int cur = kt & 1;
;     if (kt + 1 < KT) GEMM_STAGE(cur ^ 1, kt + 1);
;     const char* sa = smem + cur * 32768 + wm * 64 * 128;
;     const char* sb = smem + cur * 32768 + 16384 + wn * 64 * 128;
; #pragma unroll
;     for (int ks = 0; ks < 2; ++ks) {
;       bf16x8 wf[4], af[4];
; #pragma unroll
;       for (int j = 0; j < 4; ++j) {
;         wf[j] = *(const bf16x8*)(sb + j * 2048 + foff[ks]);
;         af[j] = *(const bf16x8*)(sa + j * 2048 + foff[ks]);
;       }
; #pragma unroll
;       for (int ni = 0; ni < 4; ++ni)
; #pragma unroll
;         for (int mi = 0; mi < 4; ++mi) acc[ni][mi] = __builtin_amdgcn_mfma_f32_16x16x32_bf16(wf[ni], af[mi], acc[ni][mi], 0, 0, 0);
;     }
;     asm volatile("s_waitcnt vmcnt(0)" ::: "memory");
;     __syncthreads();
;   }
.LBB0_2314:
	s_and_b32 s6, s1, 0x8000
	s_xor_b32 s7, s6, 0x8000
	v_add_u32_e32 v108, s7, v90
	v_add_u32_e32 v91, s6, v88
	v_or_b32_e32 v116, s6, v89
	v_readfirstlane_b32 s6, v108
	v_add_u32_e32 v109, 0x4000, v108
	v_lshl_add_u64 v[92:93], v[66:67], 0, s[4:5]
	v_add_u32_e32 v110, 0x400, v108
	v_readfirstlane_b32 s7, v109
	s_mov_b32 m0, s6
	v_lshl_add_u64 v[94:95], v[68:69], 0, s[4:5]
	v_add_u32_e32 v111, 0x4400, v108
	v_readfirstlane_b32 s8, v110
	global_load_lds_dwordx4 v[92:93], off
	s_mov_b32 m0, s7
	v_lshl_add_u64 v[96:97], v[70:71], 0, s[4:5]
	v_add_u32_e32 v113, 0x800, v108
	v_readfirstlane_b32 s9, v111
	global_load_lds_dwordx4 v[94:95], off
	s_mov_b32 m0, s8
	v_lshl_add_u64 v[98:99], v[72:73], 0, s[4:5]
	v_add_u32_e32 v114, 0x4800, v108
	v_readfirstlane_b32 s10, v113
	global_load_lds_dwordx4 v[96:97], off
	s_mov_b32 m0, s9
	v_lshl_add_u64 v[100:101], v[74:75], 0, s[4:5]
	v_add_u32_e32 v115, 0xc00, v108
	v_readfirstlane_b32 s11, v114
	global_load_lds_dwordx4 v[98:99], off
	s_mov_b32 m0, s10
	v_lshl_add_u64 v[102:103], v[76:77], 0, s[4:5]
	v_add_u32_e32 v108, 0x4c00, v108
	v_readfirstlane_b32 s26, v115
	global_load_lds_dwordx4 v[100:101], off
	s_mov_b32 m0, s11
	v_lshl_add_u64 v[104:105], v[78:79], 0, s[4:5]
	v_readfirstlane_b32 s27, v108
	global_load_lds_dwordx4 v[102:103], off
	s_mov_b32 m0, s26
	v_lshl_add_u64 v[106:107], v[80:81], 0, s[4:5]
	global_load_lds_dwordx4 v[104:105], off
	s_mov_b32 m0, s27
	v_add_u32_e32 v117, v116, v87
	global_load_lds_dwordx4 v[106:107], off
	v_add_u32_e32 v112, v91, v87
	ds_read_b128 v[92:95], v117 offset:16384
	ds_read_b128 v[96:99], v112
	ds_read_b128 v[100:103], v117 offset:18432
	ds_read_b128 v[104:107], v112 offset:2048
	ds_read_b128 v[108:111], v112 offset:4096
	ds_read_b128 v[112:115], v112 offset:6144
	s_waitcnt lgkmcnt(0)
	v_mfma_f32_16x16x32_bf16 v[60:63], v[92:95], v[96:99], v[60:63]
	v_add_u32_e32 v116, v116, v86
	v_add_u32_e32 v91, v91, v86
	s_add_i32 s1, s1, 0x8000
	v_mfma_f32_16x16x32_bf16 v[56:59], v[92:95], v[104:107], v[56:59]
	s_add_u32 s4, s4, 0x80
	s_addc_u32 s5, s5, 0
	s_cmpk_eq_i32 s4, 0x780
	v_mfma_f32_16x16x32_bf16 v[48:51], v[92:95], v[108:111], v[48:51]
	v_mfma_f32_16x16x32_bf16 v[40:43], v[92:95], v[112:115], v[40:43]
	v_mfma_f32_16x16x32_bf16 v[36:39], v[100:103], v[96:99], v[36:39]
	v_mfma_f32_16x16x32_bf16 v[32:35], v[100:103], v[104:107], v[32:35]
	v_mfma_f32_16x16x32_bf16 v[28:31], v[100:103], v[108:111], v[28:31]
	v_mfma_f32_16x16x32_bf16 v[24:27], v[100:103], v[112:115], v[24:27]
	ds_read_b128 v[92:95], v117 offset:20480
	ds_read_b128 v[100:103], v117 offset:22528
	s_waitcnt lgkmcnt(0)
	v_mfma_f32_16x16x32_bf16 v[20:23], v[92:95], v[96:99], v[20:23]
	v_mfma_f32_16x16x32_bf16 v[16:19], v[92:95], v[104:107], v[16:19]
	v_mfma_f32_16x16x32_bf16 v[12:15], v[92:95], v[108:111], v[12:15]
	v_mfma_f32_16x16x32_bf16 v[8:11], v[92:95], v[112:115], v[8:11]
	ds_read_b128 v[92:95], v116 offset:16384
	v_mfma_f32_16x16x32_bf16 v[4:7], v[100:103], v[96:99], v[4:7]
	v_mfma_f32_16x16x32_bf16 v[0:3], v[100:103], v[104:107], v[0:3]
	v_mfma_f32_16x16x32_bf16 v[52:55], v[100:103], v[108:111], v[52:55]
	v_mfma_f32_16x16x32_bf16 v[44:47], v[100:103], v[112:115], v[44:47]
	ds_read_b128 v[96:99], v91
	ds_read_b128 v[100:103], v116 offset:18432
	ds_read_b128 v[104:107], v91 offset:2048
	ds_read_b128 v[108:111], v91 offset:4096
	ds_read_b128 v[112:115], v91 offset:6144
	s_waitcnt lgkmcnt(0)
	v_mfma_f32_16x16x32_bf16 v[60:63], v[92:95], v[96:99], v[60:63]
	v_mfma_f32_16x16x32_bf16 v[56:59], v[92:95], v[104:107], v[56:59]
	v_mfma_f32_16x16x32_bf16 v[48:51], v[92:95], v[108:111], v[48:51]
	v_mfma_f32_16x16x32_bf16 v[40:43], v[92:95], v[112:115], v[40:43]
	v_mfma_f32_16x16x32_bf16 v[36:39], v[100:103], v[96:99], v[36:39]
	v_mfma_f32_16x16x32_bf16 v[32:35], v[100:103], v[104:107], v[32:35]
	v_mfma_f32_16x16x32_bf16 v[28:31], v[100:103], v[108:111], v[28:31]
	v_mfma_f32_16x16x32_bf16 v[24:27], v[100:103], v[112:115], v[24:27]
	ds_read_b128 v[92:95], v116 offset:20480
	ds_read_b128 v[100:103], v116 offset:22528
	s_waitcnt vmcnt(0)
	s_waitcnt vmcnt(0) lgkmcnt(0)
	v_mfma_f32_16x16x32_bf16 v[20:23], v[92:95], v[96:99], v[20:23]
	s_barrier
	v_mfma_f32_16x16x32_bf16 v[16:19], v[92:95], v[104:107], v[16:19]
	v_mfma_f32_16x16x32_bf16 v[12:15], v[92:95], v[108:111], v[12:15]
	v_mfma_f32_16x16x32_bf16 v[8:11], v[92:95], v[112:115], v[8:11]
	v_mfma_f32_16x16x32_bf16 v[4:7], v[100:103], v[96:99], v[4:7]
	v_mfma_f32_16x16x32_bf16 v[0:3], v[100:103], v[104:107], v[0:3]
	v_mfma_f32_16x16x32_bf16 v[52:55], v[100:103], v[108:111], v[52:55]
	v_mfma_f32_16x16x32_bf16 v[44:47], v[100:103], v[112:115], v[44:47]
	s_cbranch_scc0 .LBB0_2314
; DI unsigned pack2(float a, float b) { v2f f = {a, b}; return __builtin_bit_cast(unsigned, __builtin_convertvector(f, v2bf)); }
; DI float silu_f(float v) { return v / (1.f + fexp(-v)); }
;   DI u32x2 pack(int, int, float a, float b, float c, float d, float&) const { u32x2 v; v.x = pack2(a, b); v.y = pack2(c, d); return v; }
; template <class ARow, class Epi>
; DI void gemm_tile(const ARow& arow, long a_kstride, const u16* __restrict__ Bt, long ldb, int K, int m0, int n0,
;                   const Epi& epi, char* smem) {
;     ...
;   const int nh = n0 + wn * 64;
;   if (epi.packed(nh)) {
; #pragma unroll
;     for (int mi = 0; mi < 4; ++mi) {
;       const int m = m0 + wm * 64 + mi * 16 + fr;
;       float ss = 0.f;
;       u32x2 pk[4];
; #pragma unroll
;       for (int ni = 0; ni < 4; ++ni) pk[ni] = epi.pack(m, nh + ni * 16 + fq * 4, acc[ni][mi][0], acc[ni][mi][1], acc[ni][mi][2], acc[ni][mi][3], ss);
;       epi.finish16(m, nh, ss);
;       u16* rp = epi.rowp(m) + nh;
; #pragma unroll
;       for (int pp = 0; pp < 2; ++pp) {
;         u32x2 a = pk[2 * pp], b = pk[2 * pp + 1];
;         const u32x2 rx = __builtin_amdgcn_permlane16_swap(a.x, b.x, false, false);
;         const u32x2 ry = __builtin_amdgcn_permlane16_swap(a.y, b.y, false, false);
;         const int nst = (fq & 1) ? ((2 * pp + 1) * 16 + (fq - 1) * 4) : ((2 * pp) * 16 + fq * 4);
;         *(u32x4*)(rp + nst) = (u32x4){rx[0], ry[0], rx[1], ry[1]};
;       }
;     }
;   DI u32x2 pack(int m, int n, float a, float b, float c, float d, float& ss) const {
;     if (n < q_end) { a *= qscale; b *= qscale; c *= qscale; d *= qscale; }
;     else if (n >= z_start) { a = silu_f(a); b = silu_f(b); c = silu_f(c); d = silu_f(d); }
;     ss += a * a + b * b + c * c + d * d;
;     u32x2 v; v.x = pack2(a, b); v.y = pack2(c, d);
;     return v;
;   }
	v_add_u32_e32 v106, v89, v87
	ds_read_b128 v[66:69], v106 offset:49152
	v_add_u32_e32 v87, v88, v87
	ds_read_b128 v[70:73], v87 offset:32768
	ds_read_b128 v[74:77], v87 offset:34816
	ds_read_b128 v[78:81], v87 offset:36864
	ds_read_b128 v[90:93], v87 offset:38912
	v_add_u32_e32 v114, v89, v86
	s_waitcnt lgkmcnt(3)
	v_mfma_f32_16x16x32_bf16 v[60:63], v[66:69], v[70:73], v[60:63]
	s_waitcnt lgkmcnt(2)
	v_mfma_f32_16x16x32_bf16 v[56:59], v[66:69], v[74:77], v[56:59]
	s_waitcnt lgkmcnt(1)
	v_mfma_f32_16x16x32_bf16 v[48:51], v[66:69], v[78:81], v[48:51]
	s_waitcnt lgkmcnt(0)
	v_mfma_f32_16x16x32_bf16 v[40:43], v[66:69], v[90:93], v[40:43]
	ds_read_b128 v[66:69], v106 offset:51200
	s_waitcnt lgkmcnt(0)
	v_mfma_f32_16x16x32_bf16 v[36:39], v[66:69], v[70:73], v[36:39]
	v_mfma_f32_16x16x32_bf16 v[32:35], v[66:69], v[74:77], v[32:35]
	v_mfma_f32_16x16x32_bf16 v[94:97], v[66:69], v[78:81], v[28:31]
	v_mfma_f32_16x16x32_bf16 v[66:69], v[66:69], v[90:93], v[24:27]
	s_nop 2
	ds_read_b128 v[24:27], v106 offset:53248
	s_waitcnt lgkmcnt(0)
	v_mfma_f32_16x16x32_bf16 v[102:105], v[24:27], v[90:93], v[8:11]
	s_nop 2
	ds_read_b128 v[8:11], v106 offset:55296
	v_mfma_f32_16x16x32_bf16 v[20:23], v[24:27], v[70:73], v[20:23]
	s_waitcnt lgkmcnt(0)
	v_mfma_f32_16x16x32_bf16 v[70:73], v[8:11], v[70:73], v[4:7]
	s_nop 2
	ds_read_b128 v[4:7], v114 offset:49152
	v_mfma_f32_16x16x32_bf16 v[98:101], v[24:27], v[78:81], v[12:15]
	s_nop 2
	v_add_u32_e32 v12, v88, v86
	v_mfma_f32_16x16x32_bf16 v[16:19], v[24:27], v[74:77], v[16:19]
	ds_read_b128 v[86:89], v12 offset:32768
	ds_read_b128 v[106:109], v12 offset:36864
	ds_read_b128 v[110:113], v12 offset:38912
	v_mfma_f32_16x16x32_bf16 v[0:3], v[8:11], v[74:77], v[0:3]
	v_mfma_f32_16x16x32_bf16 v[74:77], v[8:11], v[78:81], v[52:55]
	v_mfma_f32_16x16x32_bf16 v[78:81], v[8:11], v[90:93], v[44:47]
	ds_read_b128 v[90:93], v12 offset:34816
	s_waitcnt lgkmcnt(3)
	v_mfma_f32_16x16x32_bf16 v[60:63], v[4:7], v[86:89], v[60:63]
	s_waitcnt lgkmcnt(0)
	v_mfma_f32_16x16x32_bf16 v[44:47], v[4:7], v[90:93], v[56:59]
	v_mfma_f32_16x16x32_bf16 v[28:31], v[4:7], v[106:109], v[48:51]
	v_mfma_f32_16x16x32_bf16 v[12:15], v[4:7], v[110:113], v[40:43]
	ds_read_b128 v[4:7], v114 offset:51200
	s_waitcnt lgkmcnt(0)
	v_mfma_f32_16x16x32_bf16 v[56:59], v[4:7], v[86:89], v[36:39]
	v_mfma_f32_16x16x32_bf16 v[40:43], v[4:7], v[90:93], v[32:35]
	v_mfma_f32_16x16x32_bf16 v[24:27], v[4:7], v[106:109], v[94:97]
	v_mfma_f32_16x16x32_bf16 v[8:11], v[4:7], v[110:113], v[66:69]
	ds_read_b128 v[4:7], v114 offset:53248
	s_nop 0
	ds_read_b128 v[94:97], v114 offset:55296
	s_waitcnt vmcnt(0)
	s_waitcnt lgkmcnt(0)
	v_mfma_f32_16x16x32_bf16 v[32:35], v[94:97], v[90:93], v[0:3]
	s_nop 2
	v_or_b32_e32 v0, s0, v64
	v_lshl_add_u32 v66, v85, 6, v0
	v_lshl_or_b32 v68, v84, 6, s34
	v_mfma_f32_16x16x32_bf16 v[52:55], v[4:7], v[86:89], v[20:23]
	v_cmp_lt_i32_e32 vcc, s30, v68
	s_barrier
	v_mfma_f32_16x16x32_bf16 v[36:39], v[4:7], v[90:93], v[16:19]
	v_mfma_f32_16x16x32_bf16 v[20:23], v[4:7], v[106:109], v[98:101]
	v_mfma_f32_16x16x32_bf16 v[4:7], v[4:7], v[110:113], v[102:105]
	v_mfma_f32_16x16x32_bf16 v[48:51], v[94:97], v[86:89], v[70:73]
	v_mfma_f32_16x16x32_bf16 v[16:19], v[94:97], v[106:109], v[74:77]
	s_nop 1
	v_lshlrev_b32_e32 v70, 2, v83
	v_or_b32_e32 v64, v68, v70
	v_mfma_f32_16x16x32_bf16 v[0:3], v[94:97], v[110:113], v[78:81]
	s_nop 7
	v_readfirstlane_b32 s99, v68
	s_cmpk_ge_u32 s99, 0x400
	s_cbranch_scc0 .Lfe_D_not_plain
	s_cmpk_lt_u32 s99, 0xc00
	s_cbranch_scc0 .Lfe_D_not_plain
	s_load_dwordx2 s[100:101], s[56:57], 0x130
	v_and_b32_e32 v152, 1, v83
	v_mul_u32_u24_e32 v152, 12, v152
	v_lshl_add_u32 v152, v83, 2, v152
	v_add_u32_e32 v152, v152, v68
	v_lshl_add_u32 v152, v66, 12, v152
	v_lshlrev_b32_e32 v152, 1, v152
	v_add_u32_e32 v153, 0x20000, v152
	v_add_u32_e32 v154, 0x40000, v152
	v_add_u32_e32 v155, 0x60000, v152
	s_nop 3
	v_cvt_pk_bf16_f32 v120, v60, v61
	v_cvt_pk_bf16_f32 v121, v62, v63
	v_cvt_pk_bf16_f32 v122, v56, v57
	v_cvt_pk_bf16_f32 v123, v58, v59
	v_cvt_pk_bf16_f32 v124, v52, v53
	v_cvt_pk_bf16_f32 v125, v54, v55
	v_cvt_pk_bf16_f32 v126, v48, v49
	v_cvt_pk_bf16_f32 v127, v50, v51
	s_nop 1
	v_permlane16_swap_b32_e32 v120, v122
	v_permlane16_swap_b32_e32 v121, v123
	v_permlane16_swap_b32_e32 v124, v126
	v_permlane16_swap_b32_e32 v125, v127
	s_waitcnt lgkmcnt(0)
	global_store_dwordx4 v152, v[120:123], s[100:101]
	global_store_dwordx4 v152, v[124:127], s[100:101] offset:64
	v_cvt_pk_bf16_f32 v128, v44, v45
	v_cvt_pk_bf16_f32 v129, v46, v47
	v_cvt_pk_bf16_f32 v130, v40, v41
	v_cvt_pk_bf16_f32 v131, v42, v43
	v_cvt_pk_bf16_f32 v132, v36, v37
	v_cvt_pk_bf16_f32 v133, v38, v39
	v_cvt_pk_bf16_f32 v134, v32, v33
	v_cvt_pk_bf16_f32 v135, v34, v35
	s_nop 1
	v_permlane16_swap_b32_e32 v128, v130
	v_permlane16_swap_b32_e32 v129, v131
	v_permlane16_swap_b32_e32 v132, v134
	v_permlane16_swap_b32_e32 v133, v135
	global_store_dwordx4 v153, v[128:131], s[100:101]
	global_store_dwordx4 v153, v[132:135], s[100:101] offset:64
	v_cvt_pk_bf16_f32 v136, v28, v29
	v_cvt_pk_bf16_f32 v137, v30, v31
	v_cvt_pk_bf16_f32 v138, v24, v25
	v_cvt_pk_bf16_f32 v139, v26, v27
	v_cvt_pk_bf16_f32 v140, v20, v21
	v_cvt_pk_bf16_f32 v141, v22, v23
	v_cvt_pk_bf16_f32 v142, v16, v17
	v_cvt_pk_bf16_f32 v143, v18, v19
	s_nop 1
	v_permlane16_swap_b32_e32 v136, v138
	v_permlane16_swap_b32_e32 v137, v139
	v_permlane16_swap_b32_e32 v140, v142
	v_permlane16_swap_b32_e32 v141, v143
	global_store_dwordx4 v154, v[136:139], s[100:101]
	global_store_dwordx4 v154, v[140:143], s[100:101] offset:64
	v_cvt_pk_bf16_f32 v144, v12, v13
	v_cvt_pk_bf16_f32 v145, v14, v15
	v_cvt_pk_bf16_f32 v146, v8, v9
	v_cvt_pk_bf16_f32 v147, v10, v11
	v_cvt_pk_bf16_f32 v148, v4, v5
	v_cvt_pk_bf16_f32 v149, v6, v7
	v_cvt_pk_bf16_f32 v150, v0, v1
	v_cvt_pk_bf16_f32 v151, v2, v3
	s_nop 1
	v_permlane16_swap_b32_e32 v144, v146
	v_permlane16_swap_b32_e32 v145, v147
	v_permlane16_swap_b32_e32 v148, v150
	v_permlane16_swap_b32_e32 v149, v151
	global_store_dwordx4 v155, v[144:147], s[100:101]
	global_store_dwordx4 v155, v[148:151], s[100:101] offset:64
	s_branch .Lfe_join_D
; DI unsigned pack2(float a, float b) { v2f f = {a, b}; return __builtin_bit_cast(unsigned, __builtin_convertvector(f, v2bf)); }
; DI float silu_f(float v) { return v / (1.f + fexp(-v)); }
;   DI u32x2 pack(int, int, float a, float b, float c, float d, float&) const { u32x2 v; v.x = pack2(a, b); v.y = pack2(c, d); return v; }
; template <class ARow, class Epi>
; DI void gemm_tile(const ARow& arow, long a_kstride, const u16* __restrict__ Bt, long ldb, int K, int m0, int n0,
;                   const Epi& epi, char* smem) {
;     ...
;   const int nh = n0 + wn * 64;
;   if (epi.packed(nh)) {
; #pragma unroll
;     for (int mi = 0; mi < 4; ++mi) {
;       const int m = m0 + wm * 64 + mi * 16 + fr;
;       float ss = 0.f;
;       u32x2 pk[4];
; #pragma unroll
;       for (int ni = 0; ni < 4; ++ni) pk[ni] = epi.pack(m, nh + ni * 16 + fq * 4, acc[ni][mi][0], acc[ni][mi][1], acc[ni][mi][2], acc[ni][mi][3], ss);
;       epi.finish16(m, nh, ss);
;       u16* rp = epi.rowp(m) + nh;
; #pragma unroll
;       for (int pp = 0; pp < 2; ++pp) {
;         u32x2 a = pk[2 * pp], b = pk[2 * pp + 1];
;         const u32x2 rx = __builtin_amdgcn_permlane16_swap(a.x, b.x, false, false);
;         const u32x2 ry = __builtin_amdgcn_permlane16_swap(a.y, b.y, false, false);
;         const int nst = (fq & 1) ? ((2 * pp + 1) * 16 + (fq - 1) * 4) : ((2 * pp) * 16 + fq * 4);
;         *(u32x4*)(rp + nst) = (u32x4){rx[0], ry[0], rx[1], ry[1]};
;       }
;     }
;   DI u32x2 pack(int m, int n, float a, float b, float c, float d, float& ss) const {
;     if (n < q_end) { a *= qscale; b *= qscale; c *= qscale; d *= qscale; }
;     else if (n >= z_start) { a = silu_f(a); b = silu_f(b); c = silu_f(c); d = silu_f(d); }
;     ss += a * a + b * b + c * c + d * d;
;     u32x2 v; v.x = pack2(a, b); v.y = pack2(c, d);
;     return v;
;   }
.Lfe_D_not_plain:
	s_cmpk_lt_u32 s99, 0x400
	s_cbranch_scc0 .Lfe_D_not_q
	s_load_dwordx2 s[100:101], s[56:57], 0x130
	v_and_b32_e32 v152, 1, v83
	v_mul_u32_u24_e32 v152, 12, v152
	v_lshl_add_u32 v152, v83, 2, v152
	v_add_u32_e32 v152, v152, v68
	v_lshl_add_u32 v152, v66, 12, v152
	v_lshlrev_b32_e32 v152, 1, v152
	v_add_u32_e32 v153, 0x20000, v152
	v_add_u32_e32 v154, 0x40000, v152
	v_add_u32_e32 v155, 0x60000, v152
	s_mov_b32 s98, 0x3e000000
	s_nop 3
	v_pk_mul_f32 v[60:61], v[60:61], s[98:99] op_sel_hi:[1,0]
	v_pk_mul_f32 v[62:63], v[62:63], s[98:99] op_sel_hi:[1,0]
	v_pk_mul_f32 v[56:57], v[56:57], s[98:99] op_sel_hi:[1,0]
	v_pk_mul_f32 v[58:59], v[58:59], s[98:99] op_sel_hi:[1,0]
	v_pk_mul_f32 v[52:53], v[52:53], s[98:99] op_sel_hi:[1,0]
	v_pk_mul_f32 v[54:55], v[54:55], s[98:99] op_sel_hi:[1,0]
	v_pk_mul_f32 v[48:49], v[48:49], s[98:99] op_sel_hi:[1,0]
	v_pk_mul_f32 v[50:51], v[50:51], s[98:99] op_sel_hi:[1,0]
	v_cvt_pk_bf16_f32 v120, v60, v61
	v_cvt_pk_bf16_f32 v121, v62, v63
	v_cvt_pk_bf16_f32 v122, v56, v57
	v_cvt_pk_bf16_f32 v123, v58, v59
	v_cvt_pk_bf16_f32 v124, v52, v53
	v_cvt_pk_bf16_f32 v125, v54, v55
	v_cvt_pk_bf16_f32 v126, v48, v49
	v_cvt_pk_bf16_f32 v127, v50, v51
	s_nop 1
	v_permlane16_swap_b32_e32 v120, v122
	v_permlane16_swap_b32_e32 v121, v123
	v_permlane16_swap_b32_e32 v124, v126
	v_permlane16_swap_b32_e32 v125, v127
	s_waitcnt lgkmcnt(0)
	global_store_dwordx4 v152, v[120:123], s[100:101]
	global_store_dwordx4 v152, v[124:127], s[100:101] offset:64
	v_pk_mul_f32 v[44:45], v[44:45], s[98:99] op_sel_hi:[1,0]
	v_pk_mul_f32 v[46:47], v[46:47], s[98:99] op_sel_hi:[1,0]
	v_pk_mul_f32 v[40:41], v[40:41], s[98:99] op_sel_hi:[1,0]
	v_pk_mul_f32 v[42:43], v[42:43], s[98:99] op_sel_hi:[1,0]
	v_pk_mul_f32 v[36:37], v[36:37], s[98:99] op_sel_hi:[1,0]
	v_pk_mul_f32 v[38:39], v[38:39], s[98:99] op_sel_hi:[1,0]
	v_pk_mul_f32 v[32:33], v[32:33], s[98:99] op_sel_hi:[1,0]
	v_pk_mul_f32 v[34:35], v[34:35], s[98:99] op_sel_hi:[1,0]
	v_cvt_pk_bf16_f32 v128, v44, v45
	v_cvt_pk_bf16_f32 v129, v46, v47
	v_cvt_pk_bf16_f32 v130, v40, v41
	v_cvt_pk_bf16_f32 v131, v42, v43
	v_cvt_pk_bf16_f32 v132, v36, v37
	v_cvt_pk_bf16_f32 v133, v38, v39
	v_cvt_pk_bf16_f32 v134, v32, v33
	v_cvt_pk_bf16_f32 v135, v34, v35
	s_nop 1
	v_permlane16_swap_b32_e32 v128, v130
	v_permlane16_swap_b32_e32 v129, v131
	v_permlane16_swap_b32_e32 v132, v134
	v_permlane16_swap_b32_e32 v133, v135
	global_store_dwordx4 v153, v[128:131], s[100:101]
	global_store_dwordx4 v153, v[132:135], s[100:101] offset:64
	v_pk_mul_f32 v[28:29], v[28:29], s[98:99] op_sel_hi:[1,0]
	v_pk_mul_f32 v[30:31], v[30:31], s[98:99] op_sel_hi:[1,0]
	v_pk_mul_f32 v[24:25], v[24:25], s[98:99] op_sel_hi:[1,0]
	v_pk_mul_f32 v[26:27], v[26:27], s[98:99] op_sel_hi:[1,0]
	v_pk_mul_f32 v[20:21], v[20:21], s[98:99] op_sel_hi:[1,0]
	v_pk_mul_f32 v[22:23], v[22:23], s[98:99] op_sel_hi:[1,0]
	v_pk_mul_f32 v[16:17], v[16:17], s[98:99] op_sel_hi:[1,0]
	v_pk_mul_f32 v[18:19], v[18:19], s[98:99] op_sel_hi:[1,0]
	v_cvt_pk_bf16_f32 v136, v28, v29
	v_cvt_pk_bf16_f32 v137, v30, v31
	v_cvt_pk_bf16_f32 v138, v24, v25
	v_cvt_pk_bf16_f32 v139, v26, v27
	v_cvt_pk_bf16_f32 v140, v20, v21
	v_cvt_pk_bf16_f32 v141, v22, v23
	v_cvt_pk_bf16_f32 v142, v16, v17
	v_cvt_pk_bf16_f32 v143, v18, v19
	s_nop 1
	v_permlane16_swap_b32_e32 v136, v138
	v_permlane16_swap_b32_e32 v137, v139
	v_permlane16_swap_b32_e32 v140, v142
	v_permlane16_swap_b32_e32 v141, v143
	global_store_dwordx4 v154, v[136:139], s[100:101]
	global_store_dwordx4 v154, v[140:143], s[100:101] offset:64
	v_pk_mul_f32 v[12:13], v[12:13], s[98:99] op_sel_hi:[1,0]
	v_pk_mul_f32 v[14:15], v[14:15], s[98:99] op_sel_hi:[1,0]
	v_pk_mul_f32 v[8:9], v[8:9], s[98:99] op_sel_hi:[1,0]
	v_pk_mul_f32 v[10:11], v[10:11], s[98:99] op_sel_hi:[1,0]
	v_pk_mul_f32 v[4:5], v[4:5], s[98:99] op_sel_hi:[1,0]
	v_pk_mul_f32 v[6:7], v[6:7], s[98:99] op_sel_hi:[1,0]
	v_pk_mul_f32 v[0:1], v[0:1], s[98:99] op_sel_hi:[1,0]
	v_pk_mul_f32 v[2:3], v[2:3], s[98:99] op_sel_hi:[1,0]
	v_cvt_pk_bf16_f32 v144, v12, v13
	v_cvt_pk_bf16_f32 v145, v14, v15
	v_cvt_pk_bf16_f32 v146, v8, v9
	v_cvt_pk_bf16_f32 v147, v10, v11
	v_cvt_pk_bf16_f32 v148, v4, v5
	v_cvt_pk_bf16_f32 v149, v6, v7
	v_cvt_pk_bf16_f32 v150, v0, v1
	v_cvt_pk_bf16_f32 v151, v2, v3
	s_nop 1
	v_permlane16_swap_b32_e32 v144, v146
	v_permlane16_swap_b32_e32 v145, v147
	v_permlane16_swap_b32_e32 v148, v150
	v_permlane16_swap_b32_e32 v149, v151
	global_store_dwordx4 v155, v[144:147], s[100:101]
	global_store_dwordx4 v155, v[148:151], s[100:101] offset:64
	s_branch .Lfe_join_D
; DI unsigned pack2(float a, float b) { v2f f = {a, b}; return __builtin_bit_cast(unsigned, __builtin_convertvector(f, v2bf)); }
; DI float silu_f(float v) { return v / (1.f + fexp(-v)); }
;   DI u32x2 pack(int, int, float a, float b, float c, float d, float&) const { u32x2 v; v.x = pack2(a, b); v.y = pack2(c, d); return v; }
; template <class ARow, class Epi>
; DI void gemm_tile(const ARow& arow, long a_kstride, const u16* __restrict__ Bt, long ldb, int K, int m0, int n0,
;                   const Epi& epi, char* smem) {
;     ...
;   const int nh = n0 + wn * 64;
;   if (epi.packed(nh)) {
; #pragma unroll
;     for (int mi = 0; mi < 4; ++mi) {
;       const int m = m0 + wm * 64 + mi * 16 + fr;
;       float ss = 0.f;
;       u32x2 pk[4];
; #pragma unroll
;       for (int ni = 0; ni < 4; ++ni) pk[ni] = epi.pack(m, nh + ni * 16 + fq * 4, acc[ni][mi][0], acc[ni][mi][1], acc[ni][mi][2], acc[ni][mi][3], ss);
;       epi.finish16(m, nh, ss);
;       u16* rp = epi.rowp(m) + nh;
; #pragma unroll
;       for (int pp = 0; pp < 2; ++pp) {
;         u32x2 a = pk[2 * pp], b = pk[2 * pp + 1];
;         const u32x2 rx = __builtin_amdgcn_permlane16_swap(a.x, b.x, false, false);
;         const u32x2 ry = __builtin_amdgcn_permlane16_swap(a.y, b.y, false, false);
;         const int nst = (fq & 1) ? ((2 * pp + 1) * 16 + (fq - 1) * 4) : ((2 * pp) * 16 + fq * 4);
;         *(u32x4*)(rp + nst) = (u32x4){rx[0], ry[0], rx[1], ry[1]};
;       }
;     }
;   DI u32x2 pack(int m, int n, float a, float b, float c, float d, float& ss) const {
;     if (n < q_end) { a *= qscale; b *= qscale; c *= qscale; d *= qscale; }
;     else if (n >= z_start) { a = silu_f(a); b = silu_f(b); c = silu_f(c); d = silu_f(d); }
;     ss += a * a + b * b + c * c + d * d;
;     u32x2 v; v.x = pack2(a, b); v.y = pack2(c, d);
;     return v;
;   }
.Lfe_D_not_q:
	s_cmpk_ge_u32 s99, 0xc00
	s_cbranch_scc0 .Lfe_D_not_z
	s_cmpk_lt_u32 s99, 0x1000
	s_cbranch_scc0 .Lfe_D_not_z
	s_load_dwordx2 s[100:101], s[56:57], 0x130
	v_and_b32_e32 v152, 1, v83
	v_mul_u32_u24_e32 v152, 12, v152
	v_lshl_add_u32 v152, v83, 2, v152
	v_add_u32_e32 v152, v152, v68
	v_lshl_add_u32 v152, v66, 12, v152
	v_lshlrev_b32_e32 v152, 1, v152
	v_add_u32_e32 v153, 0x20000, v152
	v_add_u32_e32 v154, 0x40000, v152
	v_add_u32_e32 v155, 0x60000, v152
	s_nop 3
	v_mul_f32_e32 v156, 0xbfb8aa3b, v60
	v_mul_f32_e32 v157, 0xbfb8aa3b, v61
	v_mul_f32_e32 v158, 0xbfb8aa3b, v62
	v_mul_f32_e32 v159, 0xbfb8aa3b, v63
	v_mul_f32_e32 v160, 0xbfb8aa3b, v56
	v_mul_f32_e32 v161, 0xbfb8aa3b, v57
	v_mul_f32_e32 v162, 0xbfb8aa3b, v58
	v_mul_f32_e32 v163, 0xbfb8aa3b, v59
	v_exp_f32_e32 v156, v156
	v_exp_f32_e32 v157, v157
	v_exp_f32_e32 v158, v158
	v_exp_f32_e32 v159, v159
	v_exp_f32_e32 v160, v160
	v_exp_f32_e32 v161, v161
	v_exp_f32_e32 v162, v162
	v_exp_f32_e32 v163, v163
	v_add_f32_e32 v156, 1.0, v156
	v_add_f32_e32 v157, 1.0, v157
	v_add_f32_e32 v158, 1.0, v158
	v_add_f32_e32 v159, 1.0, v159
	v_add_f32_e32 v160, 1.0, v160
	v_add_f32_e32 v161, 1.0, v161
	v_add_f32_e32 v162, 1.0, v162
	v_add_f32_e32 v163, 1.0, v163
	v_rcp_f32_e32 v156, v156
	v_rcp_f32_e32 v157, v157
	v_rcp_f32_e32 v158, v158
	v_rcp_f32_e32 v159, v159
	v_rcp_f32_e32 v160, v160
	v_rcp_f32_e32 v161, v161
	v_rcp_f32_e32 v162, v162
	v_rcp_f32_e32 v163, v163
	v_mul_f32_e32 v60, v60, v156
	v_mul_f32_e32 v61, v61, v157
	v_mul_f32_e32 v62, v62, v158
	v_mul_f32_e32 v63, v63, v159
	v_mul_f32_e32 v56, v56, v160
	v_mul_f32_e32 v57, v57, v161
	v_mul_f32_e32 v58, v58, v162
	v_mul_f32_e32 v59, v59, v163
	v_mul_f32_e32 v156, 0xbfb8aa3b, v52
	v_mul_f32_e32 v157, 0xbfb8aa3b, v53
	v_mul_f32_e32 v158, 0xbfb8aa3b, v54
	v_mul_f32_e32 v159, 0xbfb8aa3b, v55
	v_mul_f32_e32 v160, 0xbfb8aa3b, v48
	v_mul_f32_e32 v161, 0xbfb8aa3b, v49
	v_mul_f32_e32 v162, 0xbfb8aa3b, v50
	v_mul_f32_e32 v163, 0xbfb8aa3b, v51
	v_exp_f32_e32 v156, v156
	v_exp_f32_e32 v157, v157
	v_exp_f32_e32 v158, v158
	v_exp_f32_e32 v159, v159
	v_exp_f32_e32 v160, v160
	v_exp_f32_e32 v161, v161
	v_exp_f32_e32 v162, v162
	v_exp_f32_e32 v163, v163
	v_add_f32_e32 v156, 1.0, v156
	v_add_f32_e32 v157, 1.0, v157
	v_add_f32_e32 v158, 1.0, v158
	v_add_f32_e32 v159, 1.0, v159
	v_add_f32_e32 v160, 1.0, v160
	v_add_f32_e32 v161, 1.0, v161
	v_add_f32_e32 v162, 1.0, v162
	v_add_f32_e32 v163, 1.0, v163
	v_rcp_f32_e32 v156, v156
	v_rcp_f32_e32 v157, v157
	v_rcp_f32_e32 v158, v158
	v_rcp_f32_e32 v159, v159
	v_rcp_f32_e32 v160, v160
	v_rcp_f32_e32 v161, v161
	v_rcp_f32_e32 v162, v162
	v_rcp_f32_e32 v163, v163
	v_mul_f32_e32 v52, v52, v156
	v_mul_f32_e32 v53, v53, v157
	v_mul_f32_e32 v54, v54, v158
	v_mul_f32_e32 v55, v55, v159
	v_mul_f32_e32 v48, v48, v160
	v_mul_f32_e32 v49, v49, v161
	v_mul_f32_e32 v50, v50, v162
	v_mul_f32_e32 v51, v51, v163
	v_cvt_pk_bf16_f32 v120, v60, v61
	v_cvt_pk_bf16_f32 v121, v62, v63
	v_cvt_pk_bf16_f32 v122, v56, v57
	v_cvt_pk_bf16_f32 v123, v58, v59
	v_cvt_pk_bf16_f32 v124, v52, v53
	v_cvt_pk_bf16_f32 v125, v54, v55
	v_cvt_pk_bf16_f32 v126, v48, v49
	v_cvt_pk_bf16_f32 v127, v50, v51
	s_nop 1
	v_permlane16_swap_b32_e32 v120, v122
	v_permlane16_swap_b32_e32 v121, v123
	v_permlane16_swap_b32_e32 v124, v126
	v_permlane16_swap_b32_e32 v125, v127
	s_waitcnt lgkmcnt(0)
	global_store_dwordx4 v152, v[120:123], s[100:101]
	global_store_dwordx4 v152, v[124:127], s[100:101] offset:64
	v_mul_f32_e32 v156, 0xbfb8aa3b, v44
	v_mul_f32_e32 v157, 0xbfb8aa3b, v45
	v_mul_f32_e32 v158, 0xbfb8aa3b, v46
	v_mul_f32_e32 v159, 0xbfb8aa3b, v47
	v_mul_f32_e32 v160, 0xbfb8aa3b, v40
	v_mul_f32_e32 v161, 0xbfb8aa3b, v41
	v_mul_f32_e32 v162, 0xbfb8aa3b, v42
	v_mul_f32_e32 v163, 0xbfb8aa3b, v43
	v_exp_f32_e32 v156, v156
	v_exp_f32_e32 v157, v157
	v_exp_f32_e32 v158, v158
	v_exp_f32_e32 v159, v159
	v_exp_f32_e32 v160, v160
	v_exp_f32_e32 v161, v161
	v_exp_f32_e32 v162, v162
	v_exp_f32_e32 v163, v163
	v_add_f32_e32 v156, 1.0, v156
	v_add_f32_e32 v157, 1.0, v157
	v_add_f32_e32 v158, 1.0, v158
	v_add_f32_e32 v159, 1.0, v159
	v_add_f32_e32 v160, 1.0, v160
	v_add_f32_e32 v161, 1.0, v161
	v_add_f32_e32 v162, 1.0, v162
	v_add_f32_e32 v163, 1.0, v163
	v_rcp_f32_e32 v156, v156
	v_rcp_f32_e32 v157, v157
	v_rcp_f32_e32 v158, v158
	v_rcp_f32_e32 v159, v159
	v_rcp_f32_e32 v160, v160
	v_rcp_f32_e32 v161, v161
	v_rcp_f32_e32 v162, v162
	v_rcp_f32_e32 v163, v163
	v_mul_f32_e32 v44, v44, v156
	v_mul_f32_e32 v45, v45, v157
	v_mul_f32_e32 v46, v46, v158
	v_mul_f32_e32 v47, v47, v159
	v_mul_f32_e32 v40, v40, v160
	v_mul_f32_e32 v41, v41, v161
	v_mul_f32_e32 v42, v42, v162
	v_mul_f32_e32 v43, v43, v163
	v_mul_f32_e32 v156, 0xbfb8aa3b, v36
	v_mul_f32_e32 v157, 0xbfb8aa3b, v37
	v_mul_f32_e32 v158, 0xbfb8aa3b, v38
	v_mul_f32_e32 v159, 0xbfb8aa3b, v39
	v_mul_f32_e32 v160, 0xbfb8aa3b, v32
	v_mul_f32_e32 v161, 0xbfb8aa3b, v33
	v_mul_f32_e32 v162, 0xbfb8aa3b, v34
	v_mul_f32_e32 v163, 0xbfb8aa3b, v35
	v_exp_f32_e32 v156, v156
	v_exp_f32_e32 v157, v157
	v_exp_f32_e32 v158, v158
	v_exp_f32_e32 v159, v159
	v_exp_f32_e32 v160, v160
	v_exp_f32_e32 v161, v161
	v_exp_f32_e32 v162, v162
	v_exp_f32_e32 v163, v163
	v_add_f32_e32 v156, 1.0, v156
	v_add_f32_e32 v157, 1.0, v157
	v_add_f32_e32 v158, 1.0, v158
	v_add_f32_e32 v159, 1.0, v159
	v_add_f32_e32 v160, 1.0, v160
	v_add_f32_e32 v161, 1.0, v161
	v_add_f32_e32 v162, 1.0, v162
	v_add_f32_e32 v163, 1.0, v163
	v_rcp_f32_e32 v156, v156
	v_rcp_f32_e32 v157, v157
	v_rcp_f32_e32 v158, v158
	v_rcp_f32_e32 v159, v159
	v_rcp_f32_e32 v160, v160
	v_rcp_f32_e32 v161, v161
	v_rcp_f32_e32 v162, v162
	v_rcp_f32_e32 v163, v163
	v_mul_f32_e32 v36, v36, v156
; DI unsigned pack2(float a, float b) { v2f f = {a, b}; return __builtin_bit_cast(unsigned, __builtin_convertvector(f, v2bf)); }
; DI float silu_f(float v) { return v / (1.f + fexp(-v)); }
;   DI u32x2 pack(int, int, float a, float b, float c, float d, float&) const { u32x2 v; v.x = pack2(a, b); v.y = pack2(c, d); return v; }
; template <class ARow, class Epi>
; DI void gemm_tile(const ARow& arow, long a_kstride, const u16* __restrict__ Bt, long ldb, int K, int m0, int n0,
;                   const Epi& epi, char* smem) {
;     ...
;   const int nh = n0 + wn * 64;
;   if (epi.packed(nh)) {
; #pragma unroll
;     for (int mi = 0; mi < 4; ++mi) {
;       const int m = m0 + wm * 64 + mi * 16 + fr;
;       float ss = 0.f;
;       u32x2 pk[4];
; #pragma unroll
;       for (int ni = 0; ni < 4; ++ni) pk[ni] = epi.pack(m, nh + ni * 16 + fq * 4, acc[ni][mi][0], acc[ni][mi][1], acc[ni][mi][2], acc[ni][mi][3], ss);
;       epi.finish16(m, nh, ss);
;       u16* rp = epi.rowp(m) + nh;
; #pragma unroll
;       for (int pp = 0; pp < 2; ++pp) {
;         u32x2 a = pk[2 * pp], b = pk[2 * pp + 1];
;         const u32x2 rx = __builtin_amdgcn_permlane16_swap(a.x, b.x, false, false);
;         const u32x2 ry = __builtin_amdgcn_permlane16_swap(a.y, b.y, false, false);
;         const int nst = (fq & 1) ? ((2 * pp + 1) * 16 + (fq - 1) * 4) : ((2 * pp) * 16 + fq * 4);
;         *(u32x4*)(rp + nst) = (u32x4){rx[0], ry[0], rx[1], ry[1]};
;       }
;     }
;   DI u32x2 pack(int m, int n, float a, float b, float c, float d, float& ss) const {
;     if (n < q_end) { a *= qscale; b *= qscale; c *= qscale; d *= qscale; }
;     else if (n >= z_start) { a = silu_f(a); b = silu_f(b); c = silu_f(c); d = silu_f(d); }
;     ss += a * a + b * b + c * c + d * d;
;     u32x2 v; v.x = pack2(a, b); v.y = pack2(c, d);
;     return v;
;   }
	v_mul_f32_e32 v37, v37, v157
	v_mul_f32_e32 v38, v38, v158
	v_mul_f32_e32 v39, v39, v159
	v_mul_f32_e32 v32, v32, v160
	v_mul_f32_e32 v33, v33, v161
	v_mul_f32_e32 v34, v34, v162
	v_mul_f32_e32 v35, v35, v163
	v_cvt_pk_bf16_f32 v128, v44, v45
	v_cvt_pk_bf16_f32 v129, v46, v47
	v_cvt_pk_bf16_f32 v130, v40, v41
	v_cvt_pk_bf16_f32 v131, v42, v43
	v_cvt_pk_bf16_f32 v132, v36, v37
	v_cvt_pk_bf16_f32 v133, v38, v39
	v_cvt_pk_bf16_f32 v134, v32, v33
	v_cvt_pk_bf16_f32 v135, v34, v35
	s_nop 1
	v_permlane16_swap_b32_e32 v128, v130
	v_permlane16_swap_b32_e32 v129, v131
	v_permlane16_swap_b32_e32 v132, v134
	v_permlane16_swap_b32_e32 v133, v135
	global_store_dwordx4 v153, v[128:131], s[100:101]
	global_store_dwordx4 v153, v[132:135], s[100:101] offset:64
	v_mul_f32_e32 v156, 0xbfb8aa3b, v28
	v_mul_f32_e32 v157, 0xbfb8aa3b, v29
	v_mul_f32_e32 v158, 0xbfb8aa3b, v30
	v_mul_f32_e32 v159, 0xbfb8aa3b, v31
	v_mul_f32_e32 v160, 0xbfb8aa3b, v24
	v_mul_f32_e32 v161, 0xbfb8aa3b, v25
	v_mul_f32_e32 v162, 0xbfb8aa3b, v26
	v_mul_f32_e32 v163, 0xbfb8aa3b, v27
	v_exp_f32_e32 v156, v156
	v_exp_f32_e32 v157, v157
	v_exp_f32_e32 v158, v158
	v_exp_f32_e32 v159, v159
	v_exp_f32_e32 v160, v160
	v_exp_f32_e32 v161, v161
	v_exp_f32_e32 v162, v162
	v_exp_f32_e32 v163, v163
	v_add_f32_e32 v156, 1.0, v156
	v_add_f32_e32 v157, 1.0, v157
	v_add_f32_e32 v158, 1.0, v158
	v_add_f32_e32 v159, 1.0, v159
	v_add_f32_e32 v160, 1.0, v160
	v_add_f32_e32 v161, 1.0, v161
	v_add_f32_e32 v162, 1.0, v162
	v_add_f32_e32 v163, 1.0, v163
	v_rcp_f32_e32 v156, v156
	v_rcp_f32_e32 v157, v157
	v_rcp_f32_e32 v158, v158
	v_rcp_f32_e32 v159, v159
	v_rcp_f32_e32 v160, v160
	v_rcp_f32_e32 v161, v161
	v_rcp_f32_e32 v162, v162
	v_rcp_f32_e32 v163, v163
	v_mul_f32_e32 v28, v28, v156
	v_mul_f32_e32 v29, v29, v157
	v_mul_f32_e32 v30, v30, v158
	v_mul_f32_e32 v31, v31, v159
	v_mul_f32_e32 v24, v24, v160
	v_mul_f32_e32 v25, v25, v161
	v_mul_f32_e32 v26, v26, v162
	v_mul_f32_e32 v27, v27, v163
	v_mul_f32_e32 v156, 0xbfb8aa3b, v20
	v_mul_f32_e32 v157, 0xbfb8aa3b, v21
	v_mul_f32_e32 v158, 0xbfb8aa3b, v22
	v_mul_f32_e32 v159, 0xbfb8aa3b, v23
	v_mul_f32_e32 v160, 0xbfb8aa3b, v16
	v_mul_f32_e32 v161, 0xbfb8aa3b, v17
	v_mul_f32_e32 v162, 0xbfb8aa3b, v18
	v_mul_f32_e32 v163, 0xbfb8aa3b, v19
	v_exp_f32_e32 v156, v156
	v_exp_f32_e32 v157, v157
	v_exp_f32_e32 v158, v158
	v_exp_f32_e32 v159, v159
	v_exp_f32_e32 v160, v160
	v_exp_f32_e32 v161, v161
	v_exp_f32_e32 v162, v162
	v_exp_f32_e32 v163, v163
	v_add_f32_e32 v156, 1.0, v156
	v_add_f32_e32 v157, 1.0, v157
	v_add_f32_e32 v158, 1.0, v158
	v_add_f32_e32 v159, 1.0, v159
	v_add_f32_e32 v160, 1.0, v160
	v_add_f32_e32 v161, 1.0, v161
	v_add_f32_e32 v162, 1.0, v162
	v_add_f32_e32 v163, 1.0, v163
	v_rcp_f32_e32 v156, v156
	v_rcp_f32_e32 v157, v157
	v_rcp_f32_e32 v158, v158
	v_rcp_f32_e32 v159, v159
	v_rcp_f32_e32 v160, v160
	v_rcp_f32_e32 v161, v161
	v_rcp_f32_e32 v162, v162
	v_rcp_f32_e32 v163, v163
	v_mul_f32_e32 v20, v20, v156
	v_mul_f32_e32 v21, v21, v157
	v_mul_f32_e32 v22, v22, v158
	v_mul_f32_e32 v23, v23, v159
	v_mul_f32_e32 v16, v16, v160
	v_mul_f32_e32 v17, v17, v161
	v_mul_f32_e32 v18, v18, v162
	v_mul_f32_e32 v19, v19, v163
	v_cvt_pk_bf16_f32 v136, v28, v29
	v_cvt_pk_bf16_f32 v137, v30, v31
	v_cvt_pk_bf16_f32 v138, v24, v25
	v_cvt_pk_bf16_f32 v139, v26, v27
	v_cvt_pk_bf16_f32 v140, v20, v21
	v_cvt_pk_bf16_f32 v141, v22, v23
	v_cvt_pk_bf16_f32 v142, v16, v17
	v_cvt_pk_bf16_f32 v143, v18, v19
	s_nop 1
	v_permlane16_swap_b32_e32 v136, v138
	v_permlane16_swap_b32_e32 v137, v139
	v_permlane16_swap_b32_e32 v140, v142
	v_permlane16_swap_b32_e32 v141, v143
	global_store_dwordx4 v154, v[136:139], s[100:101]
	global_store_dwordx4 v154, v[140:143], s[100:101] offset:64
	v_mul_f32_e32 v156, 0xbfb8aa3b, v12
	v_mul_f32_e32 v157, 0xbfb8aa3b, v13
	v_mul_f32_e32 v158, 0xbfb8aa3b, v14
	v_mul_f32_e32 v159, 0xbfb8aa3b, v15
	v_mul_f32_e32 v160, 0xbfb8aa3b, v8
	v_mul_f32_e32 v161, 0xbfb8aa3b, v9
	v_mul_f32_e32 v162, 0xbfb8aa3b, v10
	v_mul_f32_e32 v163, 0xbfb8aa3b, v11
	v_exp_f32_e32 v156, v156
	v_exp_f32_e32 v157, v157
	v_exp_f32_e32 v158, v158
	v_exp_f32_e32 v159, v159
	v_exp_f32_e32 v160, v160
	v_exp_f32_e32 v161, v161
	v_exp_f32_e32 v162, v162
	v_exp_f32_e32 v163, v163
	v_add_f32_e32 v156, 1.0, v156
	v_add_f32_e32 v157, 1.0, v157
	v_add_f32_e32 v158, 1.0, v158
	v_add_f32_e32 v159, 1.0, v159
	v_add_f32_e32 v160, 1.0, v160
	v_add_f32_e32 v161, 1.0, v161
	v_add_f32_e32 v162, 1.0, v162
	v_add_f32_e32 v163, 1.0, v163
	v_rcp_f32_e32 v156, v156
	v_rcp_f32_e32 v157, v157
	v_rcp_f32_e32 v158, v158
	v_rcp_f32_e32 v159, v159
	v_rcp_f32_e32 v160, v160
	v_rcp_f32_e32 v161, v161
	v_rcp_f32_e32 v162, v162
	v_rcp_f32_e32 v163, v163
	v_mul_f32_e32 v12, v12, v156
	v_mul_f32_e32 v13, v13, v157
	v_mul_f32_e32 v14, v14, v158
	v_mul_f32_e32 v15, v15, v159
	v_mul_f32_e32 v8, v8, v160
	v_mul_f32_e32 v9, v9, v161
	v_mul_f32_e32 v10, v10, v162
	v_mul_f32_e32 v11, v11, v163
	v_mul_f32_e32 v156, 0xbfb8aa3b, v4
	v_mul_f32_e32 v157, 0xbfb8aa3b, v5
	v_mul_f32_e32 v158, 0xbfb8aa3b, v6
	v_mul_f32_e32 v159, 0xbfb8aa3b, v7
	v_mul_f32_e32 v160, 0xbfb8aa3b, v0
	v_mul_f32_e32 v161, 0xbfb8aa3b, v1
	v_mul_f32_e32 v162, 0xbfb8aa3b, v2
	v_mul_f32_e32 v163, 0xbfb8aa3b, v3
	v_exp_f32_e32 v156, v156
	v_exp_f32_e32 v157, v157
	v_exp_f32_e32 v158, v158
	v_exp_f32_e32 v159, v159
	v_exp_f32_e32 v160, v160
	v_exp_f32_e32 v161, v161
	v_exp_f32_e32 v162, v162
	v_exp_f32_e32 v163, v163
	v_add_f32_e32 v156, 1.0, v156
	v_add_f32_e32 v157, 1.0, v157
	v_add_f32_e32 v158, 1.0, v158
	v_add_f32_e32 v159, 1.0, v159
	v_add_f32_e32 v160, 1.0, v160
	v_add_f32_e32 v161, 1.0, v161
	v_add_f32_e32 v162, 1.0, v162
	v_add_f32_e32 v163, 1.0, v163
	v_rcp_f32_e32 v156, v156
	v_rcp_f32_e32 v157, v157
	v_rcp_f32_e32 v158, v158
	v_rcp_f32_e32 v159, v159
	v_rcp_f32_e32 v160, v160
	v_rcp_f32_e32 v161, v161
	v_rcp_f32_e32 v162, v162
	v_rcp_f32_e32 v163, v163
	v_mul_f32_e32 v4, v4, v156
	v_mul_f32_e32 v5, v5, v157
	v_mul_f32_e32 v6, v6, v158
	v_mul_f32_e32 v7, v7, v159
	v_mul_f32_e32 v0, v0, v160
	v_mul_f32_e32 v1, v1, v161
	v_mul_f32_e32 v2, v2, v162
	v_mul_f32_e32 v3, v3, v163
	v_cvt_pk_bf16_f32 v144, v12, v13
	v_cvt_pk_bf16_f32 v145, v14, v15
	v_cvt_pk_bf16_f32 v146, v8, v9
	v_cvt_pk_bf16_f32 v147, v10, v11
	v_cvt_pk_bf16_f32 v148, v4, v5
	v_cvt_pk_bf16_f32 v149, v6, v7
	v_cvt_pk_bf16_f32 v150, v0, v1
	v_cvt_pk_bf16_f32 v151, v2, v3
	s_nop 1
	v_permlane16_swap_b32_e32 v144, v146
	v_permlane16_swap_b32_e32 v145, v147
	v_permlane16_swap_b32_e32 v148, v150
	v_permlane16_swap_b32_e32 v149, v151
	global_store_dwordx4 v155, v[144:147], s[100:101]
	global_store_dwordx4 v155, v[148:151], s[100:101] offset:64
	s_branch .Lfe_join_D
; DI unsigned pack2(float a, float b) { v2f f = {a, b}; return __builtin_bit_cast(unsigned, __builtin_convertvector(f, v2bf)); }
; DI float silu_f(float v) { return v / (1.f + fexp(-v)); }
; DI float sigmoid_f(float v) { return 1.f / (1.f + fexp(-v)); }
;   DI void operator()(int m, int n, float a, float b, float c, float d, float& ss) const { u32x2 v; v.x = pack2(a, b); v.y = pack2(c, d); *(u32x2*)(y + (long)m * 1024 + n) = v; }
; template <class ARow, class Epi>
; DI void gemm_tile(const ARow& arow, long a_kstride, const u16* __restrict__ Bt, long ldb, int K, int m0, int n0,
;                   const Epi& epi, char* smem) {
;     ...
;   } else {
; #pragma unroll
;     for (int mi = 0; mi < 4; ++mi) {
;       const int m = m0 + wm * 64 + mi * 16 + fr;
;       float ss = 0.f;
; #pragma unroll
;       for (int ni = 0; ni < 4; ++ni) {
;         const int n = nh + ni * 16 + fq * 4;
;         epi(m, n, acc[ni][mi][0], acc[ni][mi][1], acc[ni][mi][2], acc[ni][mi][3], ss);
;       }
;       epi.finish16(m, nh, ss);
;     }
;   }
;   DI void operator()(int m, int n, float a, float b, float c, float d, float& ss) const {
;     if (n >= gl_start) {
;       const int j = n - gl_start;
;       if (j < 48) { float* g = gates + (long)m * 48 + j; g[0] = sigmoid_f(a); g[1] = sigmoid_f(b); g[2] = sigmoid_f(c); g[3] = sigmoid_f(d); }
;       return;
;     }
;     if (n < q_end) { a *= qscale; b *= qscale; c *= qscale; d *= qscale; }
;     else if (n >= z_start) { a = silu_f(a); b = silu_f(b); c = silu_f(c); d = silu_f(d); }
;     ss += a * a + b * b + c * c + d * d;
;     u32x2 v; v.x = pack2(a, b); v.y = pack2(c, d);
;     *(u32x2*)(dst + (long)m * ld + n) = v;
.Lfe_D_not_z:
	s_and_saveexec_b64 s[0:1], vcc
	s_xor_b64 s[26:27], exec, s[0:1]
	s_cbranch_execz .LBB0_2461
	v_mad_i64_i32 v[70:71], s[0:1], v66, s31, 0
	v_cmp_lt_i32_e64 s[4:5], s30, v64
	v_add_u32_e32 v68, -2.0, v64
	s_and_saveexec_b64 s[0:1], s[4:5]
	s_xor_b64 s[0:1], exec, s[0:1]
	s_cbranch_execz .LBB0_2320
	v_cmp_gt_u32_e32 vcc, 48, v68
	s_and_saveexec_b64 s[6:7], vcc
	s_cbranch_execz .LBB0_2319
	v_mul_f32_e32 v60, 0xbfb8aa3b, v60
	v_mul_f32_e32 v61, 0xbfb8aa3b, v61
	v_exp_f32_e32 v60, v60
	v_exp_f32_e32 v61, v61
	v_mov_b32_e32 v69, v65
	v_lshl_add_u64 v[72:73], v[68:69], 2, v[70:71]
	v_mul_f32_e32 v62, 0xbfb8aa3b, v62
	v_pk_add_f32 v[60:61], v[60:61], 1.0 op_sel_hi:[1,0]
	v_mul_f32_e32 v63, 0xbfb8aa3b, v63
	v_exp_f32_e32 v62, v62
	v_exp_f32_e32 v63, v63
	v_rcp_f32_e32 v67, v61
	s_nop 0
	v_mul_f32_e32 v61, 1.0, v67
	v_pk_add_f32 v[62:63], v[62:63], 1.0 op_sel_hi:[1,0]
	v_rcp_f32_e32 v67, v60
	s_nop 0
	v_mul_f32_e32 v60, 1.0, v67
	v_rcp_f32_e32 v67, v63
	s_nop 0
	v_mul_f32_e32 v63, 1.0, v67
	v_rcp_f32_e32 v67, v62
	s_nop 0
	v_mul_f32_e32 v62, 1.0, v67
	flat_store_dwordx4 v[72:73], v[60:63]

; __global__ void __launch_bounds__(256, 2) trunk_fwd(Params p) {
;   __shared__ __attribute__((aligned(1024))) char smem[SM_TOTAL];
	.amdhsa_kernel _Z9trunk_fwd6Params
		.amdhsa_group_segment_fixed_size 73792
		.amdhsa_private_segment_fixed_size 0
		.amdhsa_kernarg_size 624
		.amdhsa_user_sgpr_count 2
		.amdhsa_user_sgpr_dispatch_ptr 0
		.amdhsa_user_sgpr_queue_ptr 0
		.amdhsa_user_sgpr_kernarg_segment_ptr 1
		.amdhsa_user_sgpr_dispatch_id 0
		.amdhsa_user_sgpr_kernarg_preload_length 0
		.amdhsa_user_sgpr_kernarg_preload_offset 0
		.amdhsa_user_sgpr_private_segment_size 0
		.amdhsa_uses_dynamic_stack 0
		.amdhsa_enable_private_segment 0
		.amdhsa_system_sgpr_workgroup_id_x 1
		.amdhsa_system_sgpr_workgroup_id_y 0
		.amdhsa_system_sgpr_workgroup_id_z 0
		.amdhsa_system_sgpr_workgroup_info 0
		.amdhsa_system_vgpr_workitem_id 2
		.amdhsa_next_free_vgpr 256
		.amdhsa_next_free_sgpr 102
		.amdhsa_accum_offset 256
		.amdhsa_reserve_vcc 1
		.amdhsa_float_round_mode_32 0
		.amdhsa_float_round_mode_16_64 0
		.amdhsa_float_denorm_mode_32 3
		.amdhsa_float_denorm_mode_16_64 3
		.amdhsa_dx10_clamp 1
		.amdhsa_ieee_mode 1
		.amdhsa_fp16_overflow 0
		.amdhsa_tg_split 0
		.amdhsa_exception_fp_ieee_invalid_op 0
		.amdhsa_exception_fp_denorm_src 0
		.amdhsa_exception_fp_ieee_div_zero 0
		.amdhsa_exception_fp_ieee_overflow 0
		.amdhsa_exception_fp_ieee_underflow 0
		.amdhsa_exception_fp_ieee_inexact 0
		.amdhsa_exception_int_div_zero 0
	.end_amdhsa_kernel

; __global__ void __launch_bounds__(256, 2) trunk_fwd(Params p) {
;   __shared__ __attribute__((aligned(1024))) char smem[SM_TOTAL];
amdhsa.kernels:
  - .agpr_count:     0
    .args:
      - .offset:         0
        .size:           368
        .value_kind:     by_value
      - .offset:         368
        .size:           4
        .value_kind:     hidden_block_count_x
      - .offset:         372
        .size:           4
        .value_kind:     hidden_block_count_y
      - .offset:         376
        .size:           4
        .value_kind:     hidden_block_count_z
      - .offset:         380
        .size:           2
        .value_kind:     hidden_group_size_x
      - .offset:         382
        .size:           2
        .value_kind:     hidden_group_size_y
      - .offset:         384
        .size:           2
        .value_kind:     hidden_group_size_z
      - .offset:         386
        .size:           2
        .value_kind:     hidden_remainder_x
      - .offset:         388
        .size:           2
        .value_kind:     hidden_remainder_y
      - .offset:         390
        .size:           2
        .value_kind:     hidden_remainder_z
      - .offset:         408
        .size:           8
        .value_kind:     hidden_global_offset_x
      - .offset:         416
        .size:           8
        .value_kind:     hidden_global_offset_y
      - .offset:         424
        .size:           8
        .value_kind:     hidden_global_offset_z
      - .offset:         432
        .size:           2
        .value_kind:     hidden_grid_dims
      - .offset:         456
        .size:           8
        .value_kind:     hidden_multigrid_sync_arg
    .group_segment_fixed_size: 73792
    .kernarg_segment_align: 8
    .kernarg_segment_size: 624
    .language:       OpenCL C
    .language_version:
      - 2
      - 0
    .max_flat_workgroup_size: 256
    .name:           _Z9trunk_fwd6Params
    .private_segment_fixed_size: 0
    .sgpr_count:     108
    .sgpr_spill_count: 56
    .symbol:         _Z9trunk_fwd6Params.kd
    .uniform_work_group_size: 1
    .uses_dynamic_stack: false
    .vgpr_count:     256
    .vgpr_spill_count: 0
    .wavefront_size: 64
